# v20 + GEMM loops without per-segment s_setprio flips (loader wave no longer deprioritised against the MFMA wave)
# speedup vs baseline: 1.0102x; 1.0102x over previous
.LBB0_127:
	s_add_u32 s22, s20, 0xfff80080
	s_addc_u32 s23, s21, -1
	s_add_i32 s50, 0, 0x10000
	s_cmp_eq_u32 s49, 4
	s_cselect_b32 s23, s81, s23
	s_cselect_b32 s22, s80, s22
	s_cselect_b32 s39, s19, s48
	s_cselect_b32 s38, s31, s47
	v_lshl_add_u64 v[178:179], s[20:21], 0, v[138:139]
	s_add_i32 m0, s27, 0xc000
	ds_read_b128 v[162:165], v144
	ds_read_b128 v[166:169], v144 offset:1024
	ds_read_b128 v[170:173], v144 offset:2048
	ds_read_b128 v[174:177], v144 offset:3072
	ds_read_b128 v[192:195], v144 offset:4096
	ds_read_b128 v[196:199], v144 offset:5120
	ds_read_b128 v[200:203], v144 offset:6144
	ds_read_b128 v[204:207], v144 offset:7168
	global_load_lds_dwordx4 v[178:179], off
	v_lshl_add_u64 v[178:179], s[20:21], 0, v[140:141]
	s_add_i32 m0, s27, 0xe000
	s_nop 0
	global_load_lds_dwordx4 v[178:179], off
	s_waitcnt lgkmcnt(8)
	s_barrier
	s_waitcnt lgkmcnt(0)
	s_waitcnt lgkmcnt(0)
	v_mfma_f32_16x16x32_bf16 v[126:129], v[146:149], v[162:165], v[126:129]
	v_mfma_f32_16x16x32_bf16 v[122:125], v[154:157], v[162:165], v[122:125]
	v_mfma_f32_16x16x32_bf16 v[118:121], v[146:149], v[170:173], v[118:121]
	v_mfma_f32_16x16x32_bf16 v[114:117], v[154:157], v[170:173], v[114:117]
	v_mfma_f32_16x16x32_bf16 v[102:105], v[146:149], v[192:195], v[102:105]
	v_mfma_f32_16x16x32_bf16 v[98:101], v[154:157], v[192:195], v[98:101]
	v_mfma_f32_16x16x32_bf16 v[86:89], v[146:149], v[200:203], v[86:89]
	v_mfma_f32_16x16x32_bf16 v[82:85], v[154:157], v[200:203], v[82:85]
	v_mfma_f32_16x16x32_bf16 v[126:129], v[150:153], v[166:169], v[126:129]
	v_mfma_f32_16x16x32_bf16 v[122:125], v[158:161], v[166:169], v[122:125]
	v_mfma_f32_16x16x32_bf16 v[118:121], v[150:153], v[174:177], v[118:121]
	v_mfma_f32_16x16x32_bf16 v[114:117], v[158:161], v[174:177], v[114:117]
	v_mfma_f32_16x16x32_bf16 v[102:105], v[150:153], v[196:199], v[102:105]
	v_mfma_f32_16x16x32_bf16 v[98:101], v[158:161], v[196:199], v[98:101]
	v_mfma_f32_16x16x32_bf16 v[86:89], v[150:153], v[204:207], v[86:89]
	v_mfma_f32_16x16x32_bf16 v[82:85], v[158:161], v[204:207], v[82:85]
	s_barrier
	s_add_i32 s52, 0, 0x14000
	s_add_i32 s50, s50, s26
	v_add_u32_e32 v145, s52, v142
	v_lshl_add_u64 v[178:179], s[38:39], 0, v[134:135]
	s_mov_b32 m0, s50
	ds_read_b128 v[208:211], v145
	ds_read_b128 v[224:227], v145 offset:1024
	ds_read_b128 v[228:231], v145 offset:2048
	ds_read_b128 v[232:235], v145 offset:3072
	global_load_lds_dwordx4 v[178:179], off
	v_lshl_add_u64 v[212:213], s[38:39], 0, v[130:131]
	s_add_i32 m0, s50, 0x2000
	s_nop 0
	global_load_lds_dwordx4 v[212:213], off
	s_barrier
	s_waitcnt lgkmcnt(0)
	s_waitcnt lgkmcnt(0)
	v_mfma_f32_16x16x32_bf16 v[110:113], v[208:211], v[162:165], v[110:113]
	v_mfma_f32_16x16x32_bf16 v[106:109], v[228:231], v[162:165], v[106:109]
	v_mfma_f32_16x16x32_bf16 v[94:97], v[208:211], v[170:173], v[94:97]
	v_mfma_f32_16x16x32_bf16 v[90:93], v[228:231], v[170:173], v[90:93]
	v_mfma_f32_16x16x32_bf16 v[78:81], v[208:211], v[192:195], v[78:81]
	v_mfma_f32_16x16x32_bf16 v[74:77], v[228:231], v[192:195], v[74:77]
	v_mfma_f32_16x16x32_bf16 v[70:73], v[208:211], v[200:203], v[70:73]
	v_mfma_f32_16x16x32_bf16 v[66:69], v[228:231], v[200:203], v[66:69]
	v_mfma_f32_16x16x32_bf16 v[110:113], v[224:227], v[166:169], v[110:113]
	v_mfma_f32_16x16x32_bf16 v[106:109], v[232:235], v[166:169], v[106:109]
	v_mfma_f32_16x16x32_bf16 v[94:97], v[224:227], v[174:177], v[94:97]
	v_mfma_f32_16x16x32_bf16 v[90:93], v[232:235], v[174:177], v[90:93]
	v_mfma_f32_16x16x32_bf16 v[78:81], v[224:227], v[196:199], v[78:81]
	v_mfma_f32_16x16x32_bf16 v[74:77], v[232:235], v[196:199], v[74:77]
	v_mfma_f32_16x16x32_bf16 v[70:73], v[224:227], v[204:207], v[70:73]
	v_mfma_f32_16x16x32_bf16 v[66:69], v[232:235], v[204:207], v[66:69]
	s_mov_b32 m0, s27
	v_lshl_add_u64 v[236:237], s[22:23], 0, v[136:137]
	s_barrier
	ds_read_b128 v[162:165], v144 offset:16384
	ds_read_b128 v[166:169], v144 offset:17408
	ds_read_b128 v[170:173], v144 offset:18432
	ds_read_b128 v[174:177], v144 offset:19456
	ds_read_b128 v[192:195], v144 offset:20480
	ds_read_b128 v[196:199], v144 offset:21504
	ds_read_b128 v[200:203], v144 offset:22528
	ds_read_b128 v[204:207], v144 offset:23552
	global_load_lds_dwordx4 v[236:237], off
	v_lshl_add_u64 v[238:239], s[22:23], 0, v[132:133]
	s_mov_b32 m0, s28
	s_nop 0
	global_load_lds_dwordx4 v[238:239], off
	s_waitcnt vmcnt(10)
	s_barrier
	s_waitcnt lgkmcnt(0)
	s_waitcnt lgkmcnt(0)
	v_mfma_f32_16x16x32_bf16 v[62:65], v[146:149], v[162:165], v[62:65]
	v_mfma_f32_16x16x32_bf16 v[58:61], v[154:157], v[162:165], v[58:61]
	v_mfma_f32_16x16x32_bf16 v[54:57], v[146:149], v[170:173], v[54:57]
	v_mfma_f32_16x16x32_bf16 v[50:53], v[154:157], v[170:173], v[50:53]
	v_mfma_f32_16x16x32_bf16 v[38:41], v[146:149], v[192:195], v[38:41]
	v_mfma_f32_16x16x32_bf16 v[34:37], v[154:157], v[192:195], v[34:37]
	v_mfma_f32_16x16x32_bf16 v[22:25], v[146:149], v[200:203], v[22:25]
	v_mfma_f32_16x16x32_bf16 v[18:21], v[154:157], v[200:203], v[18:21]
	v_mfma_f32_16x16x32_bf16 v[62:65], v[150:153], v[166:169], v[62:65]
	v_mfma_f32_16x16x32_bf16 v[58:61], v[158:161], v[166:169], v[58:61]
	v_mfma_f32_16x16x32_bf16 v[54:57], v[150:153], v[174:177], v[54:57]
	v_mfma_f32_16x16x32_bf16 v[50:53], v[158:161], v[174:177], v[50:53]
	v_mfma_f32_16x16x32_bf16 v[38:41], v[150:153], v[196:199], v[38:41]
	v_mfma_f32_16x16x32_bf16 v[34:37], v[158:161], v[196:199], v[34:37]
	v_mfma_f32_16x16x32_bf16 v[22:25], v[150:153], v[204:207], v[22:25]
	v_mfma_f32_16x16x32_bf16 v[18:21], v[158:161], v[204:207], v[18:21]
	s_barrier
	s_add_u32 s50, s38, 0x20000
	s_addc_u32 s51, s39, 0
	s_add_i32 s52, s52, s26
	v_lshl_add_u64 v[146:147], s[50:51], 0, v[134:135]
	s_mov_b32 m0, s52
	s_nop 0
	global_load_lds_dwordx4 v[146:147], off
	v_lshl_add_u64 v[146:147], s[50:51], 0, v[130:131]
	s_add_i32 m0, s52, 0x2000
	s_nop 0
	global_load_lds_dwordx4 v[146:147], off
	v_add_u32_e32 v145, 0x18000, v142
	ds_read_b128 v[146:149], v145
	ds_read_b128 v[150:153], v145 offset:1024
	ds_read_b128 v[154:157], v145 offset:2048
	ds_read_b128 v[158:161], v145 offset:3072
	s_waitcnt vmcnt(6)
	s_barrier
	v_mfma_f32_16x16x32_bf16 v[46:49], v[208:211], v[162:165], v[46:49]
	v_mfma_f32_16x16x32_bf16 v[42:45], v[228:231], v[162:165], v[42:45]
	v_mfma_f32_16x16x32_bf16 v[30:33], v[208:211], v[170:173], v[30:33]
	v_mfma_f32_16x16x32_bf16 v[26:29], v[228:231], v[170:173], v[26:29]
	v_mfma_f32_16x16x32_bf16 v[14:17], v[208:211], v[192:195], v[14:17]
	v_mfma_f32_16x16x32_bf16 v[10:13], v[228:231], v[192:195], v[10:13]
	v_mfma_f32_16x16x32_bf16 v[6:9], v[208:211], v[200:203], v[6:9]
	v_mfma_f32_16x16x32_bf16 v[2:5], v[228:231], v[200:203], v[2:5]
	v_mfma_f32_16x16x32_bf16 v[46:49], v[224:227], v[166:169], v[46:49]
	v_mfma_f32_16x16x32_bf16 v[42:45], v[232:235], v[166:169], v[42:45]
	v_mfma_f32_16x16x32_bf16 v[30:33], v[224:227], v[174:177], v[30:33]
	v_mfma_f32_16x16x32_bf16 v[26:29], v[232:235], v[174:177], v[26:29]
	v_mfma_f32_16x16x32_bf16 v[14:17], v[224:227], v[196:199], v[14:17]
	v_mfma_f32_16x16x32_bf16 v[10:13], v[232:235], v[196:199], v[10:13]
	v_mfma_f32_16x16x32_bf16 v[6:9], v[224:227], v[204:207], v[6:9]
	v_mfma_f32_16x16x32_bf16 v[2:5], v[232:235], v[204:207], v[2:5]
	s_add_i32 s50, 0, 0x18000
	s_barrier
	s_add_u32 s22, s22, 0x80000
	s_addc_u32 s23, s23, 0
	s_mov_b32 m0, s29
	v_lshl_add_u64 v[208:209], s[22:23], 0, v[136:137]
	ds_read_b128 v[162:165], v144 offset:32768
	ds_read_b128 v[166:169], v144 offset:33792
	ds_read_b128 v[170:173], v144 offset:34816
	ds_read_b128 v[174:177], v144 offset:35840
	ds_read_b128 v[192:195], v144 offset:36864
	ds_read_b128 v[196:199], v144 offset:37888
	ds_read_b128 v[200:203], v144 offset:38912
	ds_read_b128 v[204:207], v144 offset:39936
	global_load_lds_dwordx4 v[208:209], off
	v_lshl_add_u64 v[208:209], s[22:23], 0, v[132:133]
	s_mov_b32 m0, s36
	s_nop 0
	global_load_lds_dwordx4 v[208:209], off
	s_waitcnt lgkmcnt(8)
	s_barrier
	s_waitcnt lgkmcnt(0)
	s_waitcnt lgkmcnt(0)
	v_mfma_f32_16x16x32_bf16 v[126:129], v[146:149], v[162:165], v[126:129]
	v_mfma_f32_16x16x32_bf16 v[122:125], v[154:157], v[162:165], v[122:125]
	v_mfma_f32_16x16x32_bf16 v[118:121], v[146:149], v[170:173], v[118:121]
	v_mfma_f32_16x16x32_bf16 v[114:117], v[154:157], v[170:173], v[114:117]
	v_mfma_f32_16x16x32_bf16 v[102:105], v[146:149], v[192:195], v[102:105]
	v_mfma_f32_16x16x32_bf16 v[98:101], v[154:157], v[192:195], v[98:101]
	v_mfma_f32_16x16x32_bf16 v[86:89], v[146:149], v[200:203], v[86:89]
	v_mfma_f32_16x16x32_bf16 v[82:85], v[154:157], v[200:203], v[82:85]
	v_mfma_f32_16x16x32_bf16 v[126:129], v[150:153], v[166:169], v[126:129]
	v_mfma_f32_16x16x32_bf16 v[122:125], v[158:161], v[166:169], v[122:125]
	v_mfma_f32_16x16x32_bf16 v[118:121], v[150:153], v[174:177], v[118:121]
	v_mfma_f32_16x16x32_bf16 v[114:117], v[158:161], v[174:177], v[114:117]
	v_mfma_f32_16x16x32_bf16 v[102:105], v[150:153], v[196:199], v[102:105]
	v_mfma_f32_16x16x32_bf16 v[98:101], v[158:161], v[196:199], v[98:101]
	v_mfma_f32_16x16x32_bf16 v[86:89], v[150:153], v[204:207], v[86:89]
	v_mfma_f32_16x16x32_bf16 v[82:85], v[158:161], v[204:207], v[82:85]
	s_barrier
	s_add_i32 s51, 0, 0x1c000
	s_add_i32 s22, s50, s26
	v_add_u32_e32 v145, s51, v142
	v_lshl_add_u64 v[178:179], v[178:179], 0, s[78:79]
	s_mov_b32 m0, s22
	ds_read_b128 v[208:211], v145
	ds_read_b128 v[224:227], v145 offset:1024
	ds_read_b128 v[228:231], v145 offset:2048
	ds_read_b128 v[232:235], v145 offset:3072
	global_load_lds_dwordx4 v[178:179], off
	v_lshl_add_u64 v[178:179], v[212:213], 0, s[78:79]
	s_add_i32 m0, s22, 0x2000
	s_nop 0
	global_load_lds_dwordx4 v[178:179], off
	s_barrier
	s_waitcnt lgkmcnt(0)
	s_waitcnt lgkmcnt(0)
	v_mfma_f32_16x16x32_bf16 v[110:113], v[208:211], v[162:165], v[110:113]
	v_mfma_f32_16x16x32_bf16 v[106:109], v[228:231], v[162:165], v[106:109]
	v_mfma_f32_16x16x32_bf16 v[94:97], v[208:211], v[170:173], v[94:97]
	v_mfma_f32_16x16x32_bf16 v[90:93], v[228:231], v[170:173], v[90:93]
	v_mfma_f32_16x16x32_bf16 v[78:81], v[208:211], v[192:195], v[78:81]
	v_mfma_f32_16x16x32_bf16 v[74:77], v[228:231], v[192:195], v[74:77]
	v_mfma_f32_16x16x32_bf16 v[70:73], v[208:211], v[200:203], v[70:73]
	v_mfma_f32_16x16x32_bf16 v[66:69], v[228:231], v[200:203], v[66:69]
	v_mfma_f32_16x16x32_bf16 v[110:113], v[224:227], v[166:169], v[110:113]
	v_mfma_f32_16x16x32_bf16 v[106:109], v[232:235], v[166:169], v[106:109]
	v_mfma_f32_16x16x32_bf16 v[94:97], v[224:227], v[174:177], v[94:97]
	v_mfma_f32_16x16x32_bf16 v[90:93], v[232:235], v[174:177], v[90:93]
	v_mfma_f32_16x16x32_bf16 v[78:81], v[224:227], v[196:199], v[78:81]
	v_mfma_f32_16x16x32_bf16 v[74:77], v[232:235], v[196:199], v[74:77]
	v_mfma_f32_16x16x32_bf16 v[70:73], v[224:227], v[204:207], v[70:73]
	v_mfma_f32_16x16x32_bf16 v[66:69], v[232:235], v[204:207], v[66:69]
	s_mov_b32 m0, s42
	v_lshl_add_u64 v[178:179], v[236:237], 0, s[78:79]
	s_barrier
	ds_read_b128 v[162:165], v144 offset:49152
	ds_read_b128 v[166:169], v144 offset:50176
	ds_read_b128 v[170:173], v144 offset:51200
	ds_read_b128 v[174:177], v144 offset:52224
	ds_read_b128 v[192:195], v144 offset:53248
	ds_read_b128 v[196:199], v144 offset:54272
	ds_read_b128 v[200:203], v144 offset:55296
	ds_read_b128 v[204:207], v144 offset:56320
	global_load_lds_dwordx4 v[178:179], off
	v_lshl_add_u64 v[178:179], v[238:239], 0, s[78:79]
	s_mov_b32 m0, s43
	s_nop 0
	global_load_lds_dwordx4 v[178:179], off
	s_waitcnt vmcnt(10)
	s_barrier
	s_waitcnt lgkmcnt(0)
	s_waitcnt lgkmcnt(0)
	v_mfma_f32_16x16x32_bf16 v[62:65], v[146:149], v[162:165], v[62:65]
	v_mfma_f32_16x16x32_bf16 v[58:61], v[154:157], v[162:165], v[58:61]
	v_mfma_f32_16x16x32_bf16 v[54:57], v[146:149], v[170:173], v[54:57]
	v_mfma_f32_16x16x32_bf16 v[50:53], v[154:157], v[170:173], v[50:53]
	v_mfma_f32_16x16x32_bf16 v[38:41], v[146:149], v[192:195], v[38:41]
	v_mfma_f32_16x16x32_bf16 v[34:37], v[154:157], v[192:195], v[34:37]
	v_mfma_f32_16x16x32_bf16 v[22:25], v[146:149], v[200:203], v[22:25]
	v_mfma_f32_16x16x32_bf16 v[18:21], v[154:157], v[200:203], v[18:21]
	v_mfma_f32_16x16x32_bf16 v[62:65], v[150:153], v[166:169], v[62:65]
	v_mfma_f32_16x16x32_bf16 v[58:61], v[158:161], v[166:169], v[58:61]
	v_mfma_f32_16x16x32_bf16 v[54:57], v[150:153], v[174:177], v[54:57]
	v_mfma_f32_16x16x32_bf16 v[50:53], v[158:161], v[174:177], v[50:53]
	v_mfma_f32_16x16x32_bf16 v[38:41], v[150:153], v[196:199], v[38:41]
	v_mfma_f32_16x16x32_bf16 v[34:37], v[158:161], v[196:199], v[34:37]
	v_mfma_f32_16x16x32_bf16 v[22:25], v[150:153], v[204:207], v[22:25]
	v_mfma_f32_16x16x32_bf16 v[18:21], v[158:161], v[204:207], v[18:21]
	s_barrier
	s_add_u32 s22, s38, 0x20080
	s_addc_u32 s23, s39, 0
	s_add_i32 s38, s51, s26
	v_lshl_add_u64 v[146:147], s[22:23], 0, v[134:135]
	s_mov_b32 m0, s38
	s_nop 0
	global_load_lds_dwordx4 v[146:147], off
	v_lshl_add_u64 v[146:147], s[22:23], 0, v[130:131]
	s_add_i32 m0, s38, 0x2000
	s_nop 0
	global_load_lds_dwordx4 v[146:147], off
	v_add_u32_e32 v145, 0x10000, v142
	ds_read_b128 v[146:149], v145
	ds_read_b128 v[150:153], v145 offset:1024
	ds_read_b128 v[154:157], v145 offset:2048
	ds_read_b128 v[158:161], v145 offset:3072
	s_waitcnt vmcnt(6)
	s_barrier
	v_mfma_f32_16x16x32_bf16 v[46:49], v[208:211], v[162:165], v[46:49]
	v_mfma_f32_16x16x32_bf16 v[42:45], v[228:231], v[162:165], v[42:45]
	v_mfma_f32_16x16x32_bf16 v[30:33], v[208:211], v[170:173], v[30:33]
	v_mfma_f32_16x16x32_bf16 v[26:29], v[228:231], v[170:173], v[26:29]
	v_mfma_f32_16x16x32_bf16 v[14:17], v[208:211], v[192:195], v[14:17]
	v_mfma_f32_16x16x32_bf16 v[10:13], v[228:231], v[192:195], v[10:13]
	v_mfma_f32_16x16x32_bf16 v[6:9], v[208:211], v[200:203], v[6:9]
	v_mfma_f32_16x16x32_bf16 v[2:5], v[228:231], v[200:203], v[2:5]
	v_mfma_f32_16x16x32_bf16 v[46:49], v[224:227], v[166:169], v[46:49]
	v_mfma_f32_16x16x32_bf16 v[42:45], v[232:235], v[166:169], v[42:45]
	v_mfma_f32_16x16x32_bf16 v[30:33], v[224:227], v[174:177], v[30:33]
	v_mfma_f32_16x16x32_bf16 v[26:29], v[232:235], v[174:177], v[26:29]
	v_mfma_f32_16x16x32_bf16 v[14:17], v[224:227], v[196:199], v[14:17]
	v_mfma_f32_16x16x32_bf16 v[10:13], v[232:235], v[196:199], v[10:13]
	v_mfma_f32_16x16x32_bf16 v[6:9], v[224:227], v[204:207], v[6:9]
	v_mfma_f32_16x16x32_bf16 v[2:5], v[232:235], v[204:207], v[2:5]
	s_add_i32 s49, s49, 2
	s_add_u32 s20, s20, 0x100
	s_addc_u32 s21, s21, 0
	s_add_u32 s47, s47, 0x100
	s_addc_u32 s48, s48, 0
	s_cmp_gt_u32 s49, 5
	s_barrier
	s_cbranch_scc0 .LBB0_127
	s_waitcnt lgkmcnt(0)
	v_lshl_add_u32 v146, s46, 8, v1
	v_lshl_or_b32 v148, s45, 8, v143
	v_ashrrev_i32_e32 v147, 31, v146
	v_readlane_b32 s48, v254, 40
	v_ashrrev_i32_e32 v149, 31, v148
	v_lshlrev_b64 v[150:151], 12, v[146:147]
	v_readlane_b32 s52, v254, 44
	v_readlane_b32 s53, v254, 45
	v_lshlrev_b64 v[148:149], 1, v[148:149]
	s_mov_b32 s19, 0x80000
	v_lshl_add_u64 v[150:151], s[52:53], 0, v[150:151]
	v_lshl_add_u64 v[150:151], v[150:151], 0, v[148:149]
	s_mov_b64 s[20:21], 0x80000
	v_cvt_pk_bf16_f32 v62, v62, v63
	v_cvt_pk_bf16_f32 v63, v64, v65
	v_cvt_pk_bf16_f32 v64, v58, v59
	v_add_co_u32_e32 v58, vcc, s19, v150
	v_cvt_pk_bf16_f32 v70, v70, v71
	v_cvt_pk_bf16_f32 v71, v72, v73
	v_cvt_pk_bf16_f32 v72, v66, v67
	v_lshl_add_u64 v[66:67], v[150:151], 0, s[20:21]
	v_addc_co_u32_e32 v59, vcc, 0, v151, vcc
	v_cvt_pk_bf16_f32 v46, v46, v47
	v_cvt_pk_bf16_f32 v47, v48, v49
	v_cvt_pk_bf16_f32 v48, v42, v43
	v_cvt_pk_bf16_f32 v49, v44, v45
	s_mov_b32 s19, 0x90000
	v_cvt_pk_bf16_f32 v110, v110, v111
	v_cvt_pk_bf16_f32 v111, v112, v113
	v_cvt_pk_bf16_f32 v112, v106, v107
	v_or_b32_e32 v106, 16, v146
	global_store_dwordx4 v[66:67], v[46:49], off offset:256
	s_mov_b64 s[20:21], 0x90000
	v_ashrrev_i32_e32 v107, 31, v106
	v_add_co_u32_e32 v48, vcc, s19, v150
	v_cvt_pk_bf16_f32 v94, v94, v95
	v_cvt_pk_bf16_f32 v95, v96, v97
	v_cvt_pk_bf16_f32 v96, v90, v91
	v_or_b32_e32 v90, 32, v146
	v_lshl_add_u64 v[46:47], v[150:151], 0, s[20:21]
	v_addc_co_u32_e32 v49, vcc, 0, v151, vcc
	v_cvt_pk_bf16_f32 v30, v30, v31
	v_cvt_pk_bf16_f32 v31, v32, v33
	v_cvt_pk_bf16_f32 v32, v26, v27
	v_cvt_pk_bf16_f32 v33, v28, v29
	s_mov_b32 s19, 0xa0000
	v_lshlrev_b64 v[106:107], 12, v[106:107]
	v_ashrrev_i32_e32 v91, 31, v90
	v_cvt_pk_bf16_f32 v78, v78, v79
	v_cvt_pk_bf16_f32 v79, v80, v81
	v_cvt_pk_bf16_f32 v80, v74, v75
	v_or_b32_e32 v74, 48, v146
	global_store_dwordx4 v[46:47], v[30:33], off offset:256
	s_mov_b64 s[20:21], 0xa0000
	v_cvt_pk_bf16_f32 v113, v108, v109
	v_add_co_u32_e32 v32, vcc, s19, v150
	v_lshl_add_u64 v[106:107], s[52:53], 0, v[106:107]
	v_lshlrev_b64 v[90:91], 12, v[90:91]
	v_ashrrev_i32_e32 v75, 31, v74
	v_lshl_add_u64 v[30:31], v[150:151], 0, s[20:21]
	v_addc_co_u32_e32 v33, vcc, 0, v151, vcc
	v_cvt_pk_bf16_f32 v14, v14, v15
	v_cvt_pk_bf16_f32 v15, v16, v17
	v_cvt_pk_bf16_f32 v16, v10, v11
	v_cvt_pk_bf16_f32 v17, v12, v13
	s_mov_b32 s19, 0xb0000
	global_store_dwordx4 v[150:151], v[110:113], off offset:256
	v_cvt_pk_bf16_f32 v97, v92, v93
	v_lshl_add_u64 v[90:91], s[52:53], 0, v[90:91]
	v_lshl_add_u64 v[110:111], v[106:107], 0, v[148:149]
	v_lshlrev_b64 v[74:75], 12, v[74:75]
	global_store_dwordx4 v[30:31], v[14:17], off offset:256
	global_store_dwordx4 v[110:111], v[94:97], off offset:256
	v_cvt_pk_bf16_f32 v81, v76, v77
	v_add_co_u32_e32 v16, vcc, s19, v150
	v_lshl_add_u64 v[94:95], v[90:91], 0, v[148:149]
	v_lshl_add_u64 v[74:75], s[52:53], 0, v[74:75]
	s_mov_b64 s[20:21], 0xb0000
	v_addc_co_u32_e32 v17, vcc, 0, v151, vcc
	v_cvt_pk_bf16_f32 v126, v126, v127
	v_cvt_pk_bf16_f32 v127, v128, v129
	v_cvt_pk_bf16_f32 v128, v122, v123
	v_cvt_pk_bf16_f32 v129, v124, v125
	v_cvt_pk_bf16_f32 v106, v118, v119
	v_cvt_pk_bf16_f32 v107, v120, v121
	v_cvt_pk_bf16_f32 v108, v114, v115
	v_cvt_pk_bf16_f32 v109, v116, v117
	v_cvt_pk_bf16_f32 v90, v102, v103
	v_cvt_pk_bf16_f32 v91, v104, v105
	v_cvt_pk_bf16_f32 v92, v98, v99
	v_cvt_pk_bf16_f32 v93, v100, v101
	global_store_dwordx4 v[94:95], v[78:81], off offset:256
	v_cvt_pk_bf16_f32 v76, v82, v83
	v_cvt_pk_bf16_f32 v77, v84, v85
	v_lshl_add_u64 v[78:79], v[74:75], 0, v[148:149]
	v_cvt_pk_bf16_f32 v74, v86, v87
	v_cvt_pk_bf16_f32 v75, v88, v89
	v_cvt_pk_bf16_f32 v73, v68, v69
	v_cvt_pk_bf16_f32 v65, v60, v61
	v_cvt_pk_bf16_f32 v42, v54, v55
	v_cvt_pk_bf16_f32 v43, v56, v57
	v_cvt_pk_bf16_f32 v44, v50, v51
	v_cvt_pk_bf16_f32 v45, v52, v53
	v_cvt_pk_bf16_f32 v26, v38, v39
	v_cvt_pk_bf16_f32 v27, v40, v41
	v_cvt_pk_bf16_f32 v28, v34, v35
	v_cvt_pk_bf16_f32 v29, v36, v37
	v_lshl_add_u64 v[14:15], v[150:151], 0, s[20:21]
	v_cvt_pk_bf16_f32 v10, v22, v23
	v_cvt_pk_bf16_f32 v11, v24, v25
	v_cvt_pk_bf16_f32 v12, v18, v19
	v_cvt_pk_bf16_f32 v13, v20, v21
	v_cvt_pk_bf16_f32 v6, v6, v7
	v_cvt_pk_bf16_f32 v7, v8, v9
	v_cvt_pk_bf16_f32 v8, v2, v3
	v_cvt_pk_bf16_f32 v9, v4, v5
	s_and_b64 vcc, exec, s[0:1]
	s_mov_b32 s45, s18
	s_mov_b32 s46, s30
	s_mov_b64 s[22:23], s[82:83]
	s_mov_b64 s[20:21], s[80:81]
	s_mov_b32 s64, 0x800000
	s_movk_i32 s65, 0x1fff
	v_readlane_b32 s49, v254, 41
	v_readlane_b32 s50, v254, 42
	v_readlane_b32 s51, v254, 43
	v_readlane_b32 s54, v254, 46
	v_readlane_b32 s55, v254, 47
	v_readlane_b32 s56, v254, 48
	v_readlane_b32 s57, v254, 49
	v_readlane_b32 s58, v254, 50
	v_readlane_b32 s59, v254, 51
	v_readlane_b32 s60, v254, 52
	v_readlane_b32 s61, v254, 53
	v_readlane_b32 s62, v254, 54
	v_readlane_b32 s63, v254, 55
	global_store_dwordx4 v[150:151], v[126:129], off
	global_store_dwordx4 v[110:111], v[106:109], off
	global_store_dwordx4 v[94:95], v[90:93], off
	global_store_dwordx4 v[78:79], v[74:77], off
	global_store_dwordx4 v[78:79], v[70:73], off offset:256
	global_store_dwordx4 v[58:59], v[62:65], off
	global_store_dwordx4 v[48:49], v[42:45], off
	global_store_dwordx4 v[32:33], v[26:29], off
	global_store_dwordx4 v[16:17], v[10:13], off
	global_store_dwordx4 v[14:15], v[6:9], off offset:256
	s_cbranch_vccz .LBB0_118
	s_waitcnt vmcnt(0)
	v_readlane_b32 s44, v255, 30
	s_mov_b32 s66, s90
	s_cmpk_gt_u32 s25, 0xff
	v_readlane_b32 s45, v255, 31
	v_readlane_b32 s42, v255, 32
	s_cbranch_scc1 .LBB0_131
	s_barrier

.LBB0_240:
	s_add_u32 s22, s80, 0xfff80080
	s_addc_u32 s23, s81, -1
	s_add_i32 s52, 0, 0x10000
	s_cmp_eq_u32 s51, 28
	s_cselect_b32 s23, s21, s23
	s_cselect_b32 s22, s47, s22
	s_cselect_b32 s83, s19, s50
	s_cselect_b32 s82, s48, s49
	v_lshl_add_u64 v[178:179], s[80:81], 0, v[134:135]
	s_add_i32 m0, s27, 0xc000
	ds_read_b128 v[158:161], v140
	ds_read_b128 v[162:165], v140 offset:1024
	ds_read_b128 v[166:169], v140 offset:2048
	ds_read_b128 v[170:173], v140 offset:3072
	ds_read_b128 v[174:177], v140 offset:4096
	ds_read_b128 v[192:195], v140 offset:5120
	ds_read_b128 v[196:199], v140 offset:6144
	ds_read_b128 v[200:203], v140 offset:7168
	global_load_lds_dwordx4 v[178:179], off
	v_lshl_add_u64 v[178:179], s[80:81], 0, v[136:137]
	s_add_i32 m0, s27, 0xe000
	s_nop 0
	global_load_lds_dwordx4 v[178:179], off
	s_waitcnt lgkmcnt(8)
	s_barrier
	s_waitcnt lgkmcnt(0)
	s_waitcnt lgkmcnt(0)
	v_mfma_f32_16x16x32_bf16 v[126:129], v[142:145], v[158:161], v[126:129]
	v_mfma_f32_16x16x32_bf16 v[122:125], v[150:153], v[158:161], v[122:125]
	v_mfma_f32_16x16x32_bf16 v[118:121], v[142:145], v[166:169], v[118:121]
	v_mfma_f32_16x16x32_bf16 v[114:117], v[150:153], v[166:169], v[114:117]
	v_mfma_f32_16x16x32_bf16 v[110:113], v[142:145], v[174:177], v[110:113]
	v_mfma_f32_16x16x32_bf16 v[102:105], v[150:153], v[174:177], v[102:105]
	v_mfma_f32_16x16x32_bf16 v[94:97], v[142:145], v[196:199], v[94:97]
	v_mfma_f32_16x16x32_bf16 v[86:89], v[150:153], v[196:199], v[86:89]
	v_mfma_f32_16x16x32_bf16 v[126:129], v[146:149], v[162:165], v[126:129]
	v_mfma_f32_16x16x32_bf16 v[122:125], v[154:157], v[162:165], v[122:125]
	v_mfma_f32_16x16x32_bf16 v[118:121], v[146:149], v[170:173], v[118:121]
	v_mfma_f32_16x16x32_bf16 v[114:117], v[154:157], v[170:173], v[114:117]
	v_mfma_f32_16x16x32_bf16 v[110:113], v[146:149], v[192:195], v[110:113]
	v_mfma_f32_16x16x32_bf16 v[102:105], v[154:157], v[192:195], v[102:105]
	v_mfma_f32_16x16x32_bf16 v[94:97], v[146:149], v[200:203], v[94:97]
	v_mfma_f32_16x16x32_bf16 v[86:89], v[154:157], v[200:203], v[86:89]
	s_barrier
	s_add_i32 s54, 0, 0x14000
	s_add_i32 s52, s52, s26
	v_add_u32_e32 v141, s54, v138
	v_lshl_add_u64 v[178:179], s[82:83], 0, v[132:133]
	s_mov_b32 m0, s52
	ds_read_b128 v[204:207], v141
	ds_read_b128 v[208:211], v141 offset:1024
	ds_read_b128 v[224:227], v141 offset:2048
	ds_read_b128 v[228:231], v141 offset:3072
	global_load_lds_dwordx4 v[178:179], off
	v_lshl_add_u64 v[212:213], s[82:83], 0, v[130:131]
	s_add_i32 m0, s52, 0x2000
	s_nop 0
	global_load_lds_dwordx4 v[212:213], off
	s_barrier
	s_waitcnt lgkmcnt(0)
	s_waitcnt lgkmcnt(0)
	v_mfma_f32_16x16x32_bf16 v[106:109], v[204:207], v[158:161], v[106:109]
	v_mfma_f32_16x16x32_bf16 v[98:101], v[224:227], v[158:161], v[98:101]
	v_mfma_f32_16x16x32_bf16 v[90:93], v[204:207], v[166:169], v[90:93]
	v_mfma_f32_16x16x32_bf16 v[82:85], v[224:227], v[166:169], v[82:85]
	v_mfma_f32_16x16x32_bf16 v[78:81], v[204:207], v[174:177], v[78:81]
	v_mfma_f32_16x16x32_bf16 v[74:77], v[224:227], v[174:177], v[74:77]
	v_mfma_f32_16x16x32_bf16 v[70:73], v[204:207], v[196:199], v[70:73]
	v_mfma_f32_16x16x32_bf16 v[66:69], v[224:227], v[196:199], v[66:69]
	v_mfma_f32_16x16x32_bf16 v[106:109], v[208:211], v[162:165], v[106:109]
	v_mfma_f32_16x16x32_bf16 v[98:101], v[228:231], v[162:165], v[98:101]
	v_mfma_f32_16x16x32_bf16 v[90:93], v[208:211], v[170:173], v[90:93]
	v_mfma_f32_16x16x32_bf16 v[82:85], v[228:231], v[170:173], v[82:85]
	v_mfma_f32_16x16x32_bf16 v[78:81], v[208:211], v[192:195], v[78:81]
	v_mfma_f32_16x16x32_bf16 v[74:77], v[228:231], v[192:195], v[74:77]
	v_mfma_f32_16x16x32_bf16 v[70:73], v[208:211], v[200:203], v[70:73]
	v_mfma_f32_16x16x32_bf16 v[66:69], v[228:231], v[200:203], v[66:69]
	s_mov_b32 m0, s27
	v_lshl_add_u64 v[232:233], s[22:23], 0, v[132:133]
	s_barrier
	ds_read_b128 v[158:161], v140 offset:16384
	ds_read_b128 v[162:165], v140 offset:17408
	ds_read_b128 v[166:169], v140 offset:18432
	ds_read_b128 v[170:173], v140 offset:19456
	ds_read_b128 v[174:177], v140 offset:20480
	ds_read_b128 v[192:195], v140 offset:21504
	ds_read_b128 v[196:199], v140 offset:22528
	ds_read_b128 v[200:203], v140 offset:23552
	global_load_lds_dwordx4 v[232:233], off
	v_lshl_add_u64 v[234:235], s[22:23], 0, v[130:131]
	s_mov_b32 m0, s28
	s_nop 0
	global_load_lds_dwordx4 v[234:235], off
	s_waitcnt vmcnt(10)
	s_barrier
	s_waitcnt lgkmcnt(0)
	s_waitcnt lgkmcnt(0)
	v_mfma_f32_16x16x32_bf16 v[62:65], v[142:145], v[158:161], v[62:65]
	v_mfma_f32_16x16x32_bf16 v[58:61], v[150:153], v[158:161], v[58:61]
	v_mfma_f32_16x16x32_bf16 v[54:57], v[142:145], v[166:169], v[54:57]
	v_mfma_f32_16x16x32_bf16 v[50:53], v[150:153], v[166:169], v[50:53]
	v_mfma_f32_16x16x32_bf16 v[46:49], v[142:145], v[174:177], v[46:49]
	v_mfma_f32_16x16x32_bf16 v[38:41], v[150:153], v[174:177], v[38:41]
	v_mfma_f32_16x16x32_bf16 v[30:33], v[142:145], v[196:199], v[30:33]
	v_mfma_f32_16x16x32_bf16 v[22:25], v[150:153], v[196:199], v[22:25]
	v_mfma_f32_16x16x32_bf16 v[62:65], v[146:149], v[162:165], v[62:65]
	v_mfma_f32_16x16x32_bf16 v[58:61], v[154:157], v[162:165], v[58:61]
	v_mfma_f32_16x16x32_bf16 v[54:57], v[146:149], v[170:173], v[54:57]
	v_mfma_f32_16x16x32_bf16 v[50:53], v[154:157], v[170:173], v[50:53]
	v_mfma_f32_16x16x32_bf16 v[46:49], v[146:149], v[192:195], v[46:49]
	v_mfma_f32_16x16x32_bf16 v[38:41], v[154:157], v[192:195], v[38:41]
	v_mfma_f32_16x16x32_bf16 v[30:33], v[146:149], v[200:203], v[30:33]
	v_mfma_f32_16x16x32_bf16 v[22:25], v[154:157], v[200:203], v[22:25]
	s_barrier
	s_add_u32 s52, s82, 0x80000
	s_addc_u32 s53, s83, 0
	s_add_i32 s54, s54, s26
	v_lshl_add_u64 v[142:143], s[52:53], 0, v[132:133]
	s_mov_b32 m0, s54
	s_nop 0
	global_load_lds_dwordx4 v[142:143], off
	v_lshl_add_u64 v[142:143], s[52:53], 0, v[130:131]
	s_add_i32 m0, s54, 0x2000
	s_nop 0
	global_load_lds_dwordx4 v[142:143], off
	v_add_u32_e32 v141, 0x18000, v138
	ds_read_b128 v[142:145], v141
	ds_read_b128 v[146:149], v141 offset:1024
	ds_read_b128 v[150:153], v141 offset:2048
	ds_read_b128 v[154:157], v141 offset:3072
	s_waitcnt vmcnt(6)
	s_barrier
	v_mfma_f32_16x16x32_bf16 v[42:45], v[204:207], v[158:161], v[42:45]
	v_mfma_f32_16x16x32_bf16 v[34:37], v[224:227], v[158:161], v[34:37]
	v_mfma_f32_16x16x32_bf16 v[26:29], v[204:207], v[166:169], v[26:29]
	v_mfma_f32_16x16x32_bf16 v[18:21], v[224:227], v[166:169], v[18:21]
	v_mfma_f32_16x16x32_bf16 v[14:17], v[204:207], v[174:177], v[14:17]
	v_mfma_f32_16x16x32_bf16 v[10:13], v[224:227], v[174:177], v[10:13]
	v_mfma_f32_16x16x32_bf16 v[6:9], v[204:207], v[196:199], v[6:9]
	v_mfma_f32_16x16x32_bf16 v[2:5], v[224:227], v[196:199], v[2:5]
	v_mfma_f32_16x16x32_bf16 v[42:45], v[208:211], v[162:165], v[42:45]
	v_mfma_f32_16x16x32_bf16 v[34:37], v[228:231], v[162:165], v[34:37]
	v_mfma_f32_16x16x32_bf16 v[26:29], v[208:211], v[170:173], v[26:29]
	v_mfma_f32_16x16x32_bf16 v[18:21], v[228:231], v[170:173], v[18:21]
	v_mfma_f32_16x16x32_bf16 v[14:17], v[208:211], v[192:195], v[14:17]
	v_mfma_f32_16x16x32_bf16 v[10:13], v[228:231], v[192:195], v[10:13]
	v_mfma_f32_16x16x32_bf16 v[6:9], v[208:211], v[200:203], v[6:9]
	v_mfma_f32_16x16x32_bf16 v[2:5], v[228:231], v[200:203], v[2:5]
	s_add_i32 s52, 0, 0x18000
	s_barrier
	s_add_u32 s22, s22, 0x80000
	s_addc_u32 s23, s23, 0
	s_mov_b32 m0, s29
	v_lshl_add_u64 v[204:205], s[22:23], 0, v[132:133]
	ds_read_b128 v[158:161], v140 offset:32768
	ds_read_b128 v[162:165], v140 offset:33792
	ds_read_b128 v[166:169], v140 offset:34816
	ds_read_b128 v[170:173], v140 offset:35840
	ds_read_b128 v[174:177], v140 offset:36864
	ds_read_b128 v[192:195], v140 offset:37888
	ds_read_b128 v[196:199], v140 offset:38912
	ds_read_b128 v[200:203], v140 offset:39936
	global_load_lds_dwordx4 v[204:205], off
	v_lshl_add_u64 v[204:205], s[22:23], 0, v[130:131]
	s_mov_b32 m0, s36
	s_nop 0
	global_load_lds_dwordx4 v[204:205], off
	s_waitcnt lgkmcnt(8)
	s_barrier
	s_waitcnt lgkmcnt(0)
	s_waitcnt lgkmcnt(0)
	v_mfma_f32_16x16x32_bf16 v[126:129], v[142:145], v[158:161], v[126:129]
	v_mfma_f32_16x16x32_bf16 v[122:125], v[150:153], v[158:161], v[122:125]
	v_mfma_f32_16x16x32_bf16 v[118:121], v[142:145], v[166:169], v[118:121]
	v_mfma_f32_16x16x32_bf16 v[114:117], v[150:153], v[166:169], v[114:117]
	v_mfma_f32_16x16x32_bf16 v[110:113], v[142:145], v[174:177], v[110:113]
	v_mfma_f32_16x16x32_bf16 v[102:105], v[150:153], v[174:177], v[102:105]
	v_mfma_f32_16x16x32_bf16 v[94:97], v[142:145], v[196:199], v[94:97]
	v_mfma_f32_16x16x32_bf16 v[86:89], v[150:153], v[196:199], v[86:89]
	v_mfma_f32_16x16x32_bf16 v[126:129], v[146:149], v[162:165], v[126:129]
	v_mfma_f32_16x16x32_bf16 v[122:125], v[154:157], v[162:165], v[122:125]
	v_mfma_f32_16x16x32_bf16 v[118:121], v[146:149], v[170:173], v[118:121]
	v_mfma_f32_16x16x32_bf16 v[114:117], v[154:157], v[170:173], v[114:117]
	v_mfma_f32_16x16x32_bf16 v[110:113], v[146:149], v[192:195], v[110:113]
	v_mfma_f32_16x16x32_bf16 v[102:105], v[154:157], v[192:195], v[102:105]
	v_mfma_f32_16x16x32_bf16 v[94:97], v[146:149], v[200:203], v[94:97]
	v_mfma_f32_16x16x32_bf16 v[86:89], v[154:157], v[200:203], v[86:89]
	s_barrier
	s_add_i32 s53, 0, 0x1c000
	s_add_i32 s22, s52, s26
	v_add_u32_e32 v141, s53, v138
	v_lshl_add_u64 v[178:179], v[178:179], 0, s[78:79]
	s_mov_b32 m0, s22
	ds_read_b128 v[204:207], v141
	ds_read_b128 v[208:211], v141 offset:1024
	ds_read_b128 v[224:227], v141 offset:2048
	ds_read_b128 v[228:231], v141 offset:3072
	global_load_lds_dwordx4 v[178:179], off
	v_lshl_add_u64 v[178:179], v[212:213], 0, s[78:79]
	s_add_i32 m0, s22, 0x2000
	s_nop 0
	global_load_lds_dwordx4 v[178:179], off
	s_barrier
	s_waitcnt lgkmcnt(0)
	s_waitcnt lgkmcnt(0)
	v_mfma_f32_16x16x32_bf16 v[106:109], v[204:207], v[158:161], v[106:109]
	v_mfma_f32_16x16x32_bf16 v[98:101], v[224:227], v[158:161], v[98:101]
	v_mfma_f32_16x16x32_bf16 v[90:93], v[204:207], v[166:169], v[90:93]
	v_mfma_f32_16x16x32_bf16 v[82:85], v[224:227], v[166:169], v[82:85]
	v_mfma_f32_16x16x32_bf16 v[78:81], v[204:207], v[174:177], v[78:81]
	v_mfma_f32_16x16x32_bf16 v[74:77], v[224:227], v[174:177], v[74:77]
	v_mfma_f32_16x16x32_bf16 v[70:73], v[204:207], v[196:199], v[70:73]
	v_mfma_f32_16x16x32_bf16 v[66:69], v[224:227], v[196:199], v[66:69]
	v_mfma_f32_16x16x32_bf16 v[106:109], v[208:211], v[162:165], v[106:109]
	v_mfma_f32_16x16x32_bf16 v[98:101], v[228:231], v[162:165], v[98:101]
	v_mfma_f32_16x16x32_bf16 v[90:93], v[208:211], v[170:173], v[90:93]
	v_mfma_f32_16x16x32_bf16 v[82:85], v[228:231], v[170:173], v[82:85]
	v_mfma_f32_16x16x32_bf16 v[78:81], v[208:211], v[192:195], v[78:81]
	v_mfma_f32_16x16x32_bf16 v[74:77], v[228:231], v[192:195], v[74:77]
	v_mfma_f32_16x16x32_bf16 v[70:73], v[208:211], v[200:203], v[70:73]
	v_mfma_f32_16x16x32_bf16 v[66:69], v[228:231], v[200:203], v[66:69]
	s_mov_b32 m0, s42
	v_lshl_add_u64 v[178:179], v[232:233], 0, s[78:79]
	s_barrier
	ds_read_b128 v[158:161], v140 offset:49152
	ds_read_b128 v[162:165], v140 offset:50176
	ds_read_b128 v[166:169], v140 offset:51200
	ds_read_b128 v[170:173], v140 offset:52224
	ds_read_b128 v[174:177], v140 offset:53248
	ds_read_b128 v[192:195], v140 offset:54272
	ds_read_b128 v[196:199], v140 offset:55296
	ds_read_b128 v[200:203], v140 offset:56320
	global_load_lds_dwordx4 v[178:179], off
	v_lshl_add_u64 v[178:179], v[234:235], 0, s[78:79]
	s_mov_b32 m0, s43
	s_nop 0
	global_load_lds_dwordx4 v[178:179], off
	s_waitcnt vmcnt(10)
	s_barrier
	s_waitcnt lgkmcnt(0)
	s_waitcnt lgkmcnt(0)
	v_mfma_f32_16x16x32_bf16 v[62:65], v[142:145], v[158:161], v[62:65]
	v_mfma_f32_16x16x32_bf16 v[58:61], v[150:153], v[158:161], v[58:61]
	v_mfma_f32_16x16x32_bf16 v[54:57], v[142:145], v[166:169], v[54:57]
	v_mfma_f32_16x16x32_bf16 v[50:53], v[150:153], v[166:169], v[50:53]
	v_mfma_f32_16x16x32_bf16 v[46:49], v[142:145], v[174:177], v[46:49]
	v_mfma_f32_16x16x32_bf16 v[38:41], v[150:153], v[174:177], v[38:41]
	v_mfma_f32_16x16x32_bf16 v[30:33], v[142:145], v[196:199], v[30:33]
	v_mfma_f32_16x16x32_bf16 v[22:25], v[150:153], v[196:199], v[22:25]
	v_mfma_f32_16x16x32_bf16 v[62:65], v[146:149], v[162:165], v[62:65]
	v_mfma_f32_16x16x32_bf16 v[58:61], v[154:157], v[162:165], v[58:61]
	v_mfma_f32_16x16x32_bf16 v[54:57], v[146:149], v[170:173], v[54:57]
	v_mfma_f32_16x16x32_bf16 v[50:53], v[154:157], v[170:173], v[50:53]
	v_mfma_f32_16x16x32_bf16 v[46:49], v[146:149], v[192:195], v[46:49]
	v_mfma_f32_16x16x32_bf16 v[38:41], v[154:157], v[192:195], v[38:41]
	v_mfma_f32_16x16x32_bf16 v[30:33], v[146:149], v[200:203], v[30:33]
	v_mfma_f32_16x16x32_bf16 v[22:25], v[154:157], v[200:203], v[22:25]
	s_barrier
	s_add_u32 s22, s82, 0x80080
	s_addc_u32 s23, s83, 0
	s_add_i32 s52, s53, s26
	v_lshl_add_u64 v[142:143], s[22:23], 0, v[132:133]
	s_mov_b32 m0, s52
	s_nop 0
	global_load_lds_dwordx4 v[142:143], off
	v_lshl_add_u64 v[142:143], s[22:23], 0, v[130:131]
	s_add_i32 m0, s52, 0x2000
	s_nop 0
	global_load_lds_dwordx4 v[142:143], off
	v_add_u32_e32 v141, 0x10000, v138
	ds_read_b128 v[142:145], v141
	ds_read_b128 v[146:149], v141 offset:1024
	ds_read_b128 v[150:153], v141 offset:2048
	ds_read_b128 v[154:157], v141 offset:3072
	s_waitcnt vmcnt(6)
	s_barrier
	v_mfma_f32_16x16x32_bf16 v[42:45], v[204:207], v[158:161], v[42:45]
	v_mfma_f32_16x16x32_bf16 v[34:37], v[224:227], v[158:161], v[34:37]
	v_mfma_f32_16x16x32_bf16 v[26:29], v[204:207], v[166:169], v[26:29]
	v_mfma_f32_16x16x32_bf16 v[18:21], v[224:227], v[166:169], v[18:21]
	v_mfma_f32_16x16x32_bf16 v[14:17], v[204:207], v[174:177], v[14:17]
	v_mfma_f32_16x16x32_bf16 v[10:13], v[224:227], v[174:177], v[10:13]
	v_mfma_f32_16x16x32_bf16 v[6:9], v[204:207], v[196:199], v[6:9]
	v_mfma_f32_16x16x32_bf16 v[2:5], v[224:227], v[196:199], v[2:5]
	v_mfma_f32_16x16x32_bf16 v[42:45], v[208:211], v[162:165], v[42:45]
	v_mfma_f32_16x16x32_bf16 v[34:37], v[228:231], v[162:165], v[34:37]
	v_mfma_f32_16x16x32_bf16 v[26:29], v[208:211], v[170:173], v[26:29]
	v_mfma_f32_16x16x32_bf16 v[18:21], v[228:231], v[170:173], v[18:21]
	v_mfma_f32_16x16x32_bf16 v[14:17], v[208:211], v[192:195], v[14:17]
	v_mfma_f32_16x16x32_bf16 v[10:13], v[228:231], v[192:195], v[10:13]
	v_mfma_f32_16x16x32_bf16 v[6:9], v[208:211], v[200:203], v[6:9]
	v_mfma_f32_16x16x32_bf16 v[2:5], v[228:231], v[200:203], v[2:5]
	s_add_i32 s51, s51, 2
	s_add_u32 s80, s80, 0x100
	s_addc_u32 s81, s81, 0
	s_add_u32 s49, s49, 0x100
	s_addc_u32 s50, s50, 0
	s_cmp_gt_u32 s51, 29
	s_barrier
	s_cbranch_scc0 .LBB0_240
	s_waitcnt lgkmcnt(0)
	v_readlane_b32 s48, v254, 40
	v_lshl_or_b32 v142, s45, 8, v139
	v_readlane_b32 s52, v254, 44
	v_readlane_b32 s53, v254, 45
	v_lshl_add_u32 v141, s46, 8, v1
	v_ashrrev_i32_e32 v143, 31, v142
	v_mov_b64_e32 v[144:145], s[52:53]
	s_movk_i32 s19, 0x1400
	v_mad_i64_i32 v[146:147], s[22:23], v141, s19, v[144:145]
	v_lshlrev_b64 v[142:143], 2, v[142:143]
	v_lshl_add_u64 v[146:147], v[146:147], 0, v[142:143]
	global_store_dwordx4 v[146:147], v[126:129], off
	global_store_dwordx4 v[146:147], v[122:125], off offset:64
	global_store_dwordx4 v[146:147], v[106:109], off offset:512
	global_store_dwordx4 v[146:147], v[98:101], off offset:576
	s_movk_i32 s94, 0x1400
	s_and_b64 vcc, exec, s[0:1]
	v_or_b32_e32 v98, 16, v141
	v_mad_i64_i32 v[98:99], s[22:23], v98, s19, v[144:145]
	v_lshl_add_u64 v[98:99], v[98:99], 0, v[142:143]
	global_store_dwordx4 v[98:99], v[118:121], off
	global_store_dwordx4 v[98:99], v[114:117], off offset:64
	global_store_dwordx4 v[98:99], v[90:93], off offset:512
	global_store_dwordx4 v[98:99], v[82:85], off offset:576
	s_mov_b32 s45, s18
	s_mov_b32 s46, s20
	v_or_b32_e32 v82, 32, v141
	v_mad_i64_i32 v[82:83], s[22:23], v82, s19, v[144:145]
	v_lshl_add_u64 v[82:83], v[82:83], 0, v[142:143]
	global_store_dwordx4 v[82:83], v[110:113], off
	global_store_dwordx4 v[82:83], v[102:105], off offset:64
	global_store_dwordx4 v[82:83], v[78:81], off offset:512
	global_store_dwordx4 v[82:83], v[74:77], off offset:576
	s_mov_b64 s[80:81], s[30:31]
	v_readlane_b32 s49, v254, 41
	v_or_b32_e32 v74, 48, v141
	v_mad_i64_i32 v[74:75], s[22:23], v74, s19, v[144:145]
	v_lshl_add_u64 v[74:75], v[74:75], 0, v[142:143]
	global_store_dwordx4 v[74:75], v[94:97], off
	global_store_dwordx4 v[74:75], v[86:89], off offset:64
	global_store_dwordx4 v[74:75], v[70:73], off offset:512
	global_store_dwordx4 v[74:75], v[66:69], off offset:576
	v_readlane_b32 s50, v254, 42
	v_readlane_b32 s51, v254, 43
	v_add_u32_e32 v66, 0x80, v141
	v_mad_i64_i32 v[66:67], s[22:23], v66, s19, v[144:145]
	v_lshl_add_u64 v[66:67], v[66:67], 0, v[142:143]
	global_store_dwordx4 v[66:67], v[62:65], off
	global_store_dwordx4 v[66:67], v[58:61], off offset:64
	global_store_dwordx4 v[66:67], v[42:45], off offset:512
	global_store_dwordx4 v[66:67], v[34:37], off offset:576
	v_readlane_b32 s54, v254, 46
	v_readlane_b32 s55, v254, 47
	v_add_u32_e32 v34, 0x90, v141
	v_mad_i64_i32 v[34:35], s[22:23], v34, s19, v[144:145]
	v_lshl_add_u64 v[34:35], v[34:35], 0, v[142:143]
	global_store_dwordx4 v[34:35], v[54:57], off
	global_store_dwordx4 v[34:35], v[50:53], off offset:64
	global_store_dwordx4 v[34:35], v[26:29], off offset:512
	global_store_dwordx4 v[34:35], v[18:21], off offset:576
	v_readlane_b32 s56, v254, 48
	v_readlane_b32 s57, v254, 49
	v_add_u32_e32 v18, 0xa0, v141
	v_mad_i64_i32 v[18:19], s[22:23], v18, s19, v[144:145]
	v_lshl_add_u64 v[18:19], v[18:19], 0, v[142:143]
	global_store_dwordx4 v[18:19], v[46:49], off
	global_store_dwordx4 v[18:19], v[38:41], off offset:64
	global_store_dwordx4 v[18:19], v[14:17], off offset:512
	global_store_dwordx4 v[18:19], v[10:13], off offset:576
	v_readlane_b32 s58, v254, 50
	v_readlane_b32 s59, v254, 51
	v_add_u32_e32 v10, 0xb0, v141
	v_mad_i64_i32 v[10:11], s[22:23], v10, s19, v[144:145]
	v_lshl_add_u64 v[10:11], v[10:11], 0, v[142:143]
	s_mov_b64 s[22:23], s[38:39]
	v_readlane_b32 s60, v254, 52
	v_readlane_b32 s61, v254, 53
	v_readlane_b32 s62, v254, 54
	v_readlane_b32 s63, v254, 55
	global_store_dwordx4 v[10:11], v[30:33], off
	global_store_dwordx4 v[10:11], v[22:25], off offset:64
	global_store_dwordx4 v[10:11], v[6:9], off offset:512
	global_store_dwordx4 v[10:11], v[2:5], off offset:576
	s_cbranch_vccz .LBB0_237
	s_waitcnt vmcnt(0)
	v_readlane_b32 s44, v255, 30
	s_cmpk_gt_u32 s25, 0xff
	v_readlane_b32 s45, v255, 31
	v_readlane_b32 s42, v255, 32
	s_cbranch_scc1 .LBB0_244
	s_barrier

.LBB0_357:
	s_add_u32 s22, s20, 0xfffe0080
	s_addc_u32 s23, s21, -1
	s_add_i32 s52, 0, 0x10000
	s_cmp_eq_u32 s51, 4
	s_cselect_b32 s23, s31, s23
	s_cselect_b32 s22, s47, s22
	s_cselect_b32 s85, s19, s50
	s_cselect_b32 s84, s48, s49
	v_lshl_add_u64 v[178:179], s[20:21], 0, v[138:139]
	s_add_i32 m0, s27, 0xc000
	ds_read_b128 v[162:165], v144
	ds_read_b128 v[166:169], v144 offset:1024
	ds_read_b128 v[170:173], v144 offset:2048
	ds_read_b128 v[174:177], v144 offset:3072
	ds_read_b128 v[192:195], v144 offset:4096
	ds_read_b128 v[196:199], v144 offset:5120
	ds_read_b128 v[200:203], v144 offset:6144
	ds_read_b128 v[204:207], v144 offset:7168
	global_load_lds_dwordx4 v[178:179], off
	v_lshl_add_u64 v[178:179], s[20:21], 0, v[140:141]
	s_add_i32 m0, s27, 0xe000
	s_nop 0
	global_load_lds_dwordx4 v[178:179], off
	s_waitcnt lgkmcnt(8)
	s_barrier
	s_waitcnt lgkmcnt(0)
	s_waitcnt lgkmcnt(0)
	v_mfma_f32_16x16x32_bf16 v[126:129], v[146:149], v[162:165], v[126:129]
	v_mfma_f32_16x16x32_bf16 v[122:125], v[154:157], v[162:165], v[122:125]
	v_mfma_f32_16x16x32_bf16 v[118:121], v[146:149], v[170:173], v[118:121]
	v_mfma_f32_16x16x32_bf16 v[114:117], v[154:157], v[170:173], v[114:117]
	v_mfma_f32_16x16x32_bf16 v[102:105], v[146:149], v[192:195], v[102:105]
	v_mfma_f32_16x16x32_bf16 v[98:101], v[154:157], v[192:195], v[98:101]
	v_mfma_f32_16x16x32_bf16 v[86:89], v[146:149], v[200:203], v[86:89]
	v_mfma_f32_16x16x32_bf16 v[82:85], v[154:157], v[200:203], v[82:85]
	v_mfma_f32_16x16x32_bf16 v[126:129], v[150:153], v[166:169], v[126:129]
	v_mfma_f32_16x16x32_bf16 v[122:125], v[158:161], v[166:169], v[122:125]
	v_mfma_f32_16x16x32_bf16 v[118:121], v[150:153], v[174:177], v[118:121]
	v_mfma_f32_16x16x32_bf16 v[114:117], v[158:161], v[174:177], v[114:117]
	v_mfma_f32_16x16x32_bf16 v[102:105], v[150:153], v[196:199], v[102:105]
	v_mfma_f32_16x16x32_bf16 v[98:101], v[158:161], v[196:199], v[98:101]
	v_mfma_f32_16x16x32_bf16 v[86:89], v[150:153], v[204:207], v[86:89]
	v_mfma_f32_16x16x32_bf16 v[82:85], v[158:161], v[204:207], v[82:85]
	s_barrier
	s_add_i32 s54, 0, 0x14000
	s_add_i32 s52, s52, s26
	v_add_u32_e32 v145, s54, v142
	v_lshl_add_u64 v[178:179], s[84:85], 0, v[134:135]
	s_mov_b32 m0, s52
	ds_read_b128 v[208:211], v145
	ds_read_b128 v[224:227], v145 offset:1024
	ds_read_b128 v[228:231], v145 offset:2048
	ds_read_b128 v[232:235], v145 offset:3072
	global_load_lds_dwordx4 v[178:179], off
	v_lshl_add_u64 v[212:213], s[84:85], 0, v[130:131]
	s_add_i32 m0, s52, 0x2000
	s_nop 0
	global_load_lds_dwordx4 v[212:213], off
	s_barrier
	s_waitcnt lgkmcnt(0)
	s_waitcnt lgkmcnt(0)
	v_mfma_f32_16x16x32_bf16 v[110:113], v[208:211], v[162:165], v[110:113]
	v_mfma_f32_16x16x32_bf16 v[106:109], v[228:231], v[162:165], v[106:109]
	v_mfma_f32_16x16x32_bf16 v[94:97], v[208:211], v[170:173], v[94:97]
	v_mfma_f32_16x16x32_bf16 v[90:93], v[228:231], v[170:173], v[90:93]
	v_mfma_f32_16x16x32_bf16 v[78:81], v[208:211], v[192:195], v[78:81]
	v_mfma_f32_16x16x32_bf16 v[74:77], v[228:231], v[192:195], v[74:77]
	v_mfma_f32_16x16x32_bf16 v[70:73], v[208:211], v[200:203], v[70:73]
	v_mfma_f32_16x16x32_bf16 v[66:69], v[228:231], v[200:203], v[66:69]
	v_mfma_f32_16x16x32_bf16 v[110:113], v[224:227], v[166:169], v[110:113]
	v_mfma_f32_16x16x32_bf16 v[106:109], v[232:235], v[166:169], v[106:109]
	v_mfma_f32_16x16x32_bf16 v[94:97], v[224:227], v[174:177], v[94:97]
	v_mfma_f32_16x16x32_bf16 v[90:93], v[232:235], v[174:177], v[90:93]
	v_mfma_f32_16x16x32_bf16 v[78:81], v[224:227], v[196:199], v[78:81]
	v_mfma_f32_16x16x32_bf16 v[74:77], v[232:235], v[196:199], v[74:77]
	v_mfma_f32_16x16x32_bf16 v[70:73], v[224:227], v[204:207], v[70:73]
	v_mfma_f32_16x16x32_bf16 v[66:69], v[232:235], v[204:207], v[66:69]
	s_mov_b32 m0, s27
	v_lshl_add_u64 v[236:237], s[22:23], 0, v[136:137]
	s_barrier
	ds_read_b128 v[162:165], v144 offset:16384
	ds_read_b128 v[166:169], v144 offset:17408
	ds_read_b128 v[170:173], v144 offset:18432
	ds_read_b128 v[174:177], v144 offset:19456
	ds_read_b128 v[192:195], v144 offset:20480
	ds_read_b128 v[196:199], v144 offset:21504
	ds_read_b128 v[200:203], v144 offset:22528
	ds_read_b128 v[204:207], v144 offset:23552
	global_load_lds_dwordx4 v[236:237], off
	v_lshl_add_u64 v[238:239], s[22:23], 0, v[132:133]
	s_mov_b32 m0, s28
	s_nop 0
	global_load_lds_dwordx4 v[238:239], off
	s_waitcnt vmcnt(10)
	s_barrier
	s_waitcnt lgkmcnt(0)
	s_waitcnt lgkmcnt(0)
	v_mfma_f32_16x16x32_bf16 v[62:65], v[146:149], v[162:165], v[62:65]
	v_mfma_f32_16x16x32_bf16 v[58:61], v[154:157], v[162:165], v[58:61]
	v_mfma_f32_16x16x32_bf16 v[54:57], v[146:149], v[170:173], v[54:57]
	v_mfma_f32_16x16x32_bf16 v[50:53], v[154:157], v[170:173], v[50:53]
	v_mfma_f32_16x16x32_bf16 v[38:41], v[146:149], v[192:195], v[38:41]
	v_mfma_f32_16x16x32_bf16 v[34:37], v[154:157], v[192:195], v[34:37]
	v_mfma_f32_16x16x32_bf16 v[22:25], v[146:149], v[200:203], v[22:25]
	v_mfma_f32_16x16x32_bf16 v[18:21], v[154:157], v[200:203], v[18:21]
	v_mfma_f32_16x16x32_bf16 v[62:65], v[150:153], v[166:169], v[62:65]
	v_mfma_f32_16x16x32_bf16 v[58:61], v[158:161], v[166:169], v[58:61]
	v_mfma_f32_16x16x32_bf16 v[54:57], v[150:153], v[174:177], v[54:57]
	v_mfma_f32_16x16x32_bf16 v[50:53], v[158:161], v[174:177], v[50:53]
	v_mfma_f32_16x16x32_bf16 v[38:41], v[150:153], v[196:199], v[38:41]
	v_mfma_f32_16x16x32_bf16 v[34:37], v[158:161], v[196:199], v[34:37]
	v_mfma_f32_16x16x32_bf16 v[22:25], v[150:153], v[204:207], v[22:25]
	v_mfma_f32_16x16x32_bf16 v[18:21], v[158:161], v[204:207], v[18:21]
	s_barrier
	s_add_u32 s52, s84, 0x20000
	s_addc_u32 s53, s85, 0
	s_add_i32 s54, s54, s26
	v_lshl_add_u64 v[146:147], s[52:53], 0, v[134:135]
	s_mov_b32 m0, s54
	s_nop 0
	global_load_lds_dwordx4 v[146:147], off
	v_lshl_add_u64 v[146:147], s[52:53], 0, v[130:131]
	s_add_i32 m0, s54, 0x2000
	s_nop 0
	global_load_lds_dwordx4 v[146:147], off
	v_add_u32_e32 v145, 0x18000, v142
	ds_read_b128 v[146:149], v145
	ds_read_b128 v[150:153], v145 offset:1024
	ds_read_b128 v[154:157], v145 offset:2048
	ds_read_b128 v[158:161], v145 offset:3072
	s_waitcnt vmcnt(6)
	s_barrier
	v_mfma_f32_16x16x32_bf16 v[46:49], v[208:211], v[162:165], v[46:49]
	v_mfma_f32_16x16x32_bf16 v[42:45], v[228:231], v[162:165], v[42:45]
	v_mfma_f32_16x16x32_bf16 v[30:33], v[208:211], v[170:173], v[30:33]
	v_mfma_f32_16x16x32_bf16 v[26:29], v[228:231], v[170:173], v[26:29]
	v_mfma_f32_16x16x32_bf16 v[14:17], v[208:211], v[192:195], v[14:17]
	v_mfma_f32_16x16x32_bf16 v[10:13], v[228:231], v[192:195], v[10:13]
	v_mfma_f32_16x16x32_bf16 v[6:9], v[208:211], v[200:203], v[6:9]
	v_mfma_f32_16x16x32_bf16 v[2:5], v[228:231], v[200:203], v[2:5]
	v_mfma_f32_16x16x32_bf16 v[46:49], v[224:227], v[166:169], v[46:49]
	v_mfma_f32_16x16x32_bf16 v[42:45], v[232:235], v[166:169], v[42:45]
	v_mfma_f32_16x16x32_bf16 v[30:33], v[224:227], v[174:177], v[30:33]
	v_mfma_f32_16x16x32_bf16 v[26:29], v[232:235], v[174:177], v[26:29]
	v_mfma_f32_16x16x32_bf16 v[14:17], v[224:227], v[196:199], v[14:17]
	v_mfma_f32_16x16x32_bf16 v[10:13], v[232:235], v[196:199], v[10:13]
	v_mfma_f32_16x16x32_bf16 v[6:9], v[224:227], v[204:207], v[6:9]
	v_mfma_f32_16x16x32_bf16 v[2:5], v[232:235], v[204:207], v[2:5]
	s_add_i32 s52, 0, 0x18000
	s_barrier
	s_add_u32 s22, s22, 0x20000
	s_addc_u32 s23, s23, 0
	s_mov_b32 m0, s29
	v_lshl_add_u64 v[208:209], s[22:23], 0, v[136:137]
	ds_read_b128 v[162:165], v144 offset:32768
	ds_read_b128 v[166:169], v144 offset:33792
	ds_read_b128 v[170:173], v144 offset:34816
	ds_read_b128 v[174:177], v144 offset:35840
	ds_read_b128 v[192:195], v144 offset:36864
	ds_read_b128 v[196:199], v144 offset:37888
	ds_read_b128 v[200:203], v144 offset:38912
	ds_read_b128 v[204:207], v144 offset:39936
	global_load_lds_dwordx4 v[208:209], off
	v_lshl_add_u64 v[208:209], s[22:23], 0, v[132:133]
	s_mov_b32 m0, s36
	s_nop 0
	global_load_lds_dwordx4 v[208:209], off
	s_waitcnt lgkmcnt(8)
	s_barrier
	s_waitcnt lgkmcnt(0)
	s_waitcnt lgkmcnt(0)
	v_mfma_f32_16x16x32_bf16 v[126:129], v[146:149], v[162:165], v[126:129]
	v_mfma_f32_16x16x32_bf16 v[122:125], v[154:157], v[162:165], v[122:125]
	v_mfma_f32_16x16x32_bf16 v[118:121], v[146:149], v[170:173], v[118:121]
	v_mfma_f32_16x16x32_bf16 v[114:117], v[154:157], v[170:173], v[114:117]
	v_mfma_f32_16x16x32_bf16 v[102:105], v[146:149], v[192:195], v[102:105]
	v_mfma_f32_16x16x32_bf16 v[98:101], v[154:157], v[192:195], v[98:101]
	v_mfma_f32_16x16x32_bf16 v[86:89], v[146:149], v[200:203], v[86:89]
	v_mfma_f32_16x16x32_bf16 v[82:85], v[154:157], v[200:203], v[82:85]
	v_mfma_f32_16x16x32_bf16 v[126:129], v[150:153], v[166:169], v[126:129]
	v_mfma_f32_16x16x32_bf16 v[122:125], v[158:161], v[166:169], v[122:125]
	v_mfma_f32_16x16x32_bf16 v[118:121], v[150:153], v[174:177], v[118:121]
	v_mfma_f32_16x16x32_bf16 v[114:117], v[158:161], v[174:177], v[114:117]
	v_mfma_f32_16x16x32_bf16 v[102:105], v[150:153], v[196:199], v[102:105]
	v_mfma_f32_16x16x32_bf16 v[98:101], v[158:161], v[196:199], v[98:101]
	v_mfma_f32_16x16x32_bf16 v[86:89], v[150:153], v[204:207], v[86:89]
	v_mfma_f32_16x16x32_bf16 v[82:85], v[158:161], v[204:207], v[82:85]
	s_barrier
	s_add_i32 s53, 0, 0x1c000
	s_add_i32 s22, s52, s26
	v_add_u32_e32 v145, s53, v142
	v_lshl_add_u64 v[178:179], v[178:179], 0, s[78:79]
	s_mov_b32 m0, s22
	ds_read_b128 v[208:211], v145
	ds_read_b128 v[224:227], v145 offset:1024
	ds_read_b128 v[228:231], v145 offset:2048
	ds_read_b128 v[232:235], v145 offset:3072
	global_load_lds_dwordx4 v[178:179], off
	v_lshl_add_u64 v[178:179], v[212:213], 0, s[78:79]
	s_add_i32 m0, s22, 0x2000
	s_nop 0
	global_load_lds_dwordx4 v[178:179], off
	s_barrier
	s_waitcnt lgkmcnt(0)
	s_waitcnt lgkmcnt(0)
	v_mfma_f32_16x16x32_bf16 v[110:113], v[208:211], v[162:165], v[110:113]
	v_mfma_f32_16x16x32_bf16 v[106:109], v[228:231], v[162:165], v[106:109]
	v_mfma_f32_16x16x32_bf16 v[94:97], v[208:211], v[170:173], v[94:97]
	v_mfma_f32_16x16x32_bf16 v[90:93], v[228:231], v[170:173], v[90:93]
	v_mfma_f32_16x16x32_bf16 v[78:81], v[208:211], v[192:195], v[78:81]
	v_mfma_f32_16x16x32_bf16 v[74:77], v[228:231], v[192:195], v[74:77]
	v_mfma_f32_16x16x32_bf16 v[70:73], v[208:211], v[200:203], v[70:73]
	v_mfma_f32_16x16x32_bf16 v[66:69], v[228:231], v[200:203], v[66:69]
	v_mfma_f32_16x16x32_bf16 v[110:113], v[224:227], v[166:169], v[110:113]
	v_mfma_f32_16x16x32_bf16 v[106:109], v[232:235], v[166:169], v[106:109]
	v_mfma_f32_16x16x32_bf16 v[94:97], v[224:227], v[174:177], v[94:97]
	v_mfma_f32_16x16x32_bf16 v[90:93], v[232:235], v[174:177], v[90:93]
	v_mfma_f32_16x16x32_bf16 v[78:81], v[224:227], v[196:199], v[78:81]
	v_mfma_f32_16x16x32_bf16 v[74:77], v[232:235], v[196:199], v[74:77]
	v_mfma_f32_16x16x32_bf16 v[70:73], v[224:227], v[204:207], v[70:73]
	v_mfma_f32_16x16x32_bf16 v[66:69], v[232:235], v[204:207], v[66:69]
	s_mov_b32 m0, s42
	v_lshl_add_u64 v[178:179], v[236:237], 0, s[78:79]
	s_barrier
	ds_read_b128 v[162:165], v144 offset:49152
	ds_read_b128 v[166:169], v144 offset:50176
	ds_read_b128 v[170:173], v144 offset:51200
	ds_read_b128 v[174:177], v144 offset:52224
	ds_read_b128 v[192:195], v144 offset:53248
	ds_read_b128 v[196:199], v144 offset:54272
	ds_read_b128 v[200:203], v144 offset:55296
	ds_read_b128 v[204:207], v144 offset:56320
	global_load_lds_dwordx4 v[178:179], off
	v_lshl_add_u64 v[178:179], v[238:239], 0, s[78:79]
	s_mov_b32 m0, s43
	s_nop 0
	global_load_lds_dwordx4 v[178:179], off
	s_waitcnt vmcnt(10)
	s_barrier
	s_waitcnt lgkmcnt(0)
	s_waitcnt lgkmcnt(0)
	v_mfma_f32_16x16x32_bf16 v[62:65], v[146:149], v[162:165], v[62:65]
	v_mfma_f32_16x16x32_bf16 v[58:61], v[154:157], v[162:165], v[58:61]
	v_mfma_f32_16x16x32_bf16 v[54:57], v[146:149], v[170:173], v[54:57]
	v_mfma_f32_16x16x32_bf16 v[50:53], v[154:157], v[170:173], v[50:53]
	v_mfma_f32_16x16x32_bf16 v[38:41], v[146:149], v[192:195], v[38:41]
	v_mfma_f32_16x16x32_bf16 v[34:37], v[154:157], v[192:195], v[34:37]
	v_mfma_f32_16x16x32_bf16 v[22:25], v[146:149], v[200:203], v[22:25]
	v_mfma_f32_16x16x32_bf16 v[18:21], v[154:157], v[200:203], v[18:21]
	v_mfma_f32_16x16x32_bf16 v[62:65], v[150:153], v[166:169], v[62:65]
	v_mfma_f32_16x16x32_bf16 v[58:61], v[158:161], v[166:169], v[58:61]
	v_mfma_f32_16x16x32_bf16 v[54:57], v[150:153], v[174:177], v[54:57]
	v_mfma_f32_16x16x32_bf16 v[50:53], v[158:161], v[174:177], v[50:53]
	v_mfma_f32_16x16x32_bf16 v[38:41], v[150:153], v[196:199], v[38:41]
	v_mfma_f32_16x16x32_bf16 v[34:37], v[158:161], v[196:199], v[34:37]
	v_mfma_f32_16x16x32_bf16 v[22:25], v[150:153], v[204:207], v[22:25]
	v_mfma_f32_16x16x32_bf16 v[18:21], v[158:161], v[204:207], v[18:21]
	s_barrier
	s_add_u32 s22, s84, 0x20080
	s_addc_u32 s23, s85, 0
	s_add_i32 s52, s53, s26
	v_lshl_add_u64 v[146:147], s[22:23], 0, v[134:135]
	s_mov_b32 m0, s52
	s_nop 0
	global_load_lds_dwordx4 v[146:147], off
	v_lshl_add_u64 v[146:147], s[22:23], 0, v[130:131]
	s_add_i32 m0, s52, 0x2000
	s_nop 0
	global_load_lds_dwordx4 v[146:147], off
	v_add_u32_e32 v145, 0x10000, v142
	ds_read_b128 v[146:149], v145
	ds_read_b128 v[150:153], v145 offset:1024
	ds_read_b128 v[154:157], v145 offset:2048
	ds_read_b128 v[158:161], v145 offset:3072
	s_waitcnt vmcnt(6)
	s_barrier
	v_mfma_f32_16x16x32_bf16 v[46:49], v[208:211], v[162:165], v[46:49]
	v_mfma_f32_16x16x32_bf16 v[42:45], v[228:231], v[162:165], v[42:45]
	v_mfma_f32_16x16x32_bf16 v[30:33], v[208:211], v[170:173], v[30:33]
	v_mfma_f32_16x16x32_bf16 v[26:29], v[228:231], v[170:173], v[26:29]
	v_mfma_f32_16x16x32_bf16 v[14:17], v[208:211], v[192:195], v[14:17]
	v_mfma_f32_16x16x32_bf16 v[10:13], v[228:231], v[192:195], v[10:13]
	v_mfma_f32_16x16x32_bf16 v[6:9], v[208:211], v[200:203], v[6:9]
	v_mfma_f32_16x16x32_bf16 v[2:5], v[228:231], v[200:203], v[2:5]
	v_mfma_f32_16x16x32_bf16 v[46:49], v[224:227], v[166:169], v[46:49]
	v_mfma_f32_16x16x32_bf16 v[42:45], v[232:235], v[166:169], v[42:45]
	v_mfma_f32_16x16x32_bf16 v[30:33], v[224:227], v[174:177], v[30:33]
	v_mfma_f32_16x16x32_bf16 v[26:29], v[232:235], v[174:177], v[26:29]
	v_mfma_f32_16x16x32_bf16 v[14:17], v[224:227], v[196:199], v[14:17]
	v_mfma_f32_16x16x32_bf16 v[10:13], v[232:235], v[196:199], v[10:13]
	v_mfma_f32_16x16x32_bf16 v[6:9], v[224:227], v[204:207], v[6:9]
	v_mfma_f32_16x16x32_bf16 v[2:5], v[232:235], v[204:207], v[2:5]
	s_add_i32 s51, s51, 2
	s_add_u32 s20, s20, 0x100
	s_addc_u32 s21, s21, 0
	s_add_u32 s49, s49, 0x100
	s_addc_u32 s50, s50, 0
	s_cmp_gt_u32 s51, 5
	s_barrier
	s_cbranch_scc0 .LBB0_357
	s_waitcnt lgkmcnt(0)
	v_lshl_add_u32 v146, s46, 8, v1
	v_lshl_or_b32 v148, s45, 8, v143
	v_ashrrev_i32_e32 v147, 31, v146
	v_readlane_b32 s48, v254, 40
	v_ashrrev_i32_e32 v149, 31, v148
	v_lshlrev_b64 v[150:151], 12, v[146:147]
	v_readlane_b32 s60, v254, 52
	v_readlane_b32 s61, v254, 53
	v_lshlrev_b64 v[148:149], 1, v[148:149]
	s_mov_b32 s19, 0x80000
	v_lshl_add_u64 v[150:151], s[60:61], 0, v[150:151]
	v_lshl_add_u64 v[150:151], v[150:151], 0, v[148:149]
	s_mov_b64 s[20:21], 0x80000
	v_cvt_pk_bf16_f32 v62, v62, v63
	v_cvt_pk_bf16_f32 v63, v64, v65
	v_cvt_pk_bf16_f32 v64, v58, v59
	v_add_co_u32_e32 v58, vcc, s19, v150
	v_cvt_pk_bf16_f32 v70, v70, v71
	v_cvt_pk_bf16_f32 v71, v72, v73
	v_cvt_pk_bf16_f32 v72, v66, v67
	v_lshl_add_u64 v[66:67], v[150:151], 0, s[20:21]
	v_addc_co_u32_e32 v59, vcc, 0, v151, vcc
	v_cvt_pk_bf16_f32 v46, v46, v47
	v_cvt_pk_bf16_f32 v47, v48, v49
	v_cvt_pk_bf16_f32 v48, v42, v43
	v_cvt_pk_bf16_f32 v49, v44, v45
	s_mov_b32 s19, 0x90000
	v_cvt_pk_bf16_f32 v110, v110, v111
	v_cvt_pk_bf16_f32 v111, v112, v113
	v_cvt_pk_bf16_f32 v112, v106, v107
	v_or_b32_e32 v106, 16, v146
	global_store_dwordx4 v[66:67], v[46:49], off offset:256
	s_mov_b64 s[20:21], 0x90000
	v_ashrrev_i32_e32 v107, 31, v106
	v_add_co_u32_e32 v48, vcc, s19, v150
	v_cvt_pk_bf16_f32 v94, v94, v95
	v_cvt_pk_bf16_f32 v95, v96, v97
	v_cvt_pk_bf16_f32 v96, v90, v91
	v_or_b32_e32 v90, 32, v146
	v_lshl_add_u64 v[46:47], v[150:151], 0, s[20:21]
	v_addc_co_u32_e32 v49, vcc, 0, v151, vcc
	v_cvt_pk_bf16_f32 v30, v30, v31
	v_cvt_pk_bf16_f32 v31, v32, v33
	v_cvt_pk_bf16_f32 v32, v26, v27
	v_cvt_pk_bf16_f32 v33, v28, v29
	s_mov_b32 s19, 0xa0000
	v_lshlrev_b64 v[106:107], 12, v[106:107]
	v_ashrrev_i32_e32 v91, 31, v90
	v_cvt_pk_bf16_f32 v78, v78, v79
	v_cvt_pk_bf16_f32 v79, v80, v81
	v_cvt_pk_bf16_f32 v80, v74, v75
	v_or_b32_e32 v74, 48, v146
	global_store_dwordx4 v[46:47], v[30:33], off offset:256
	s_mov_b64 s[20:21], 0xa0000
	v_cvt_pk_bf16_f32 v113, v108, v109
	v_add_co_u32_e32 v32, vcc, s19, v150
	v_lshl_add_u64 v[106:107], s[60:61], 0, v[106:107]
	v_lshlrev_b64 v[90:91], 12, v[90:91]
	v_ashrrev_i32_e32 v75, 31, v74
	v_lshl_add_u64 v[30:31], v[150:151], 0, s[20:21]
	v_addc_co_u32_e32 v33, vcc, 0, v151, vcc
	v_cvt_pk_bf16_f32 v14, v14, v15
	v_cvt_pk_bf16_f32 v15, v16, v17
	v_cvt_pk_bf16_f32 v16, v10, v11
	v_cvt_pk_bf16_f32 v17, v12, v13
	s_mov_b32 s19, 0xb0000
	global_store_dwordx4 v[150:151], v[110:113], off offset:256
	v_cvt_pk_bf16_f32 v97, v92, v93
	v_lshl_add_u64 v[90:91], s[60:61], 0, v[90:91]
	v_lshl_add_u64 v[110:111], v[106:107], 0, v[148:149]
	v_lshlrev_b64 v[74:75], 12, v[74:75]
	global_store_dwordx4 v[30:31], v[14:17], off offset:256
	global_store_dwordx4 v[110:111], v[94:97], off offset:256
	v_cvt_pk_bf16_f32 v81, v76, v77
	v_add_co_u32_e32 v16, vcc, s19, v150
	v_lshl_add_u64 v[94:95], v[90:91], 0, v[148:149]
	v_lshl_add_u64 v[74:75], s[60:61], 0, v[74:75]
	s_mov_b64 s[20:21], 0xb0000
	v_addc_co_u32_e32 v17, vcc, 0, v151, vcc
	v_cvt_pk_bf16_f32 v126, v126, v127
	v_cvt_pk_bf16_f32 v127, v128, v129
	v_cvt_pk_bf16_f32 v128, v122, v123
	v_cvt_pk_bf16_f32 v129, v124, v125
	v_cvt_pk_bf16_f32 v106, v118, v119
	v_cvt_pk_bf16_f32 v107, v120, v121
	v_cvt_pk_bf16_f32 v108, v114, v115
	v_cvt_pk_bf16_f32 v109, v116, v117
	v_cvt_pk_bf16_f32 v90, v102, v103
	v_cvt_pk_bf16_f32 v91, v104, v105
	v_cvt_pk_bf16_f32 v92, v98, v99
	v_cvt_pk_bf16_f32 v93, v100, v101
	global_store_dwordx4 v[94:95], v[78:81], off offset:256
	v_cvt_pk_bf16_f32 v76, v82, v83
	v_cvt_pk_bf16_f32 v77, v84, v85
	v_lshl_add_u64 v[78:79], v[74:75], 0, v[148:149]
	v_cvt_pk_bf16_f32 v74, v86, v87
	v_cvt_pk_bf16_f32 v75, v88, v89
	v_cvt_pk_bf16_f32 v73, v68, v69
	v_cvt_pk_bf16_f32 v65, v60, v61
	v_cvt_pk_bf16_f32 v42, v54, v55
	v_cvt_pk_bf16_f32 v43, v56, v57
	v_cvt_pk_bf16_f32 v44, v50, v51
	v_cvt_pk_bf16_f32 v45, v52, v53
	v_cvt_pk_bf16_f32 v26, v38, v39
	v_cvt_pk_bf16_f32 v27, v40, v41
	v_cvt_pk_bf16_f32 v28, v34, v35
	v_cvt_pk_bf16_f32 v29, v36, v37
	v_lshl_add_u64 v[14:15], v[150:151], 0, s[20:21]
	v_cvt_pk_bf16_f32 v10, v22, v23
	v_cvt_pk_bf16_f32 v11, v24, v25
	v_cvt_pk_bf16_f32 v12, v18, v19
	v_cvt_pk_bf16_f32 v13, v20, v21
	v_cvt_pk_bf16_f32 v6, v6, v7
	v_cvt_pk_bf16_f32 v7, v8, v9
	v_cvt_pk_bf16_f32 v8, v2, v3
	v_cvt_pk_bf16_f32 v9, v4, v5
	s_and_b64 vcc, exec, s[38:39]
	s_mov_b32 s45, s18
	s_mov_b32 s46, s30
	s_mov_b64 s[22:23], s[82:83]
	s_mov_b64 s[20:21], s[80:81]
	s_mov_b32 s64, 0x800000
	s_movk_i32 s65, 0x1fff
	v_readlane_b32 s49, v254, 41
	v_readlane_b32 s50, v254, 42
	v_readlane_b32 s51, v254, 43
	v_readlane_b32 s52, v254, 44
	v_readlane_b32 s53, v254, 45
	v_readlane_b32 s54, v254, 46
	v_readlane_b32 s55, v254, 47
	v_readlane_b32 s56, v254, 48
	v_readlane_b32 s57, v254, 49
	v_readlane_b32 s58, v254, 50
	v_readlane_b32 s59, v254, 51
	v_readlane_b32 s62, v254, 54
	v_readlane_b32 s63, v254, 55
	global_store_dwordx4 v[150:151], v[126:129], off
	global_store_dwordx4 v[110:111], v[106:109], off
	global_store_dwordx4 v[94:95], v[90:93], off
	global_store_dwordx4 v[78:79], v[74:77], off
	global_store_dwordx4 v[78:79], v[70:73], off offset:256
	global_store_dwordx4 v[58:59], v[62:65], off
	global_store_dwordx4 v[48:49], v[42:45], off
	global_store_dwordx4 v[32:33], v[26:29], off
	global_store_dwordx4 v[16:17], v[10:13], off
	global_store_dwordx4 v[14:15], v[6:9], off offset:256
	s_cbranch_vccz .LBB0_350
	s_waitcnt vmcnt(0)
	v_readlane_b32 s44, v255, 30
	s_mov_b32 s66, s90
	s_cmpk_gt_u32 s25, 0xff
	v_readlane_b32 s45, v255, 31
	v_readlane_b32 s42, v255, 32
	s_cbranch_scc1 .LBB0_361
	s_barrier

.LBB0_373:
	s_add_u32 s22, s20, 0xfffe0080
	s_addc_u32 s23, s21, -1
	s_add_i32 s52, 0, 0x10000
	s_cmp_eq_u32 s51, 4
	s_cselect_b32 s23, s31, s23
	s_cselect_b32 s22, s47, s22
	s_cselect_b32 s83, s19, s50
	s_cselect_b32 s82, s48, s49
	v_lshl_add_u64 v[178:179], s[20:21], 0, v[138:139]
	s_add_i32 m0, s27, 0xc000
	ds_read_b128 v[162:165], v144
	ds_read_b128 v[166:169], v144 offset:1024
	ds_read_b128 v[170:173], v144 offset:2048
	ds_read_b128 v[174:177], v144 offset:3072
	ds_read_b128 v[192:195], v144 offset:4096
	ds_read_b128 v[196:199], v144 offset:5120
	ds_read_b128 v[200:203], v144 offset:6144
	ds_read_b128 v[204:207], v144 offset:7168
	global_load_lds_dwordx4 v[178:179], off
	v_lshl_add_u64 v[178:179], s[20:21], 0, v[140:141]
	s_add_i32 m0, s27, 0xe000
	s_nop 0
	global_load_lds_dwordx4 v[178:179], off
	s_waitcnt lgkmcnt(8)
	s_barrier
	s_waitcnt lgkmcnt(0)
	s_waitcnt lgkmcnt(0)
	v_mfma_f32_16x16x32_bf16 v[126:129], v[146:149], v[162:165], v[126:129]
	v_mfma_f32_16x16x32_bf16 v[122:125], v[154:157], v[162:165], v[122:125]
	v_mfma_f32_16x16x32_bf16 v[118:121], v[146:149], v[170:173], v[118:121]
	v_mfma_f32_16x16x32_bf16 v[114:117], v[154:157], v[170:173], v[114:117]
	v_mfma_f32_16x16x32_bf16 v[102:105], v[146:149], v[192:195], v[102:105]
	v_mfma_f32_16x16x32_bf16 v[98:101], v[154:157], v[192:195], v[98:101]
	v_mfma_f32_16x16x32_bf16 v[86:89], v[146:149], v[200:203], v[86:89]
	v_mfma_f32_16x16x32_bf16 v[82:85], v[154:157], v[200:203], v[82:85]
	v_mfma_f32_16x16x32_bf16 v[126:129], v[150:153], v[166:169], v[126:129]
	v_mfma_f32_16x16x32_bf16 v[122:125], v[158:161], v[166:169], v[122:125]
	v_mfma_f32_16x16x32_bf16 v[118:121], v[150:153], v[174:177], v[118:121]
	v_mfma_f32_16x16x32_bf16 v[114:117], v[158:161], v[174:177], v[114:117]
	v_mfma_f32_16x16x32_bf16 v[102:105], v[150:153], v[196:199], v[102:105]
	v_mfma_f32_16x16x32_bf16 v[98:101], v[158:161], v[196:199], v[98:101]
	v_mfma_f32_16x16x32_bf16 v[86:89], v[150:153], v[204:207], v[86:89]
	v_mfma_f32_16x16x32_bf16 v[82:85], v[158:161], v[204:207], v[82:85]
	s_barrier
	s_add_i32 s54, 0, 0x14000
	s_add_i32 s52, s52, s26
	v_add_u32_e32 v145, s54, v142
	v_lshl_add_u64 v[178:179], s[82:83], 0, v[134:135]
	s_mov_b32 m0, s52
	ds_read_b128 v[208:211], v145
	ds_read_b128 v[224:227], v145 offset:1024
	ds_read_b128 v[228:231], v145 offset:2048
	ds_read_b128 v[232:235], v145 offset:3072
	global_load_lds_dwordx4 v[178:179], off
	v_lshl_add_u64 v[212:213], s[82:83], 0, v[130:131]
	s_add_i32 m0, s52, 0x2000
	s_nop 0
	global_load_lds_dwordx4 v[212:213], off
	s_barrier
	s_waitcnt lgkmcnt(0)
	s_waitcnt lgkmcnt(0)
	v_mfma_f32_16x16x32_bf16 v[110:113], v[208:211], v[162:165], v[110:113]
	v_mfma_f32_16x16x32_bf16 v[106:109], v[228:231], v[162:165], v[106:109]
	v_mfma_f32_16x16x32_bf16 v[94:97], v[208:211], v[170:173], v[94:97]
	v_mfma_f32_16x16x32_bf16 v[90:93], v[228:231], v[170:173], v[90:93]
	v_mfma_f32_16x16x32_bf16 v[78:81], v[208:211], v[192:195], v[78:81]
	v_mfma_f32_16x16x32_bf16 v[74:77], v[228:231], v[192:195], v[74:77]
	v_mfma_f32_16x16x32_bf16 v[70:73], v[208:211], v[200:203], v[70:73]
	v_mfma_f32_16x16x32_bf16 v[66:69], v[228:231], v[200:203], v[66:69]
	v_mfma_f32_16x16x32_bf16 v[110:113], v[224:227], v[166:169], v[110:113]
	v_mfma_f32_16x16x32_bf16 v[106:109], v[232:235], v[166:169], v[106:109]
	v_mfma_f32_16x16x32_bf16 v[94:97], v[224:227], v[174:177], v[94:97]
	v_mfma_f32_16x16x32_bf16 v[90:93], v[232:235], v[174:177], v[90:93]
	v_mfma_f32_16x16x32_bf16 v[78:81], v[224:227], v[196:199], v[78:81]
	v_mfma_f32_16x16x32_bf16 v[74:77], v[232:235], v[196:199], v[74:77]
	v_mfma_f32_16x16x32_bf16 v[70:73], v[224:227], v[204:207], v[70:73]
	v_mfma_f32_16x16x32_bf16 v[66:69], v[232:235], v[204:207], v[66:69]
	s_mov_b32 m0, s27
	v_lshl_add_u64 v[236:237], s[22:23], 0, v[136:137]
	s_barrier
	ds_read_b128 v[162:165], v144 offset:16384
	ds_read_b128 v[166:169], v144 offset:17408
	ds_read_b128 v[170:173], v144 offset:18432
	ds_read_b128 v[174:177], v144 offset:19456
	ds_read_b128 v[192:195], v144 offset:20480
	ds_read_b128 v[196:199], v144 offset:21504
	ds_read_b128 v[200:203], v144 offset:22528
	ds_read_b128 v[204:207], v144 offset:23552
	global_load_lds_dwordx4 v[236:237], off
	v_lshl_add_u64 v[238:239], s[22:23], 0, v[132:133]
	s_mov_b32 m0, s28
	s_nop 0
	global_load_lds_dwordx4 v[238:239], off
	s_waitcnt vmcnt(10)
	s_barrier
	s_waitcnt lgkmcnt(0)
	s_waitcnt lgkmcnt(0)
	v_mfma_f32_16x16x32_bf16 v[62:65], v[146:149], v[162:165], v[62:65]
	v_mfma_f32_16x16x32_bf16 v[58:61], v[154:157], v[162:165], v[58:61]
	v_mfma_f32_16x16x32_bf16 v[54:57], v[146:149], v[170:173], v[54:57]
	v_mfma_f32_16x16x32_bf16 v[50:53], v[154:157], v[170:173], v[50:53]
	v_mfma_f32_16x16x32_bf16 v[38:41], v[146:149], v[192:195], v[38:41]
	v_mfma_f32_16x16x32_bf16 v[34:37], v[154:157], v[192:195], v[34:37]
	v_mfma_f32_16x16x32_bf16 v[22:25], v[146:149], v[200:203], v[22:25]
	v_mfma_f32_16x16x32_bf16 v[18:21], v[154:157], v[200:203], v[18:21]
	v_mfma_f32_16x16x32_bf16 v[62:65], v[150:153], v[166:169], v[62:65]
	v_mfma_f32_16x16x32_bf16 v[58:61], v[158:161], v[166:169], v[58:61]
	v_mfma_f32_16x16x32_bf16 v[54:57], v[150:153], v[174:177], v[54:57]
	v_mfma_f32_16x16x32_bf16 v[50:53], v[158:161], v[174:177], v[50:53]
	v_mfma_f32_16x16x32_bf16 v[38:41], v[150:153], v[196:199], v[38:41]
	v_mfma_f32_16x16x32_bf16 v[34:37], v[158:161], v[196:199], v[34:37]
	v_mfma_f32_16x16x32_bf16 v[22:25], v[150:153], v[204:207], v[22:25]
	v_mfma_f32_16x16x32_bf16 v[18:21], v[158:161], v[204:207], v[18:21]
	s_barrier
	s_add_u32 s52, s82, 0x20000
	s_addc_u32 s53, s83, 0
	s_add_i32 s54, s54, s26
	v_lshl_add_u64 v[146:147], s[52:53], 0, v[134:135]
	s_mov_b32 m0, s54
	s_nop 0
	global_load_lds_dwordx4 v[146:147], off
	v_lshl_add_u64 v[146:147], s[52:53], 0, v[130:131]
	s_add_i32 m0, s54, 0x2000
	s_nop 0
	global_load_lds_dwordx4 v[146:147], off
	v_add_u32_e32 v145, 0x18000, v142
	ds_read_b128 v[146:149], v145
	ds_read_b128 v[150:153], v145 offset:1024
	ds_read_b128 v[154:157], v145 offset:2048
	ds_read_b128 v[158:161], v145 offset:3072
	s_waitcnt vmcnt(6)
	s_barrier
	v_mfma_f32_16x16x32_bf16 v[46:49], v[208:211], v[162:165], v[46:49]
	v_mfma_f32_16x16x32_bf16 v[42:45], v[228:231], v[162:165], v[42:45]
	v_mfma_f32_16x16x32_bf16 v[30:33], v[208:211], v[170:173], v[30:33]
	v_mfma_f32_16x16x32_bf16 v[26:29], v[228:231], v[170:173], v[26:29]
	v_mfma_f32_16x16x32_bf16 v[14:17], v[208:211], v[192:195], v[14:17]
	v_mfma_f32_16x16x32_bf16 v[10:13], v[228:231], v[192:195], v[10:13]
	v_mfma_f32_16x16x32_bf16 v[6:9], v[208:211], v[200:203], v[6:9]
	v_mfma_f32_16x16x32_bf16 v[2:5], v[228:231], v[200:203], v[2:5]
	v_mfma_f32_16x16x32_bf16 v[46:49], v[224:227], v[166:169], v[46:49]
	v_mfma_f32_16x16x32_bf16 v[42:45], v[232:235], v[166:169], v[42:45]
	v_mfma_f32_16x16x32_bf16 v[30:33], v[224:227], v[174:177], v[30:33]
	v_mfma_f32_16x16x32_bf16 v[26:29], v[232:235], v[174:177], v[26:29]
	v_mfma_f32_16x16x32_bf16 v[14:17], v[224:227], v[196:199], v[14:17]
	v_mfma_f32_16x16x32_bf16 v[10:13], v[232:235], v[196:199], v[10:13]
	v_mfma_f32_16x16x32_bf16 v[6:9], v[224:227], v[204:207], v[6:9]
	v_mfma_f32_16x16x32_bf16 v[2:5], v[232:235], v[204:207], v[2:5]
	s_add_i32 s52, 0, 0x18000
	s_barrier
	s_add_u32 s22, s22, 0x20000
	s_addc_u32 s23, s23, 0
	s_mov_b32 m0, s29
	v_lshl_add_u64 v[208:209], s[22:23], 0, v[136:137]
	ds_read_b128 v[162:165], v144 offset:32768
	ds_read_b128 v[166:169], v144 offset:33792
	ds_read_b128 v[170:173], v144 offset:34816
	ds_read_b128 v[174:177], v144 offset:35840
	ds_read_b128 v[192:195], v144 offset:36864
	ds_read_b128 v[196:199], v144 offset:37888
	ds_read_b128 v[200:203], v144 offset:38912
	ds_read_b128 v[204:207], v144 offset:39936
	global_load_lds_dwordx4 v[208:209], off
	v_lshl_add_u64 v[208:209], s[22:23], 0, v[132:133]
	s_mov_b32 m0, s36
	s_nop 0
	global_load_lds_dwordx4 v[208:209], off
	s_waitcnt lgkmcnt(8)
	s_barrier
	s_waitcnt lgkmcnt(0)
	s_waitcnt lgkmcnt(0)
	v_mfma_f32_16x16x32_bf16 v[126:129], v[146:149], v[162:165], v[126:129]
	v_mfma_f32_16x16x32_bf16 v[122:125], v[154:157], v[162:165], v[122:125]
	v_mfma_f32_16x16x32_bf16 v[118:121], v[146:149], v[170:173], v[118:121]
	v_mfma_f32_16x16x32_bf16 v[114:117], v[154:157], v[170:173], v[114:117]
	v_mfma_f32_16x16x32_bf16 v[102:105], v[146:149], v[192:195], v[102:105]
	v_mfma_f32_16x16x32_bf16 v[98:101], v[154:157], v[192:195], v[98:101]
	v_mfma_f32_16x16x32_bf16 v[86:89], v[146:149], v[200:203], v[86:89]
	v_mfma_f32_16x16x32_bf16 v[82:85], v[154:157], v[200:203], v[82:85]
	v_mfma_f32_16x16x32_bf16 v[126:129], v[150:153], v[166:169], v[126:129]
	v_mfma_f32_16x16x32_bf16 v[122:125], v[158:161], v[166:169], v[122:125]
	v_mfma_f32_16x16x32_bf16 v[118:121], v[150:153], v[174:177], v[118:121]
	v_mfma_f32_16x16x32_bf16 v[114:117], v[158:161], v[174:177], v[114:117]
	v_mfma_f32_16x16x32_bf16 v[102:105], v[150:153], v[196:199], v[102:105]
	v_mfma_f32_16x16x32_bf16 v[98:101], v[158:161], v[196:199], v[98:101]
	v_mfma_f32_16x16x32_bf16 v[86:89], v[150:153], v[204:207], v[86:89]
	v_mfma_f32_16x16x32_bf16 v[82:85], v[158:161], v[204:207], v[82:85]
	s_barrier
	s_add_i32 s53, 0, 0x1c000
	s_add_i32 s22, s52, s26
	v_add_u32_e32 v145, s53, v142
	v_lshl_add_u64 v[178:179], v[178:179], 0, s[78:79]
	s_mov_b32 m0, s22
	ds_read_b128 v[208:211], v145
	ds_read_b128 v[224:227], v145 offset:1024
	ds_read_b128 v[228:231], v145 offset:2048
	ds_read_b128 v[232:235], v145 offset:3072
	global_load_lds_dwordx4 v[178:179], off
	v_lshl_add_u64 v[178:179], v[212:213], 0, s[78:79]
	s_add_i32 m0, s22, 0x2000
	s_nop 0
	global_load_lds_dwordx4 v[178:179], off
	s_barrier
	s_waitcnt lgkmcnt(0)
	s_waitcnt lgkmcnt(0)
	v_mfma_f32_16x16x32_bf16 v[110:113], v[208:211], v[162:165], v[110:113]
	v_mfma_f32_16x16x32_bf16 v[106:109], v[228:231], v[162:165], v[106:109]
	v_mfma_f32_16x16x32_bf16 v[94:97], v[208:211], v[170:173], v[94:97]
	v_mfma_f32_16x16x32_bf16 v[90:93], v[228:231], v[170:173], v[90:93]
	v_mfma_f32_16x16x32_bf16 v[78:81], v[208:211], v[192:195], v[78:81]
	v_mfma_f32_16x16x32_bf16 v[74:77], v[228:231], v[192:195], v[74:77]
	v_mfma_f32_16x16x32_bf16 v[70:73], v[208:211], v[200:203], v[70:73]
	v_mfma_f32_16x16x32_bf16 v[66:69], v[228:231], v[200:203], v[66:69]
	v_mfma_f32_16x16x32_bf16 v[110:113], v[224:227], v[166:169], v[110:113]
	v_mfma_f32_16x16x32_bf16 v[106:109], v[232:235], v[166:169], v[106:109]
	v_mfma_f32_16x16x32_bf16 v[94:97], v[224:227], v[174:177], v[94:97]
	v_mfma_f32_16x16x32_bf16 v[90:93], v[232:235], v[174:177], v[90:93]
	v_mfma_f32_16x16x32_bf16 v[78:81], v[224:227], v[196:199], v[78:81]
	v_mfma_f32_16x16x32_bf16 v[74:77], v[232:235], v[196:199], v[74:77]
	v_mfma_f32_16x16x32_bf16 v[70:73], v[224:227], v[204:207], v[70:73]
	v_mfma_f32_16x16x32_bf16 v[66:69], v[232:235], v[204:207], v[66:69]
	s_mov_b32 m0, s42
	v_lshl_add_u64 v[178:179], v[236:237], 0, s[78:79]
	s_barrier
	ds_read_b128 v[162:165], v144 offset:49152
	ds_read_b128 v[166:169], v144 offset:50176
	ds_read_b128 v[170:173], v144 offset:51200
	ds_read_b128 v[174:177], v144 offset:52224
	ds_read_b128 v[192:195], v144 offset:53248
	ds_read_b128 v[196:199], v144 offset:54272
	ds_read_b128 v[200:203], v144 offset:55296
	ds_read_b128 v[204:207], v144 offset:56320
	global_load_lds_dwordx4 v[178:179], off
	v_lshl_add_u64 v[178:179], v[238:239], 0, s[78:79]
	s_mov_b32 m0, s43
	s_nop 0
	global_load_lds_dwordx4 v[178:179], off
	s_waitcnt vmcnt(10)
	s_barrier
	s_waitcnt lgkmcnt(0)
	s_waitcnt lgkmcnt(0)
	v_mfma_f32_16x16x32_bf16 v[62:65], v[146:149], v[162:165], v[62:65]
	v_mfma_f32_16x16x32_bf16 v[58:61], v[154:157], v[162:165], v[58:61]
	v_mfma_f32_16x16x32_bf16 v[54:57], v[146:149], v[170:173], v[54:57]
	v_mfma_f32_16x16x32_bf16 v[50:53], v[154:157], v[170:173], v[50:53]
	v_mfma_f32_16x16x32_bf16 v[38:41], v[146:149], v[192:195], v[38:41]
	v_mfma_f32_16x16x32_bf16 v[34:37], v[154:157], v[192:195], v[34:37]
	v_mfma_f32_16x16x32_bf16 v[22:25], v[146:149], v[200:203], v[22:25]
	v_mfma_f32_16x16x32_bf16 v[18:21], v[154:157], v[200:203], v[18:21]
	v_mfma_f32_16x16x32_bf16 v[62:65], v[150:153], v[166:169], v[62:65]
	v_mfma_f32_16x16x32_bf16 v[58:61], v[158:161], v[166:169], v[58:61]
	v_mfma_f32_16x16x32_bf16 v[54:57], v[150:153], v[174:177], v[54:57]
	v_mfma_f32_16x16x32_bf16 v[50:53], v[158:161], v[174:177], v[50:53]
	v_mfma_f32_16x16x32_bf16 v[38:41], v[150:153], v[196:199], v[38:41]
	v_mfma_f32_16x16x32_bf16 v[34:37], v[158:161], v[196:199], v[34:37]
	v_mfma_f32_16x16x32_bf16 v[22:25], v[150:153], v[204:207], v[22:25]
	v_mfma_f32_16x16x32_bf16 v[18:21], v[158:161], v[204:207], v[18:21]
	s_barrier
	s_add_u32 s22, s82, 0x20080
	s_addc_u32 s23, s83, 0
	s_add_i32 s52, s53, s26
	v_lshl_add_u64 v[146:147], s[22:23], 0, v[134:135]
	s_mov_b32 m0, s52
	s_nop 0
	global_load_lds_dwordx4 v[146:147], off
	v_lshl_add_u64 v[146:147], s[22:23], 0, v[130:131]
	s_add_i32 m0, s52, 0x2000
	s_nop 0
	global_load_lds_dwordx4 v[146:147], off
	v_add_u32_e32 v145, 0x10000, v142
	ds_read_b128 v[146:149], v145
	ds_read_b128 v[150:153], v145 offset:1024
	ds_read_b128 v[154:157], v145 offset:2048
	ds_read_b128 v[158:161], v145 offset:3072
	s_waitcnt vmcnt(6)
	s_barrier
	v_mfma_f32_16x16x32_bf16 v[46:49], v[208:211], v[162:165], v[46:49]
	v_mfma_f32_16x16x32_bf16 v[42:45], v[228:231], v[162:165], v[42:45]
	v_mfma_f32_16x16x32_bf16 v[30:33], v[208:211], v[170:173], v[30:33]
	v_mfma_f32_16x16x32_bf16 v[26:29], v[228:231], v[170:173], v[26:29]
	v_mfma_f32_16x16x32_bf16 v[14:17], v[208:211], v[192:195], v[14:17]
	v_mfma_f32_16x16x32_bf16 v[10:13], v[228:231], v[192:195], v[10:13]
	v_mfma_f32_16x16x32_bf16 v[6:9], v[208:211], v[200:203], v[6:9]
	v_mfma_f32_16x16x32_bf16 v[2:5], v[228:231], v[200:203], v[2:5]
	v_mfma_f32_16x16x32_bf16 v[46:49], v[224:227], v[166:169], v[46:49]
	v_mfma_f32_16x16x32_bf16 v[42:45], v[232:235], v[166:169], v[42:45]
	v_mfma_f32_16x16x32_bf16 v[30:33], v[224:227], v[174:177], v[30:33]
	v_mfma_f32_16x16x32_bf16 v[26:29], v[232:235], v[174:177], v[26:29]
	v_mfma_f32_16x16x32_bf16 v[14:17], v[224:227], v[196:199], v[14:17]
	v_mfma_f32_16x16x32_bf16 v[10:13], v[232:235], v[196:199], v[10:13]
	v_mfma_f32_16x16x32_bf16 v[6:9], v[224:227], v[204:207], v[6:9]
	v_mfma_f32_16x16x32_bf16 v[2:5], v[232:235], v[204:207], v[2:5]
	s_add_i32 s51, s51, 2
	s_add_u32 s20, s20, 0x100
	s_addc_u32 s21, s21, 0
	s_add_u32 s49, s49, 0x100
	s_addc_u32 s50, s50, 0
	s_cmp_gt_u32 s51, 5
	s_barrier
	s_cbranch_scc0 .LBB0_373
	s_waitcnt lgkmcnt(0)
	v_lshl_add_u32 v146, s46, 8, v1
	v_lshl_or_b32 v148, s45, 8, v143
	v_ashrrev_i32_e32 v147, 31, v146
	v_readlane_b32 s48, v254, 40
	v_ashrrev_i32_e32 v149, 31, v148
	v_lshlrev_b64 v[150:151], 14, v[146:147]
	v_readlane_b32 s62, v254, 54
	v_readlane_b32 s63, v254, 55
	v_lshlrev_b64 v[148:149], 1, v[148:149]
	s_mov_b32 s19, 0x200000
	v_lshl_add_u64 v[150:151], s[62:63], 0, v[150:151]
	v_lshl_add_u64 v[150:151], v[150:151], 0, v[148:149]
	s_mov_b64 s[20:21], 0x200000
	v_cvt_pk_bf16_f32 v62, v62, v63
	v_cvt_pk_bf16_f32 v63, v64, v65
	v_cvt_pk_bf16_f32 v64, v58, v59
	v_add_co_u32_e32 v58, vcc, s19, v150
	v_cvt_pk_bf16_f32 v70, v70, v71
	v_cvt_pk_bf16_f32 v71, v72, v73
	v_cvt_pk_bf16_f32 v72, v66, v67
	v_lshl_add_u64 v[66:67], v[150:151], 0, s[20:21]
	v_addc_co_u32_e32 v59, vcc, 0, v151, vcc
	v_cvt_pk_bf16_f32 v46, v46, v47
	v_cvt_pk_bf16_f32 v47, v48, v49
	v_cvt_pk_bf16_f32 v48, v42, v43
	v_cvt_pk_bf16_f32 v49, v44, v45
	s_mov_b32 s19, 0x240000
	v_cvt_pk_bf16_f32 v110, v110, v111
	v_cvt_pk_bf16_f32 v111, v112, v113
	v_cvt_pk_bf16_f32 v112, v106, v107
	v_or_b32_e32 v106, 16, v146
	global_store_dwordx4 v[66:67], v[46:49], off offset:256
	s_mov_b64 s[20:21], 0x240000
	v_ashrrev_i32_e32 v107, 31, v106
	v_add_co_u32_e32 v48, vcc, s19, v150
	v_cvt_pk_bf16_f32 v94, v94, v95
	v_cvt_pk_bf16_f32 v95, v96, v97
	v_cvt_pk_bf16_f32 v96, v90, v91
	v_or_b32_e32 v90, 32, v146
	v_lshl_add_u64 v[46:47], v[150:151], 0, s[20:21]
	v_addc_co_u32_e32 v49, vcc, 0, v151, vcc
	v_cvt_pk_bf16_f32 v30, v30, v31
	v_cvt_pk_bf16_f32 v31, v32, v33
	v_cvt_pk_bf16_f32 v32, v26, v27
	v_cvt_pk_bf16_f32 v33, v28, v29
	s_mov_b32 s19, 0x280000
	v_lshlrev_b64 v[106:107], 14, v[106:107]
	v_ashrrev_i32_e32 v91, 31, v90
	v_cvt_pk_bf16_f32 v78, v78, v79
	v_cvt_pk_bf16_f32 v79, v80, v81
	v_cvt_pk_bf16_f32 v80, v74, v75
	v_or_b32_e32 v74, 48, v146
	global_store_dwordx4 v[46:47], v[30:33], off offset:256
	s_mov_b64 s[20:21], 0x280000
	v_cvt_pk_bf16_f32 v113, v108, v109
	v_add_co_u32_e32 v32, vcc, s19, v150
	v_lshl_add_u64 v[106:107], s[62:63], 0, v[106:107]
	v_lshlrev_b64 v[90:91], 14, v[90:91]
	v_ashrrev_i32_e32 v75, 31, v74
	v_lshl_add_u64 v[30:31], v[150:151], 0, s[20:21]
	v_addc_co_u32_e32 v33, vcc, 0, v151, vcc
	v_cvt_pk_bf16_f32 v14, v14, v15
	v_cvt_pk_bf16_f32 v15, v16, v17
	v_cvt_pk_bf16_f32 v16, v10, v11
	v_cvt_pk_bf16_f32 v17, v12, v13
	s_mov_b32 s19, 0x2c0000
	global_store_dwordx4 v[150:151], v[110:113], off offset:256
	v_cvt_pk_bf16_f32 v97, v92, v93
	v_lshl_add_u64 v[90:91], s[62:63], 0, v[90:91]
	v_lshl_add_u64 v[110:111], v[106:107], 0, v[148:149]
	v_lshlrev_b64 v[74:75], 14, v[74:75]
	global_store_dwordx4 v[30:31], v[14:17], off offset:256
	global_store_dwordx4 v[110:111], v[94:97], off offset:256
	v_cvt_pk_bf16_f32 v81, v76, v77
	v_add_co_u32_e32 v16, vcc, s19, v150
	v_lshl_add_u64 v[94:95], v[90:91], 0, v[148:149]
	v_lshl_add_u64 v[74:75], s[62:63], 0, v[74:75]
	s_mov_b64 s[20:21], 0x2c0000
	v_addc_co_u32_e32 v17, vcc, 0, v151, vcc
	v_cvt_pk_bf16_f32 v126, v126, v127
	v_cvt_pk_bf16_f32 v127, v128, v129
	v_cvt_pk_bf16_f32 v128, v122, v123
	v_cvt_pk_bf16_f32 v129, v124, v125
	v_cvt_pk_bf16_f32 v106, v118, v119
	v_cvt_pk_bf16_f32 v107, v120, v121
	v_cvt_pk_bf16_f32 v108, v114, v115
	v_cvt_pk_bf16_f32 v109, v116, v117
	v_cvt_pk_bf16_f32 v90, v102, v103
	v_cvt_pk_bf16_f32 v91, v104, v105
	v_cvt_pk_bf16_f32 v92, v98, v99
	v_cvt_pk_bf16_f32 v93, v100, v101
	global_store_dwordx4 v[94:95], v[78:81], off offset:256
	v_cvt_pk_bf16_f32 v76, v82, v83
	v_cvt_pk_bf16_f32 v77, v84, v85
	v_lshl_add_u64 v[78:79], v[74:75], 0, v[148:149]
	v_cvt_pk_bf16_f32 v74, v86, v87
	v_cvt_pk_bf16_f32 v75, v88, v89
	v_cvt_pk_bf16_f32 v73, v68, v69
	v_cvt_pk_bf16_f32 v65, v60, v61
	v_cvt_pk_bf16_f32 v42, v54, v55
	v_cvt_pk_bf16_f32 v43, v56, v57
	v_cvt_pk_bf16_f32 v44, v50, v51
	v_cvt_pk_bf16_f32 v45, v52, v53
	v_cvt_pk_bf16_f32 v26, v38, v39
	v_cvt_pk_bf16_f32 v27, v40, v41
	v_cvt_pk_bf16_f32 v28, v34, v35
	v_cvt_pk_bf16_f32 v29, v36, v37
	v_lshl_add_u64 v[14:15], v[150:151], 0, s[20:21]
	v_cvt_pk_bf16_f32 v10, v22, v23
	v_cvt_pk_bf16_f32 v11, v24, v25
	v_cvt_pk_bf16_f32 v12, v18, v19
	v_cvt_pk_bf16_f32 v13, v20, v21
	v_cvt_pk_bf16_f32 v6, v6, v7
	v_cvt_pk_bf16_f32 v7, v8, v9
	v_cvt_pk_bf16_f32 v8, v2, v3
	v_cvt_pk_bf16_f32 v9, v4, v5
	s_and_b64 vcc, exec, s[0:1]
	s_mov_b32 s45, s18
	s_mov_b32 s46, s30
	s_mov_b64 s[22:23], s[80:81]
	s_mov_b64 s[20:21], s[38:39]
	s_mov_b32 s64, 0x800000
	s_movk_i32 s65, 0x1fff
	v_readlane_b32 s49, v254, 41
	v_readlane_b32 s50, v254, 42
	v_readlane_b32 s51, v254, 43
	v_readlane_b32 s52, v254, 44
	v_readlane_b32 s53, v254, 45
	v_readlane_b32 s54, v254, 46
	v_readlane_b32 s55, v254, 47
	v_readlane_b32 s56, v254, 48
	v_readlane_b32 s57, v254, 49
	v_readlane_b32 s58, v254, 50
	v_readlane_b32 s59, v254, 51
	v_readlane_b32 s60, v254, 52
	v_readlane_b32 s61, v254, 53
	global_store_dwordx4 v[150:151], v[126:129], off
	global_store_dwordx4 v[110:111], v[106:109], off
	global_store_dwordx4 v[94:95], v[90:93], off
	global_store_dwordx4 v[78:79], v[74:77], off
	global_store_dwordx4 v[78:79], v[70:73], off offset:256
	global_store_dwordx4 v[58:59], v[62:65], off
	global_store_dwordx4 v[48:49], v[42:45], off
	global_store_dwordx4 v[32:33], v[26:29], off
	global_store_dwordx4 v[16:17], v[10:13], off
	global_store_dwordx4 v[14:15], v[6:9], off offset:256
	s_cbranch_vccz .LBB0_366
	s_waitcnt vmcnt(0)
	v_readlane_b32 s44, v255, 30
	s_mov_b32 s66, s90
	s_cmpk_gt_u32 s25, 0xff
	v_readlane_b32 s45, v255, 31
	v_readlane_b32 s42, v255, 32
	s_cbranch_scc1 .LBB0_377
	s_barrier

.LBB0_386:
	s_add_u32 s20, s18, 0xfffe0080
	s_addc_u32 s21, s19, -1
	s_add_i32 s50, 0, 0x10000
	s_cmp_eq_u32 s49, 4
	s_cselect_b32 s23, s44, s21
	s_cselect_b32 s22, s45, s20
	s_cselect_b32 s21, s39, s48
	s_cselect_b32 s20, s46, s47
	v_lshl_add_u64 v[178:179], s[18:19], 0, v[146:147]
	s_add_i32 m0, s90, 0xc000
	ds_read_b128 v[162:165], v156
	ds_read_b128 v[166:169], v156 offset:1024
	ds_read_b128 v[170:173], v156 offset:2048
	ds_read_b128 v[174:177], v156 offset:3072
	ds_read_b128 v[192:195], v156 offset:4096
	ds_read_b128 v[196:199], v156 offset:5120
	ds_read_b128 v[200:203], v156 offset:6144
	ds_read_b128 v[204:207], v156 offset:7168
	global_load_lds_dwordx4 v[178:179], off
	v_lshl_add_u64 v[178:179], s[18:19], 0, v[148:149]
	s_add_i32 m0, s90, 0xe000
	s_nop 0
	global_load_lds_dwordx4 v[178:179], off
	s_waitcnt lgkmcnt(8)
	s_barrier
	s_waitcnt lgkmcnt(0)
	s_waitcnt lgkmcnt(0)
	v_mfma_f32_16x16x32_bf16 v[126:129], v[130:133], v[162:165], v[126:129]
	v_mfma_f32_16x16x32_bf16 v[122:125], v[150:153], v[162:165], v[122:125]
	v_mfma_f32_16x16x32_bf16 v[118:121], v[130:133], v[170:173], v[118:121]
	v_mfma_f32_16x16x32_bf16 v[110:113], v[150:153], v[170:173], v[110:113]
	v_mfma_f32_16x16x32_bf16 v[102:105], v[130:133], v[192:195], v[102:105]
	v_mfma_f32_16x16x32_bf16 v[94:97], v[150:153], v[192:195], v[94:97]
	v_mfma_f32_16x16x32_bf16 v[86:89], v[130:133], v[200:203], v[86:89]
	v_mfma_f32_16x16x32_bf16 v[78:81], v[150:153], v[200:203], v[78:81]
	v_mfma_f32_16x16x32_bf16 v[126:129], v[134:137], v[166:169], v[126:129]
	v_mfma_f32_16x16x32_bf16 v[122:125], v[158:161], v[166:169], v[122:125]
	v_mfma_f32_16x16x32_bf16 v[118:121], v[134:137], v[174:177], v[118:121]
	v_mfma_f32_16x16x32_bf16 v[110:113], v[158:161], v[174:177], v[110:113]
	v_mfma_f32_16x16x32_bf16 v[102:105], v[134:137], v[196:199], v[102:105]
	v_mfma_f32_16x16x32_bf16 v[94:97], v[158:161], v[196:199], v[94:97]
	v_mfma_f32_16x16x32_bf16 v[86:89], v[134:137], v[204:207], v[86:89]
	v_mfma_f32_16x16x32_bf16 v[78:81], v[158:161], v[204:207], v[78:81]
	s_barrier
	s_add_i32 s52, 0, 0x14000
	s_add_i32 s50, s50, s36
	v_add_u32_e32 v157, s52, v154
	v_lshl_add_u64 v[178:179], s[20:21], 0, v[142:143]
	s_mov_b32 m0, s50
	ds_read_b128 v[208:211], v157
	ds_read_b128 v[224:227], v157 offset:1024
	ds_read_b128 v[228:231], v157 offset:2048
	ds_read_b128 v[232:235], v157 offset:3072
	global_load_lds_dwordx4 v[178:179], off
	v_lshl_add_u64 v[212:213], s[20:21], 0, v[138:139]
	s_add_i32 m0, s50, 0x2000
	s_nop 0
	global_load_lds_dwordx4 v[212:213], off
	s_barrier
	s_waitcnt lgkmcnt(0)
	s_waitcnt lgkmcnt(0)
	v_mfma_f32_16x16x32_bf16 v[114:117], v[208:211], v[162:165], v[114:117]
	v_mfma_f32_16x16x32_bf16 v[106:109], v[228:231], v[162:165], v[106:109]
	v_mfma_f32_16x16x32_bf16 v[98:101], v[208:211], v[170:173], v[98:101]
	v_mfma_f32_16x16x32_bf16 v[90:93], v[228:231], v[170:173], v[90:93]
	v_mfma_f32_16x16x32_bf16 v[82:85], v[208:211], v[192:195], v[82:85]
	v_mfma_f32_16x16x32_bf16 v[74:77], v[228:231], v[192:195], v[74:77]
	v_mfma_f32_16x16x32_bf16 v[70:73], v[208:211], v[200:203], v[70:73]
	v_mfma_f32_16x16x32_bf16 v[66:69], v[228:231], v[200:203], v[66:69]
	v_mfma_f32_16x16x32_bf16 v[114:117], v[224:227], v[166:169], v[114:117]
	v_mfma_f32_16x16x32_bf16 v[106:109], v[232:235], v[166:169], v[106:109]
	v_mfma_f32_16x16x32_bf16 v[98:101], v[224:227], v[174:177], v[98:101]
	v_mfma_f32_16x16x32_bf16 v[90:93], v[232:235], v[174:177], v[90:93]
	v_mfma_f32_16x16x32_bf16 v[82:85], v[224:227], v[196:199], v[82:85]
	v_mfma_f32_16x16x32_bf16 v[74:77], v[232:235], v[196:199], v[74:77]
	v_mfma_f32_16x16x32_bf16 v[70:73], v[224:227], v[204:207], v[70:73]
	v_mfma_f32_16x16x32_bf16 v[66:69], v[232:235], v[204:207], v[66:69]
	s_mov_b32 m0, s90
	v_lshl_add_u64 v[236:237], s[22:23], 0, v[144:145]
	s_barrier
	ds_read_b128 v[162:165], v156 offset:16384
	ds_read_b128 v[166:169], v156 offset:17408
	ds_read_b128 v[170:173], v156 offset:18432
	ds_read_b128 v[174:177], v156 offset:19456
	ds_read_b128 v[192:195], v156 offset:20480
	ds_read_b128 v[196:199], v156 offset:21504
	ds_read_b128 v[200:203], v156 offset:22528
	ds_read_b128 v[204:207], v156 offset:23552
	global_load_lds_dwordx4 v[236:237], off
	v_lshl_add_u64 v[238:239], s[22:23], 0, v[140:141]
	s_mov_b32 m0, s91
	s_nop 0
	global_load_lds_dwordx4 v[238:239], off
	s_waitcnt vmcnt(10)
	s_barrier
	s_waitcnt lgkmcnt(0)
	s_waitcnt lgkmcnt(0)
	v_mfma_f32_16x16x32_bf16 v[62:65], v[130:133], v[162:165], v[62:65]
	v_mfma_f32_16x16x32_bf16 v[58:61], v[150:153], v[162:165], v[58:61]
	v_mfma_f32_16x16x32_bf16 v[54:57], v[130:133], v[170:173], v[54:57]
	v_mfma_f32_16x16x32_bf16 v[46:49], v[150:153], v[170:173], v[46:49]
	v_mfma_f32_16x16x32_bf16 v[38:41], v[130:133], v[192:195], v[38:41]
	v_mfma_f32_16x16x32_bf16 v[30:33], v[150:153], v[192:195], v[30:33]
	v_mfma_f32_16x16x32_bf16 v[22:25], v[130:133], v[200:203], v[22:25]
	v_mfma_f32_16x16x32_bf16 v[14:17], v[150:153], v[200:203], v[14:17]
	v_mfma_f32_16x16x32_bf16 v[62:65], v[134:137], v[166:169], v[62:65]
	v_mfma_f32_16x16x32_bf16 v[58:61], v[158:161], v[166:169], v[58:61]
	v_mfma_f32_16x16x32_bf16 v[54:57], v[134:137], v[174:177], v[54:57]
	v_mfma_f32_16x16x32_bf16 v[46:49], v[158:161], v[174:177], v[46:49]
	v_mfma_f32_16x16x32_bf16 v[38:41], v[134:137], v[196:199], v[38:41]
	v_mfma_f32_16x16x32_bf16 v[30:33], v[158:161], v[196:199], v[30:33]
	v_mfma_f32_16x16x32_bf16 v[22:25], v[134:137], v[204:207], v[22:25]
	v_mfma_f32_16x16x32_bf16 v[14:17], v[158:161], v[204:207], v[14:17]
	s_barrier
	s_add_u32 s50, s20, 0x20000
	s_addc_u32 s51, s21, 0
	s_add_i32 s52, s52, s36
	v_lshl_add_u64 v[130:131], s[50:51], 0, v[142:143]
	s_mov_b32 m0, s52
	s_nop 0
	global_load_lds_dwordx4 v[130:131], off
	v_lshl_add_u64 v[130:131], s[50:51], 0, v[138:139]
	s_add_i32 m0, s52, 0x2000
	s_nop 0
	global_load_lds_dwordx4 v[130:131], off
	v_add_u32_e32 v157, 0x18000, v154
	ds_read_b128 v[130:133], v157
	ds_read_b128 v[134:137], v157 offset:1024
	ds_read_b128 v[150:153], v157 offset:2048
	ds_read_b128 v[158:161], v157 offset:3072
	s_waitcnt vmcnt(6)
	s_barrier
	v_mfma_f32_16x16x32_bf16 v[50:53], v[208:211], v[162:165], v[50:53]
	v_mfma_f32_16x16x32_bf16 v[42:45], v[228:231], v[162:165], v[42:45]
	v_mfma_f32_16x16x32_bf16 v[34:37], v[208:211], v[170:173], v[34:37]
	v_mfma_f32_16x16x32_bf16 v[26:29], v[228:231], v[170:173], v[26:29]
	v_mfma_f32_16x16x32_bf16 v[18:21], v[208:211], v[192:195], v[18:21]
	v_mfma_f32_16x16x32_bf16 v[10:13], v[228:231], v[192:195], v[10:13]
	v_mfma_f32_16x16x32_bf16 v[6:9], v[208:211], v[200:203], v[6:9]
	v_mfma_f32_16x16x32_bf16 v[2:5], v[228:231], v[200:203], v[2:5]
	v_mfma_f32_16x16x32_bf16 v[50:53], v[224:227], v[166:169], v[50:53]
	v_mfma_f32_16x16x32_bf16 v[42:45], v[232:235], v[166:169], v[42:45]
	v_mfma_f32_16x16x32_bf16 v[34:37], v[224:227], v[174:177], v[34:37]
	v_mfma_f32_16x16x32_bf16 v[26:29], v[232:235], v[174:177], v[26:29]
	v_mfma_f32_16x16x32_bf16 v[18:21], v[224:227], v[196:199], v[18:21]
	v_mfma_f32_16x16x32_bf16 v[10:13], v[232:235], v[196:199], v[10:13]
	v_mfma_f32_16x16x32_bf16 v[6:9], v[224:227], v[204:207], v[6:9]
	v_mfma_f32_16x16x32_bf16 v[2:5], v[232:235], v[204:207], v[2:5]
	s_add_i32 s50, 0, 0x18000
	s_barrier
	s_add_u32 s22, s22, 0x20000
	s_addc_u32 s23, s23, 0
	s_mov_b32 m0, s42
	v_lshl_add_u64 v[208:209], s[22:23], 0, v[144:145]
	ds_read_b128 v[162:165], v156 offset:32768
	ds_read_b128 v[166:169], v156 offset:33792
	ds_read_b128 v[170:173], v156 offset:34816
	ds_read_b128 v[174:177], v156 offset:35840
	ds_read_b128 v[192:195], v156 offset:36864
	ds_read_b128 v[196:199], v156 offset:37888
	ds_read_b128 v[200:203], v156 offset:38912
	ds_read_b128 v[204:207], v156 offset:39936
	global_load_lds_dwordx4 v[208:209], off
	v_lshl_add_u64 v[208:209], s[22:23], 0, v[140:141]
	s_mov_b32 m0, s43
	s_nop 0
	global_load_lds_dwordx4 v[208:209], off
	s_waitcnt lgkmcnt(8)
	s_barrier
	s_waitcnt lgkmcnt(0)
	s_waitcnt lgkmcnt(0)
	v_mfma_f32_16x16x32_bf16 v[126:129], v[130:133], v[162:165], v[126:129]
	v_mfma_f32_16x16x32_bf16 v[122:125], v[150:153], v[162:165], v[122:125]
	v_mfma_f32_16x16x32_bf16 v[118:121], v[130:133], v[170:173], v[118:121]
	v_mfma_f32_16x16x32_bf16 v[110:113], v[150:153], v[170:173], v[110:113]
	v_mfma_f32_16x16x32_bf16 v[102:105], v[130:133], v[192:195], v[102:105]
	v_mfma_f32_16x16x32_bf16 v[94:97], v[150:153], v[192:195], v[94:97]
	v_mfma_f32_16x16x32_bf16 v[86:89], v[130:133], v[200:203], v[86:89]
	v_mfma_f32_16x16x32_bf16 v[78:81], v[150:153], v[200:203], v[78:81]
	v_mfma_f32_16x16x32_bf16 v[126:129], v[134:137], v[166:169], v[126:129]
	v_mfma_f32_16x16x32_bf16 v[122:125], v[158:161], v[166:169], v[122:125]
	v_mfma_f32_16x16x32_bf16 v[118:121], v[134:137], v[174:177], v[118:121]
	v_mfma_f32_16x16x32_bf16 v[110:113], v[158:161], v[174:177], v[110:113]
	v_mfma_f32_16x16x32_bf16 v[102:105], v[134:137], v[196:199], v[102:105]
	v_mfma_f32_16x16x32_bf16 v[94:97], v[158:161], v[196:199], v[94:97]
	v_mfma_f32_16x16x32_bf16 v[86:89], v[134:137], v[204:207], v[86:89]
	v_mfma_f32_16x16x32_bf16 v[78:81], v[158:161], v[204:207], v[78:81]
	s_barrier
	s_add_i32 s22, 0, 0x1c000
	s_add_i32 s23, s50, s36
	v_add_u32_e32 v157, s22, v154
	v_lshl_add_u64 v[178:179], v[178:179], 0, s[78:79]
	s_mov_b32 m0, s23
	ds_read_b128 v[208:211], v157
	ds_read_b128 v[224:227], v157 offset:1024
	ds_read_b128 v[228:231], v157 offset:2048
	ds_read_b128 v[232:235], v157 offset:3072
	global_load_lds_dwordx4 v[178:179], off
	v_lshl_add_u64 v[178:179], v[212:213], 0, s[78:79]
	s_add_i32 m0, s23, 0x2000
	s_nop 0
	global_load_lds_dwordx4 v[178:179], off
	s_barrier
	s_waitcnt lgkmcnt(0)
	s_waitcnt lgkmcnt(0)
	v_mfma_f32_16x16x32_bf16 v[114:117], v[208:211], v[162:165], v[114:117]
	v_mfma_f32_16x16x32_bf16 v[106:109], v[228:231], v[162:165], v[106:109]
	v_mfma_f32_16x16x32_bf16 v[98:101], v[208:211], v[170:173], v[98:101]
	v_mfma_f32_16x16x32_bf16 v[90:93], v[228:231], v[170:173], v[90:93]
	v_mfma_f32_16x16x32_bf16 v[82:85], v[208:211], v[192:195], v[82:85]
	v_mfma_f32_16x16x32_bf16 v[74:77], v[228:231], v[192:195], v[74:77]
	v_mfma_f32_16x16x32_bf16 v[70:73], v[208:211], v[200:203], v[70:73]
	v_mfma_f32_16x16x32_bf16 v[66:69], v[228:231], v[200:203], v[66:69]
	v_mfma_f32_16x16x32_bf16 v[114:117], v[224:227], v[166:169], v[114:117]
	v_mfma_f32_16x16x32_bf16 v[106:109], v[232:235], v[166:169], v[106:109]
	v_mfma_f32_16x16x32_bf16 v[98:101], v[224:227], v[174:177], v[98:101]
	v_mfma_f32_16x16x32_bf16 v[90:93], v[232:235], v[174:177], v[90:93]
	v_mfma_f32_16x16x32_bf16 v[82:85], v[224:227], v[196:199], v[82:85]
	v_mfma_f32_16x16x32_bf16 v[74:77], v[232:235], v[196:199], v[74:77]
	v_mfma_f32_16x16x32_bf16 v[70:73], v[224:227], v[204:207], v[70:73]
	v_mfma_f32_16x16x32_bf16 v[66:69], v[232:235], v[204:207], v[66:69]
	s_mov_b32 m0, s25
	v_lshl_add_u64 v[178:179], v[236:237], 0, s[78:79]
	s_barrier
	ds_read_b128 v[162:165], v156 offset:49152
	ds_read_b128 v[166:169], v156 offset:50176
	ds_read_b128 v[170:173], v156 offset:51200
	ds_read_b128 v[174:177], v156 offset:52224
	ds_read_b128 v[192:195], v156 offset:53248
	ds_read_b128 v[196:199], v156 offset:54272
	ds_read_b128 v[200:203], v156 offset:55296
	ds_read_b128 v[204:207], v156 offset:56320
	global_load_lds_dwordx4 v[178:179], off
	v_lshl_add_u64 v[178:179], v[238:239], 0, s[78:79]
	s_mov_b32 m0, s26
	s_nop 0
	global_load_lds_dwordx4 v[178:179], off
	s_waitcnt vmcnt(10)
	s_barrier
	s_waitcnt lgkmcnt(0)
	s_waitcnt lgkmcnt(0)
	v_mfma_f32_16x16x32_bf16 v[62:65], v[130:133], v[162:165], v[62:65]
	v_mfma_f32_16x16x32_bf16 v[58:61], v[150:153], v[162:165], v[58:61]
	v_mfma_f32_16x16x32_bf16 v[54:57], v[130:133], v[170:173], v[54:57]
	v_mfma_f32_16x16x32_bf16 v[46:49], v[150:153], v[170:173], v[46:49]
	v_mfma_f32_16x16x32_bf16 v[38:41], v[130:133], v[192:195], v[38:41]
	v_mfma_f32_16x16x32_bf16 v[30:33], v[150:153], v[192:195], v[30:33]
	v_mfma_f32_16x16x32_bf16 v[22:25], v[130:133], v[200:203], v[22:25]
	v_mfma_f32_16x16x32_bf16 v[14:17], v[150:153], v[200:203], v[14:17]
	v_mfma_f32_16x16x32_bf16 v[62:65], v[134:137], v[166:169], v[62:65]
	v_mfma_f32_16x16x32_bf16 v[58:61], v[158:161], v[166:169], v[58:61]
	v_mfma_f32_16x16x32_bf16 v[54:57], v[134:137], v[174:177], v[54:57]
	v_mfma_f32_16x16x32_bf16 v[46:49], v[158:161], v[174:177], v[46:49]
	v_mfma_f32_16x16x32_bf16 v[38:41], v[134:137], v[196:199], v[38:41]
	v_mfma_f32_16x16x32_bf16 v[30:33], v[158:161], v[196:199], v[30:33]
	v_mfma_f32_16x16x32_bf16 v[22:25], v[134:137], v[204:207], v[22:25]
	v_mfma_f32_16x16x32_bf16 v[14:17], v[158:161], v[204:207], v[14:17]
	s_barrier
	s_add_u32 s20, s20, 0x20080
	s_addc_u32 s21, s21, 0
	s_add_i32 s22, s22, s36
	v_lshl_add_u64 v[130:131], s[20:21], 0, v[142:143]
	s_mov_b32 m0, s22
	s_nop 0
	global_load_lds_dwordx4 v[130:131], off
	v_lshl_add_u64 v[130:131], s[20:21], 0, v[138:139]
	s_add_i32 m0, s22, 0x2000
	s_nop 0
	global_load_lds_dwordx4 v[130:131], off
	v_add_u32_e32 v157, 0x10000, v154
	ds_read_b128 v[130:133], v157
	ds_read_b128 v[134:137], v157 offset:1024
	ds_read_b128 v[150:153], v157 offset:2048
	ds_read_b128 v[158:161], v157 offset:3072
	s_waitcnt vmcnt(6)
	s_barrier
	v_mfma_f32_16x16x32_bf16 v[50:53], v[208:211], v[162:165], v[50:53]
	v_mfma_f32_16x16x32_bf16 v[42:45], v[228:231], v[162:165], v[42:45]
	v_mfma_f32_16x16x32_bf16 v[34:37], v[208:211], v[170:173], v[34:37]
	v_mfma_f32_16x16x32_bf16 v[26:29], v[228:231], v[170:173], v[26:29]
	v_mfma_f32_16x16x32_bf16 v[18:21], v[208:211], v[192:195], v[18:21]
	v_mfma_f32_16x16x32_bf16 v[10:13], v[228:231], v[192:195], v[10:13]
	v_mfma_f32_16x16x32_bf16 v[6:9], v[208:211], v[200:203], v[6:9]
	v_mfma_f32_16x16x32_bf16 v[2:5], v[228:231], v[200:203], v[2:5]
	v_mfma_f32_16x16x32_bf16 v[50:53], v[224:227], v[166:169], v[50:53]
	v_mfma_f32_16x16x32_bf16 v[42:45], v[232:235], v[166:169], v[42:45]
	v_mfma_f32_16x16x32_bf16 v[34:37], v[224:227], v[174:177], v[34:37]
	v_mfma_f32_16x16x32_bf16 v[26:29], v[232:235], v[174:177], v[26:29]
	v_mfma_f32_16x16x32_bf16 v[18:21], v[224:227], v[196:199], v[18:21]
	v_mfma_f32_16x16x32_bf16 v[10:13], v[232:235], v[196:199], v[10:13]
	v_mfma_f32_16x16x32_bf16 v[6:9], v[224:227], v[204:207], v[6:9]
	v_mfma_f32_16x16x32_bf16 v[2:5], v[232:235], v[204:207], v[2:5]
	s_add_i32 s49, s49, 2
	s_add_u32 s18, s18, 0x100
	s_addc_u32 s19, s19, 0
	s_add_u32 s47, s47, 0x100
	s_addc_u32 s48, s48, 0
	s_cmp_gt_u32 s49, 5
	s_barrier
	s_cbranch_scc0 .LBB0_386
	s_waitcnt lgkmcnt(0)
	v_lshl_add_u32 v164, s29, 8, v1
	v_lshl_or_b32 v150, s28, 8, v155
	s_mov_b64 s[18:19], -1
	s_cmp_lt_i32 s28, 8
	v_or_b32_e32 v163, 16, v164
	v_or_b32_e32 v162, 32, v164
	v_or_b32_e32 v161, 48, v164
	v_add_u32_e32 v160, 0x80, v164
	v_add_u32_e32 v159, 0x90, v164
	v_add_u32_e32 v158, 0xa0, v164
	v_add_u32_e32 v157, 0xb0, v164
	s_cbranch_scc1 .LBB0_389
	v_lshlrev_b32_e32 v130, 7, v164
	v_readlane_b32 s4, v255, 4
	v_and_b32_e32 v132, 0x3e780, v130
	v_mov_b32_e32 v133, v0
	v_readlane_b32 s5, v255, 5
	v_readlane_b32 s6, v255, 6
	v_readlane_b32 s7, v255, 7
	v_lshlrev_b32_e32 v130, 1, v150
	v_lshl_add_u64 v[134:135], s[4:5], 0, v[132:133]
	v_and_b32_e32 v130, 0x70, v130
	v_mov_b32_e32 v131, v0
	v_lshl_add_u64 v[132:133], s[6:7], 0, v[132:133]
	v_lshl_add_u64 v[152:153], v[132:133], 0, v[130:131]
	v_lshl_add_u64 v[136:137], v[134:135], 0, v[130:131]
	global_load_dwordx4 v[170:173], v[152:153], off
	global_load_dwordx4 v[166:169], v[136:137], off
	v_readlane_b32 s8, v255, 8
	v_readlane_b32 s9, v255, 9
	v_mov_b32_e32 v151, v0
	v_lshlrev_b64 v[134:135], 1, v[150:151]
	v_mov_b64_e32 v[132:133], s[8:9]
	v_mad_i64_i32 v[174:175], s[18:19], v164, s24, v[132:133]
	v_lshl_add_u64 v[174:175], v[174:175], 0, v[134:135]
	v_readlane_b32 s10, v255, 10
	v_readlane_b32 s11, v255, 11
	s_waitcnt vmcnt(0)
	v_pk_mul_f32 v[172:173], v[172:173], s[86:87] op_sel_hi:[1,0]
	v_pk_mul_f32 v[170:171], v[170:171], s[86:87] op_sel_hi:[1,0]
	v_pk_mul_f32 v[168:169], v[168:169], s[86:87] op_sel_hi:[1,0]
	v_pk_mul_f32 v[166:167], v[166:167], s[86:87] op_sel_hi:[1,0]
	v_pk_mul_f32 v[176:177], v[124:125], v[172:173]
	v_pk_mul_f32 v[178:179], v[122:123], v[170:171]
	v_pk_mul_f32 v[172:173], v[128:129], v[172:173]
	v_pk_mul_f32 v[170:171], v[126:127], v[170:171]
	v_pk_fma_f32 v[176:177], v[128:129], v[168:169], v[176:177] neg_lo:[0,0,1] neg_hi:[0,0,1]
	v_pk_fma_f32 v[178:179], v[126:127], v[166:167], v[178:179] neg_lo:[0,0,1] neg_hi:[0,0,1]
	v_pk_fma_f32 v[172:173], v[124:125], v[168:169], v[172:173]
	v_pk_fma_f32 v[168:169], v[122:123], v[166:167], v[170:171]
	v_cvt_pk_bf16_f32 v166, v178, v179
	v_cvt_pk_bf16_f32 v167, v176, v177
	v_cvt_pk_bf16_f32 v168, v168, v169
	v_cvt_pk_bf16_f32 v169, v172, v173
	global_store_dwordx4 v[174:175], v[166:169], off
	global_load_dwordx4 v[166:169], v[136:137], off
	s_nop 0
	global_load_dwordx4 v[170:173], v[152:153], off
	v_lshlrev_b32_e32 v136, 7, v163
	v_mov_b32_e32 v137, v0
	v_and_b32_e32 v136, 0x3ef80, v136
	v_lshl_add_u64 v[152:153], s[4:5], 0, v[136:137]
	v_lshl_add_u64 v[136:137], s[6:7], 0, v[136:137]
	v_lshl_add_u64 v[136:137], v[136:137], 0, v[130:131]
	v_lshl_add_u64 v[152:153], v[152:153], 0, v[130:131]
	s_waitcnt vmcnt(0)
	v_pk_mul_f32 v[168:169], v[168:169], s[86:87] op_sel_hi:[1,0]
	v_pk_mul_f32 v[172:173], v[172:173], s[86:87] op_sel_hi:[1,0]
	v_pk_mul_f32 v[170:171], v[170:171], s[86:87] op_sel_hi:[1,0]
	v_pk_mul_f32 v[166:167], v[166:167], s[86:87] op_sel_hi:[1,0]
	v_pk_mul_f32 v[176:177], v[108:109], v[172:173]
	v_pk_mul_f32 v[178:179], v[106:107], v[170:171]
	v_pk_mul_f32 v[172:173], v[116:117], v[172:173]
	v_pk_mul_f32 v[170:171], v[114:115], v[170:171]
	v_pk_fma_f32 v[176:177], v[116:117], v[168:169], v[176:177] neg_lo:[0,0,1] neg_hi:[0,0,1]
	v_pk_fma_f32 v[178:179], v[114:115], v[166:167], v[178:179] neg_lo:[0,0,1] neg_hi:[0,0,1]
	v_pk_fma_f32 v[172:173], v[108:109], v[168:169], v[172:173]
	v_pk_fma_f32 v[168:169], v[106:107], v[166:167], v[170:171]
	v_cvt_pk_bf16_f32 v166, v178, v179
	v_cvt_pk_bf16_f32 v167, v176, v177
	v_cvt_pk_bf16_f32 v168, v168, v169
	v_cvt_pk_bf16_f32 v169, v172, v173
	global_store_dwordx4 v[174:175], v[166:169], off offset:256
	global_load_dwordx4 v[170:173], v[136:137], off
	v_mad_i64_i32 v[174:175], s[18:19], v163, s24, v[132:133]
	global_load_dwordx4 v[166:169], v[152:153], off
	v_lshl_add_u64 v[174:175], v[174:175], 0, v[134:135]
	s_waitcnt vmcnt(0)
	v_pk_mul_f32 v[172:173], v[172:173], s[86:87] op_sel_hi:[1,0]
	v_pk_mul_f32 v[170:171], v[170:171], s[86:87] op_sel_hi:[1,0]
	v_pk_mul_f32 v[176:177], v[112:113], v[172:173]
	v_pk_mul_f32 v[168:169], v[168:169], s[86:87] op_sel_hi:[1,0]
	v_pk_mul_f32 v[166:167], v[166:167], s[86:87] op_sel_hi:[1,0]
	v_pk_mul_f32 v[178:179], v[110:111], v[170:171]
	v_pk_mul_f32 v[172:173], v[120:121], v[172:173]
	v_pk_mul_f32 v[170:171], v[118:119], v[170:171]
	v_pk_fma_f32 v[176:177], v[120:121], v[168:169], v[176:177] neg_lo:[0,0,1] neg_hi:[0,0,1]
	v_pk_fma_f32 v[178:179], v[118:119], v[166:167], v[178:179] neg_lo:[0,0,1] neg_hi:[0,0,1]
	v_pk_fma_f32 v[172:173], v[112:113], v[168:169], v[172:173]
	v_pk_fma_f32 v[168:169], v[110:111], v[166:167], v[170:171]
	v_cvt_pk_bf16_f32 v166, v178, v179
	v_cvt_pk_bf16_f32 v167, v176, v177
	v_cvt_pk_bf16_f32 v168, v168, v169
	v_cvt_pk_bf16_f32 v169, v172, v173
	global_store_dwordx4 v[174:175], v[166:169], off
	global_load_dwordx4 v[166:169], v[152:153], off
	s_nop 0
	global_load_dwordx4 v[170:173], v[136:137], off
	v_lshlrev_b32_e32 v136, 7, v162
	v_mov_b32_e32 v137, v0
	v_and_b32_e32 v136, 0x3f780, v136
	v_lshl_add_u64 v[152:153], s[4:5], 0, v[136:137]
	v_lshl_add_u64 v[136:137], s[6:7], 0, v[136:137]
	v_lshl_add_u64 v[136:137], v[136:137], 0, v[130:131]
	v_lshl_add_u64 v[152:153], v[152:153], 0, v[130:131]
	s_waitcnt vmcnt(0)
	v_pk_mul_f32 v[168:169], v[168:169], s[86:87] op_sel_hi:[1,0]
	v_pk_mul_f32 v[172:173], v[172:173], s[86:87] op_sel_hi:[1,0]
	v_pk_mul_f32 v[170:171], v[170:171], s[86:87] op_sel_hi:[1,0]
	v_pk_mul_f32 v[166:167], v[166:167], s[86:87] op_sel_hi:[1,0]
	v_pk_mul_f32 v[176:177], v[92:93], v[172:173]
	v_pk_mul_f32 v[178:179], v[90:91], v[170:171]
	v_pk_mul_f32 v[172:173], v[100:101], v[172:173]
	v_pk_mul_f32 v[170:171], v[98:99], v[170:171]
	v_pk_fma_f32 v[176:177], v[100:101], v[168:169], v[176:177] neg_lo:[0,0,1] neg_hi:[0,0,1]
	v_pk_fma_f32 v[178:179], v[98:99], v[166:167], v[178:179] neg_lo:[0,0,1] neg_hi:[0,0,1]
	v_pk_fma_f32 v[172:173], v[92:93], v[168:169], v[172:173]
	v_pk_fma_f32 v[168:169], v[90:91], v[166:167], v[170:171]
	v_cvt_pk_bf16_f32 v166, v178, v179
	v_cvt_pk_bf16_f32 v167, v176, v177
	v_cvt_pk_bf16_f32 v168, v168, v169
	v_cvt_pk_bf16_f32 v169, v172, v173
	global_store_dwordx4 v[174:175], v[166:169], off offset:256
	global_load_dwordx4 v[170:173], v[136:137], off
	v_mad_i64_i32 v[174:175], s[18:19], v162, s24, v[132:133]
	global_load_dwordx4 v[166:169], v[152:153], off
	v_lshl_add_u64 v[174:175], v[174:175], 0, v[134:135]
	s_waitcnt vmcnt(0)
	v_pk_mul_f32 v[172:173], v[172:173], s[86:87] op_sel_hi:[1,0]
	v_pk_mul_f32 v[170:171], v[170:171], s[86:87] op_sel_hi:[1,0]
	v_pk_mul_f32 v[176:177], v[96:97], v[172:173]
	v_pk_mul_f32 v[168:169], v[168:169], s[86:87] op_sel_hi:[1,0]
	v_pk_mul_f32 v[166:167], v[166:167], s[86:87] op_sel_hi:[1,0]
	v_pk_mul_f32 v[178:179], v[94:95], v[170:171]
	v_pk_mul_f32 v[172:173], v[104:105], v[172:173]
	v_pk_mul_f32 v[170:171], v[102:103], v[170:171]
	v_pk_fma_f32 v[176:177], v[104:105], v[168:169], v[176:177] neg_lo:[0,0,1] neg_hi:[0,0,1]
	v_pk_fma_f32 v[178:179], v[102:103], v[166:167], v[178:179] neg_lo:[0,0,1] neg_hi:[0,0,1]
	v_pk_fma_f32 v[172:173], v[96:97], v[168:169], v[172:173]
	v_pk_fma_f32 v[168:169], v[94:95], v[166:167], v[170:171]
	v_cvt_pk_bf16_f32 v166, v178, v179
	v_cvt_pk_bf16_f32 v167, v176, v177
	v_cvt_pk_bf16_f32 v168, v168, v169
	v_cvt_pk_bf16_f32 v169, v172, v173
	global_store_dwordx4 v[174:175], v[166:169], off
	global_load_dwordx4 v[166:169], v[152:153], off
	s_nop 0
	global_load_dwordx4 v[170:173], v[136:137], off
	v_lshlrev_b32_e32 v136, 7, v161
	v_mov_b32_e32 v137, v0
	v_and_b32_e32 v136, 0x3ff80, v136
	v_lshl_add_u64 v[152:153], s[4:5], 0, v[136:137]
	v_lshl_add_u64 v[136:137], s[6:7], 0, v[136:137]
	v_lshl_add_u64 v[136:137], v[136:137], 0, v[130:131]
	v_lshl_add_u64 v[152:153], v[152:153], 0, v[130:131]
	s_waitcnt vmcnt(0)
	v_pk_mul_f32 v[168:169], v[168:169], s[86:87] op_sel_hi:[1,0]
	v_pk_mul_f32 v[172:173], v[172:173], s[86:87] op_sel_hi:[1,0]
	v_pk_mul_f32 v[170:171], v[170:171], s[86:87] op_sel_hi:[1,0]
	v_pk_mul_f32 v[166:167], v[166:167], s[86:87] op_sel_hi:[1,0]
	v_pk_mul_f32 v[176:177], v[76:77], v[172:173]
	v_pk_mul_f32 v[178:179], v[74:75], v[170:171]
	v_pk_mul_f32 v[172:173], v[84:85], v[172:173]
	v_pk_mul_f32 v[170:171], v[82:83], v[170:171]
	v_pk_fma_f32 v[176:177], v[84:85], v[168:169], v[176:177] neg_lo:[0,0,1] neg_hi:[0,0,1]
	v_pk_fma_f32 v[178:179], v[82:83], v[166:167], v[178:179] neg_lo:[0,0,1] neg_hi:[0,0,1]
	v_pk_fma_f32 v[172:173], v[76:77], v[168:169], v[172:173]
	v_pk_fma_f32 v[168:169], v[74:75], v[166:167], v[170:171]
	v_cvt_pk_bf16_f32 v166, v178, v179
	v_cvt_pk_bf16_f32 v167, v176, v177
	v_cvt_pk_bf16_f32 v168, v168, v169
	v_cvt_pk_bf16_f32 v169, v172, v173
	global_store_dwordx4 v[174:175], v[166:169], off offset:256
	global_load_dwordx4 v[170:173], v[136:137], off
	v_mad_i64_i32 v[174:175], s[18:19], v161, s24, v[132:133]
	global_load_dwordx4 v[166:169], v[152:153], off
	v_lshl_add_u64 v[174:175], v[174:175], 0, v[134:135]
	s_waitcnt vmcnt(0)
	v_pk_mul_f32 v[172:173], v[172:173], s[86:87] op_sel_hi:[1,0]
	v_pk_mul_f32 v[170:171], v[170:171], s[86:87] op_sel_hi:[1,0]
	v_pk_mul_f32 v[176:177], v[80:81], v[172:173]
	v_pk_mul_f32 v[168:169], v[168:169], s[86:87] op_sel_hi:[1,0]
	v_pk_mul_f32 v[166:167], v[166:167], s[86:87] op_sel_hi:[1,0]
	v_pk_mul_f32 v[178:179], v[78:79], v[170:171]
	v_pk_mul_f32 v[172:173], v[88:89], v[172:173]
	v_pk_mul_f32 v[170:171], v[86:87], v[170:171]
	v_pk_fma_f32 v[176:177], v[88:89], v[168:169], v[176:177] neg_lo:[0,0,1] neg_hi:[0,0,1]
	v_pk_fma_f32 v[178:179], v[86:87], v[166:167], v[178:179] neg_lo:[0,0,1] neg_hi:[0,0,1]
	v_pk_fma_f32 v[172:173], v[80:81], v[168:169], v[172:173]
	v_pk_fma_f32 v[168:169], v[78:79], v[166:167], v[170:171]
	v_cvt_pk_bf16_f32 v166, v178, v179
	v_cvt_pk_bf16_f32 v167, v176, v177
	v_cvt_pk_bf16_f32 v168, v168, v169
	v_cvt_pk_bf16_f32 v169, v172, v173
	global_store_dwordx4 v[174:175], v[166:169], off
	global_load_dwordx4 v[166:169], v[152:153], off
	s_nop 0
	global_load_dwordx4 v[170:173], v[136:137], off
	v_lshlrev_b32_e32 v136, 7, v160
	v_mov_b32_e32 v137, v0
	v_and_b32_e32 v136, 0x3e780, v136
	v_lshl_add_u64 v[152:153], s[4:5], 0, v[136:137]
	v_lshl_add_u64 v[136:137], s[6:7], 0, v[136:137]
	v_lshl_add_u64 v[136:137], v[136:137], 0, v[130:131]
	v_lshl_add_u64 v[152:153], v[152:153], 0, v[130:131]
	s_waitcnt vmcnt(0)
	v_pk_mul_f32 v[168:169], v[168:169], s[86:87] op_sel_hi:[1,0]
	v_pk_mul_f32 v[172:173], v[172:173], s[86:87] op_sel_hi:[1,0]
	v_pk_mul_f32 v[170:171], v[170:171], s[86:87] op_sel_hi:[1,0]
	v_pk_mul_f32 v[166:167], v[166:167], s[86:87] op_sel_hi:[1,0]
	v_pk_mul_f32 v[176:177], v[68:69], v[172:173]
	v_pk_mul_f32 v[178:179], v[66:67], v[170:171]
	v_pk_mul_f32 v[172:173], v[72:73], v[172:173]
	v_pk_mul_f32 v[170:171], v[70:71], v[170:171]
	v_pk_fma_f32 v[176:177], v[72:73], v[168:169], v[176:177] neg_lo:[0,0,1] neg_hi:[0,0,1]
	v_pk_fma_f32 v[178:179], v[70:71], v[166:167], v[178:179] neg_lo:[0,0,1] neg_hi:[0,0,1]
	v_pk_fma_f32 v[172:173], v[68:69], v[168:169], v[172:173]
	v_pk_fma_f32 v[168:169], v[66:67], v[166:167], v[170:171]
	v_cvt_pk_bf16_f32 v166, v178, v179
	v_cvt_pk_bf16_f32 v167, v176, v177
	v_cvt_pk_bf16_f32 v168, v168, v169
	v_cvt_pk_bf16_f32 v169, v172, v173
	global_store_dwordx4 v[174:175], v[166:169], off offset:256
	global_load_dwordx4 v[170:173], v[136:137], off
	v_mad_i64_i32 v[174:175], s[18:19], v160, s24, v[132:133]
	global_load_dwordx4 v[166:169], v[152:153], off
	v_lshl_add_u64 v[174:175], v[174:175], 0, v[134:135]
	s_waitcnt vmcnt(0)
	v_pk_mul_f32 v[172:173], v[172:173], s[86:87] op_sel_hi:[1,0]
	v_pk_mul_f32 v[170:171], v[170:171], s[86:87] op_sel_hi:[1,0]
	v_pk_mul_f32 v[176:177], v[60:61], v[172:173]
	v_pk_mul_f32 v[168:169], v[168:169], s[86:87] op_sel_hi:[1,0]
	v_pk_mul_f32 v[166:167], v[166:167], s[86:87] op_sel_hi:[1,0]
	v_pk_mul_f32 v[178:179], v[58:59], v[170:171]
	v_pk_mul_f32 v[172:173], v[64:65], v[172:173]
	v_pk_mul_f32 v[170:171], v[62:63], v[170:171]
	v_pk_fma_f32 v[176:177], v[64:65], v[168:169], v[176:177] neg_lo:[0,0,1] neg_hi:[0,0,1]
	v_pk_fma_f32 v[178:179], v[62:63], v[166:167], v[178:179] neg_lo:[0,0,1] neg_hi:[0,0,1]
	v_pk_fma_f32 v[172:173], v[60:61], v[168:169], v[172:173]
	v_pk_fma_f32 v[168:169], v[58:59], v[166:167], v[170:171]
	v_cvt_pk_bf16_f32 v166, v178, v179
	v_cvt_pk_bf16_f32 v167, v176, v177
	v_cvt_pk_bf16_f32 v168, v168, v169
	v_cvt_pk_bf16_f32 v169, v172, v173
	global_store_dwordx4 v[174:175], v[166:169], off
	global_load_dwordx4 v[166:169], v[152:153], off
	s_nop 0
	global_load_dwordx4 v[170:173], v[136:137], off
	v_lshlrev_b32_e32 v136, 7, v159
	v_mov_b32_e32 v137, v0
	v_and_b32_e32 v136, 0x3ef80, v136
	v_lshl_add_u64 v[152:153], s[4:5], 0, v[136:137]
	v_lshl_add_u64 v[136:137], s[6:7], 0, v[136:137]
	v_lshl_add_u64 v[136:137], v[136:137], 0, v[130:131]
	v_lshl_add_u64 v[152:153], v[152:153], 0, v[130:131]
	s_waitcnt vmcnt(0)
	v_pk_mul_f32 v[168:169], v[168:169], s[86:87] op_sel_hi:[1,0]
	v_pk_mul_f32 v[172:173], v[172:173], s[86:87] op_sel_hi:[1,0]
	v_pk_mul_f32 v[170:171], v[170:171], s[86:87] op_sel_hi:[1,0]
	v_pk_mul_f32 v[166:167], v[166:167], s[86:87] op_sel_hi:[1,0]
	v_pk_mul_f32 v[176:177], v[44:45], v[172:173]
	v_pk_mul_f32 v[178:179], v[42:43], v[170:171]
	v_pk_mul_f32 v[172:173], v[52:53], v[172:173]
	v_pk_mul_f32 v[170:171], v[50:51], v[170:171]
	v_pk_fma_f32 v[176:177], v[52:53], v[168:169], v[176:177] neg_lo:[0,0,1] neg_hi:[0,0,1]
	v_pk_fma_f32 v[178:179], v[50:51], v[166:167], v[178:179] neg_lo:[0,0,1] neg_hi:[0,0,1]
	v_pk_fma_f32 v[172:173], v[44:45], v[168:169], v[172:173]
	v_pk_fma_f32 v[168:169], v[42:43], v[166:167], v[170:171]
	v_cvt_pk_bf16_f32 v166, v178, v179
	v_cvt_pk_bf16_f32 v167, v176, v177
	v_cvt_pk_bf16_f32 v168, v168, v169
	v_cvt_pk_bf16_f32 v169, v172, v173
	global_store_dwordx4 v[174:175], v[166:169], off offset:256
	global_load_dwordx4 v[170:173], v[136:137], off
	v_mad_i64_i32 v[174:175], s[18:19], v159, s24, v[132:133]
	global_load_dwordx4 v[166:169], v[152:153], off
	v_lshl_add_u64 v[174:175], v[174:175], 0, v[134:135]
	s_waitcnt vmcnt(0)
	v_pk_mul_f32 v[172:173], v[172:173], s[86:87] op_sel_hi:[1,0]
	v_pk_mul_f32 v[170:171], v[170:171], s[86:87] op_sel_hi:[1,0]
	v_pk_mul_f32 v[176:177], v[48:49], v[172:173]
	v_pk_mul_f32 v[168:169], v[168:169], s[86:87] op_sel_hi:[1,0]
	v_pk_mul_f32 v[166:167], v[166:167], s[86:87] op_sel_hi:[1,0]
	v_pk_mul_f32 v[178:179], v[46:47], v[170:171]
	v_pk_mul_f32 v[172:173], v[56:57], v[172:173]
	v_pk_mul_f32 v[170:171], v[54:55], v[170:171]
	v_pk_fma_f32 v[176:177], v[56:57], v[168:169], v[176:177] neg_lo:[0,0,1] neg_hi:[0,0,1]
	v_pk_fma_f32 v[178:179], v[54:55], v[166:167], v[178:179] neg_lo:[0,0,1] neg_hi:[0,0,1]
	v_pk_fma_f32 v[172:173], v[48:49], v[168:169], v[172:173]
	v_pk_fma_f32 v[168:169], v[46:47], v[166:167], v[170:171]
	v_cvt_pk_bf16_f32 v166, v178, v179
	v_cvt_pk_bf16_f32 v167, v176, v177
	v_cvt_pk_bf16_f32 v168, v168, v169
	v_cvt_pk_bf16_f32 v169, v172, v173
	global_store_dwordx4 v[174:175], v[166:169], off
	global_load_dwordx4 v[166:169], v[152:153], off
	s_nop 0
	global_load_dwordx4 v[170:173], v[136:137], off
	v_lshlrev_b32_e32 v136, 7, v158
	v_mov_b32_e32 v137, v0
	v_and_b32_e32 v136, 0x3f780, v136
	v_lshl_add_u64 v[152:153], s[4:5], 0, v[136:137]
	v_lshl_add_u64 v[136:137], s[6:7], 0, v[136:137]
	v_lshl_add_u64 v[136:137], v[136:137], 0, v[130:131]
	v_lshl_add_u64 v[152:153], v[152:153], 0, v[130:131]
	s_waitcnt vmcnt(0)
	v_pk_mul_f32 v[168:169], v[168:169], s[86:87] op_sel_hi:[1,0]
	v_pk_mul_f32 v[172:173], v[172:173], s[86:87] op_sel_hi:[1,0]
	v_pk_mul_f32 v[170:171], v[170:171], s[86:87] op_sel_hi:[1,0]
	v_pk_mul_f32 v[166:167], v[166:167], s[86:87] op_sel_hi:[1,0]
	v_pk_mul_f32 v[176:177], v[28:29], v[172:173]
	v_pk_mul_f32 v[178:179], v[26:27], v[170:171]
	v_pk_mul_f32 v[172:173], v[36:37], v[172:173]
	v_pk_mul_f32 v[170:171], v[34:35], v[170:171]
	v_pk_fma_f32 v[176:177], v[36:37], v[168:169], v[176:177] neg_lo:[0,0,1] neg_hi:[0,0,1]
	v_pk_fma_f32 v[178:179], v[34:35], v[166:167], v[178:179] neg_lo:[0,0,1] neg_hi:[0,0,1]
	v_pk_fma_f32 v[172:173], v[28:29], v[168:169], v[172:173]
	v_pk_fma_f32 v[168:169], v[26:27], v[166:167], v[170:171]
	v_cvt_pk_bf16_f32 v166, v178, v179
	v_cvt_pk_bf16_f32 v167, v176, v177
	v_cvt_pk_bf16_f32 v168, v168, v169
	v_cvt_pk_bf16_f32 v169, v172, v173
	global_store_dwordx4 v[174:175], v[166:169], off offset:256
	global_load_dwordx4 v[170:173], v[136:137], off
	v_mad_i64_i32 v[174:175], s[18:19], v158, s24, v[132:133]
	global_load_dwordx4 v[166:169], v[152:153], off
	v_lshl_add_u64 v[174:175], v[174:175], 0, v[134:135]
	s_waitcnt vmcnt(0)
	v_pk_mul_f32 v[172:173], v[172:173], s[86:87] op_sel_hi:[1,0]
	v_pk_mul_f32 v[170:171], v[170:171], s[86:87] op_sel_hi:[1,0]
	v_pk_mul_f32 v[176:177], v[32:33], v[172:173]
	v_pk_mul_f32 v[168:169], v[168:169], s[86:87] op_sel_hi:[1,0]
	v_pk_mul_f32 v[166:167], v[166:167], s[86:87] op_sel_hi:[1,0]
	v_pk_mul_f32 v[178:179], v[30:31], v[170:171]
	v_pk_mul_f32 v[172:173], v[40:41], v[172:173]
	v_pk_mul_f32 v[170:171], v[38:39], v[170:171]
	v_pk_fma_f32 v[176:177], v[40:41], v[168:169], v[176:177] neg_lo:[0,0,1] neg_hi:[0,0,1]
	v_pk_fma_f32 v[178:179], v[38:39], v[166:167], v[178:179] neg_lo:[0,0,1] neg_hi:[0,0,1]
	v_pk_fma_f32 v[172:173], v[32:33], v[168:169], v[172:173]
	v_pk_fma_f32 v[168:169], v[30:31], v[166:167], v[170:171]
	v_cvt_pk_bf16_f32 v166, v178, v179
	v_cvt_pk_bf16_f32 v167, v176, v177
	v_cvt_pk_bf16_f32 v168, v168, v169
	v_cvt_pk_bf16_f32 v169, v172, v173
	global_store_dwordx4 v[174:175], v[166:169], off
	global_load_dwordx4 v[166:169], v[152:153], off
	s_nop 0
	global_load_dwordx4 v[170:173], v[136:137], off
	v_lshlrev_b32_e32 v136, 7, v157
	v_mov_b32_e32 v137, v0
	v_and_b32_e32 v136, 0x3ff80, v136
	v_lshl_add_u64 v[152:153], s[4:5], 0, v[136:137]
	v_lshl_add_u64 v[176:177], v[152:153], 0, v[130:131]
	v_lshl_add_u64 v[136:137], s[6:7], 0, v[136:137]
	v_lshl_add_u64 v[136:137], v[136:137], 0, v[130:131]
	v_mad_i64_i32 v[130:131], s[18:19], v157, s24, v[132:133]
	s_mov_b64 s[18:19], 0
	s_waitcnt vmcnt(0)
	v_pk_mul_f32 v[152:153], v[168:169], s[86:87] op_sel_hi:[1,0]
	v_pk_mul_f32 v[168:169], v[172:173], s[86:87] op_sel_hi:[1,0]
	v_pk_mul_f32 v[170:171], v[170:171], s[86:87] op_sel_hi:[1,0]
	v_pk_mul_f32 v[166:167], v[166:167], s[86:87] op_sel_hi:[1,0]
	v_pk_mul_f32 v[172:173], v[12:13], v[168:169]
	v_pk_mul_f32 v[178:179], v[10:11], v[170:171]
	v_pk_mul_f32 v[168:169], v[20:21], v[168:169]
	v_pk_mul_f32 v[170:171], v[18:19], v[170:171]
	v_pk_fma_f32 v[172:173], v[20:21], v[152:153], v[172:173] neg_lo:[0,0,1] neg_hi:[0,0,1]
	v_pk_fma_f32 v[178:179], v[18:19], v[166:167], v[178:179] neg_lo:[0,0,1] neg_hi:[0,0,1]
	v_pk_fma_f32 v[152:153], v[12:13], v[152:153], v[168:169]
	v_pk_fma_f32 v[168:169], v[10:11], v[166:167], v[170:171]
	v_cvt_pk_bf16_f32 v166, v178, v179
	v_cvt_pk_bf16_f32 v167, v172, v173
	v_cvt_pk_bf16_f32 v168, v168, v169
	v_cvt_pk_bf16_f32 v169, v152, v153
	global_store_dwordx4 v[174:175], v[166:169], off offset:256
	global_load_dwordx4 v[166:169], v[176:177], off
	v_lshl_add_u64 v[152:153], v[130:131], 0, v[134:135]
	global_load_dwordx4 v[170:173], v[136:137], off
	s_waitcnt vmcnt(0)
	v_pk_mul_f32 v[132:133], v[166:167], s[86:87] op_sel_hi:[1,0]
	v_pk_mul_f32 v[130:131], v[168:169], s[86:87] op_sel_hi:[1,0]
	v_pk_mul_f32 v[134:135], v[172:173], s[86:87] op_sel_hi:[1,0]
	v_pk_mul_f32 v[166:167], v[170:171], s[86:87] op_sel_hi:[1,0]
	v_pk_mul_f32 v[168:169], v[16:17], v[134:135]
	v_pk_mul_f32 v[170:171], v[14:15], v[166:167]
	v_pk_mul_f32 v[134:135], v[24:25], v[134:135]
	v_pk_mul_f32 v[166:167], v[22:23], v[166:167]
	v_pk_fma_f32 v[168:169], v[24:25], v[130:131], v[168:169] neg_lo:[0,0,1] neg_hi:[0,0,1]
	v_pk_fma_f32 v[170:171], v[22:23], v[132:133], v[170:171] neg_lo:[0,0,1] neg_hi:[0,0,1]
	v_pk_fma_f32 v[134:135], v[16:17], v[130:131], v[134:135]
	v_pk_fma_f32 v[132:133], v[14:15], v[132:133], v[166:167]
	v_cvt_pk_bf16_f32 v130, v170, v171
	v_cvt_pk_bf16_f32 v131, v168, v169
	v_cvt_pk_bf16_f32 v132, v132, v133
	v_cvt_pk_bf16_f32 v133, v134, v135
	global_store_dwordx4 v[152:153], v[130:133], off
	global_load_dwordx4 v[130:133], v[176:177], off
	s_nop 0
	global_load_dwordx4 v[134:137], v[136:137], off
	s_waitcnt vmcnt(0)
	v_pk_mul_f32 v[166:167], v[132:133], s[86:87] op_sel_hi:[1,0]
	v_pk_mul_f32 v[168:169], v[130:131], s[86:87] op_sel_hi:[1,0]
	v_pk_mul_f32 v[130:131], v[136:137], s[86:87] op_sel_hi:[1,0]
	v_pk_mul_f32 v[132:133], v[134:135], s[86:87] op_sel_hi:[1,0]
	v_pk_mul_f32 v[134:135], v[4:5], v[130:131]
	v_pk_mul_f32 v[136:137], v[2:3], v[132:133]
	v_pk_mul_f32 v[170:171], v[8:9], v[130:131]
	v_pk_mul_f32 v[172:173], v[6:7], v[132:133]
	v_pk_fma_f32 v[132:133], v[8:9], v[166:167], v[134:135] neg_lo:[0,0,1] neg_hi:[0,0,1]
	v_pk_fma_f32 v[130:131], v[6:7], v[168:169], v[136:137] neg_lo:[0,0,1] neg_hi:[0,0,1]
	v_pk_fma_f32 v[136:137], v[4:5], v[166:167], v[170:171]
	v_pk_fma_f32 v[134:135], v[2:3], v[168:169], v[172:173]

.LBB0_526:
	s_add_u32 s20, s18, 0xfff80080
	s_addc_u32 s21, s19, -1
	s_add_i32 s56, 0, 0x10000
	s_cmp_eq_u32 s55, 28
	s_cselect_b32 s23, s39, s21
	s_cselect_b32 s22, s51, s20
	s_cselect_b32 s21, s31, s54
	s_cselect_b32 s20, s52, s53
	v_lshl_add_u64 v[152:153], s[18:19], 0, v[140:141]
	s_add_i32 m0, s29, 0xc000
	ds_read_b128 v[164:167], v154
	ds_read_b128 v[168:171], v154 offset:1024
	ds_read_b128 v[172:175], v154 offset:2048
	ds_read_b128 v[176:179], v154 offset:3072
	ds_read_b128 v[192:195], v154 offset:4096
	ds_read_b128 v[196:199], v154 offset:5120
	ds_read_b128 v[200:203], v154 offset:6144
	ds_read_b128 v[204:207], v154 offset:7168
	global_load_lds_dwordx4 v[152:153], off
	v_lshl_add_u64 v[152:153], s[18:19], 0, v[142:143]
	s_add_i32 m0, s29, 0xe000
	s_nop 0
	global_load_lds_dwordx4 v[152:153], off
	s_waitcnt lgkmcnt(8)
	s_barrier
	s_waitcnt lgkmcnt(0)
	s_waitcnt lgkmcnt(0)
	v_mfma_f32_16x16x32_bf16 v[126:129], v[144:147], v[164:167], v[126:129]
	v_mfma_f32_16x16x32_bf16 v[122:125], v[156:159], v[164:167], v[122:125]
	v_mfma_f32_16x16x32_bf16 v[118:121], v[144:147], v[172:175], v[118:121]
	v_mfma_f32_16x16x32_bf16 v[114:117], v[156:159], v[172:175], v[114:117]
	v_mfma_f32_16x16x32_bf16 v[102:105], v[144:147], v[192:195], v[102:105]
	v_mfma_f32_16x16x32_bf16 v[98:101], v[156:159], v[192:195], v[98:101]
	v_mfma_f32_16x16x32_bf16 v[86:89], v[144:147], v[200:203], v[86:89]
	v_mfma_f32_16x16x32_bf16 v[82:85], v[156:159], v[200:203], v[82:85]
	v_mfma_f32_16x16x32_bf16 v[126:129], v[148:151], v[168:171], v[126:129]
	v_mfma_f32_16x16x32_bf16 v[122:125], v[160:163], v[168:171], v[122:125]
	v_mfma_f32_16x16x32_bf16 v[118:121], v[148:151], v[176:179], v[118:121]
	v_mfma_f32_16x16x32_bf16 v[114:117], v[160:163], v[176:179], v[114:117]
	v_mfma_f32_16x16x32_bf16 v[102:105], v[148:151], v[196:199], v[102:105]
	v_mfma_f32_16x16x32_bf16 v[98:101], v[160:163], v[196:199], v[98:101]
	v_mfma_f32_16x16x32_bf16 v[86:89], v[148:151], v[204:207], v[86:89]
	v_mfma_f32_16x16x32_bf16 v[82:85], v[160:163], v[204:207], v[82:85]
	s_barrier
	s_add_i32 s58, 0, 0x14000
	v_add_u32_e32 v152, s58, v139
	s_add_i32 s56, s56, s28
	ds_read_b128 v[208:211], v152
	ds_read_b128 v[224:227], v152 offset:1024
	ds_read_b128 v[228:231], v152 offset:2048
	ds_read_b128 v[232:235], v152 offset:3072
	v_lshl_add_u64 v[152:153], s[20:21], 0, v[134:135]
	s_mov_b32 m0, s56
	v_lshl_add_u64 v[212:213], s[20:21], 0, v[130:131]
	global_load_lds_dwordx4 v[152:153], off
	s_add_i32 m0, s56, 0x2000
	s_nop 0
	global_load_lds_dwordx4 v[212:213], off
	s_barrier
	s_waitcnt lgkmcnt(0)
	s_waitcnt lgkmcnt(0)
	v_mfma_f32_16x16x32_bf16 v[110:113], v[208:211], v[164:167], v[110:113]
	v_mfma_f32_16x16x32_bf16 v[106:109], v[228:231], v[164:167], v[106:109]
	v_mfma_f32_16x16x32_bf16 v[94:97], v[208:211], v[172:175], v[94:97]
	v_mfma_f32_16x16x32_bf16 v[90:93], v[228:231], v[172:175], v[90:93]
	v_mfma_f32_16x16x32_bf16 v[78:81], v[208:211], v[192:195], v[78:81]
	v_mfma_f32_16x16x32_bf16 v[74:77], v[228:231], v[192:195], v[74:77]
	v_mfma_f32_16x16x32_bf16 v[70:73], v[208:211], v[200:203], v[70:73]
	v_mfma_f32_16x16x32_bf16 v[66:69], v[228:231], v[200:203], v[66:69]
	v_mfma_f32_16x16x32_bf16 v[110:113], v[224:227], v[168:171], v[110:113]
	v_mfma_f32_16x16x32_bf16 v[106:109], v[232:235], v[168:171], v[106:109]
	v_mfma_f32_16x16x32_bf16 v[94:97], v[224:227], v[176:179], v[94:97]
	v_mfma_f32_16x16x32_bf16 v[90:93], v[232:235], v[176:179], v[90:93]
	v_mfma_f32_16x16x32_bf16 v[78:81], v[224:227], v[196:199], v[78:81]
	v_mfma_f32_16x16x32_bf16 v[74:77], v[232:235], v[196:199], v[74:77]
	v_mfma_f32_16x16x32_bf16 v[70:73], v[224:227], v[204:207], v[70:73]
	v_mfma_f32_16x16x32_bf16 v[66:69], v[232:235], v[204:207], v[66:69]
	s_mov_b32 m0, s29
	v_lshl_add_u64 v[236:237], s[22:23], 0, v[136:137]
	s_barrier
	ds_read_b128 v[164:167], v154 offset:16384
	ds_read_b128 v[168:171], v154 offset:17408
	ds_read_b128 v[172:175], v154 offset:18432
	ds_read_b128 v[176:179], v154 offset:19456
	ds_read_b128 v[192:195], v154 offset:20480
	ds_read_b128 v[196:199], v154 offset:21504
	ds_read_b128 v[200:203], v154 offset:22528
	ds_read_b128 v[204:207], v154 offset:23552
	global_load_lds_dwordx4 v[236:237], off
	v_lshl_add_u64 v[238:239], s[22:23], 0, v[132:133]
	s_mov_b32 m0, s44
	s_nop 0
	global_load_lds_dwordx4 v[238:239], off
	s_waitcnt vmcnt(10)
	s_barrier
	s_waitcnt lgkmcnt(0)
	s_waitcnt lgkmcnt(0)
	v_mfma_f32_16x16x32_bf16 v[62:65], v[144:147], v[164:167], v[62:65]
	v_mfma_f32_16x16x32_bf16 v[58:61], v[156:159], v[164:167], v[58:61]
	v_mfma_f32_16x16x32_bf16 v[54:57], v[144:147], v[172:175], v[54:57]
	v_mfma_f32_16x16x32_bf16 v[50:53], v[156:159], v[172:175], v[50:53]
	v_mfma_f32_16x16x32_bf16 v[38:41], v[144:147], v[192:195], v[38:41]
	v_mfma_f32_16x16x32_bf16 v[34:37], v[156:159], v[192:195], v[34:37]
	v_mfma_f32_16x16x32_bf16 v[22:25], v[144:147], v[200:203], v[22:25]
	v_mfma_f32_16x16x32_bf16 v[18:21], v[156:159], v[200:203], v[18:21]
	v_mfma_f32_16x16x32_bf16 v[62:65], v[148:151], v[168:171], v[62:65]
	v_mfma_f32_16x16x32_bf16 v[58:61], v[160:163], v[168:171], v[58:61]
	v_mfma_f32_16x16x32_bf16 v[54:57], v[148:151], v[176:179], v[54:57]
	v_mfma_f32_16x16x32_bf16 v[50:53], v[160:163], v[176:179], v[50:53]
	v_mfma_f32_16x16x32_bf16 v[38:41], v[148:151], v[196:199], v[38:41]
	v_mfma_f32_16x16x32_bf16 v[34:37], v[160:163], v[196:199], v[34:37]
	v_mfma_f32_16x16x32_bf16 v[22:25], v[148:151], v[204:207], v[22:25]
	v_mfma_f32_16x16x32_bf16 v[18:21], v[160:163], v[204:207], v[18:21]
	s_barrier
	s_add_u32 s56, s20, 0x80000
	s_addc_u32 s57, s21, 0
	s_add_i32 s58, s58, s28
	v_lshl_add_u64 v[144:145], s[56:57], 0, v[134:135]
	s_mov_b32 m0, s58
	s_nop 0
	global_load_lds_dwordx4 v[144:145], off
	v_lshl_add_u64 v[144:145], s[56:57], 0, v[130:131]
	s_add_i32 m0, s58, 0x2000
	s_nop 0
	global_load_lds_dwordx4 v[144:145], off
	v_add_u32_e32 v155, 0x18000, v139
	ds_read_b128 v[144:147], v155
	ds_read_b128 v[148:151], v155 offset:1024
	ds_read_b128 v[156:159], v155 offset:2048
	ds_read_b128 v[160:163], v155 offset:3072
	s_waitcnt vmcnt(6)
	s_barrier
	v_mfma_f32_16x16x32_bf16 v[46:49], v[208:211], v[164:167], v[46:49]
	v_mfma_f32_16x16x32_bf16 v[42:45], v[228:231], v[164:167], v[42:45]
	v_mfma_f32_16x16x32_bf16 v[30:33], v[208:211], v[172:175], v[30:33]
	v_mfma_f32_16x16x32_bf16 v[26:29], v[228:231], v[172:175], v[26:29]
	v_mfma_f32_16x16x32_bf16 v[14:17], v[208:211], v[192:195], v[14:17]
	v_mfma_f32_16x16x32_bf16 v[10:13], v[228:231], v[192:195], v[10:13]
	v_mfma_f32_16x16x32_bf16 v[6:9], v[208:211], v[200:203], v[6:9]
	v_mfma_f32_16x16x32_bf16 v[2:5], v[228:231], v[200:203], v[2:5]
	v_mfma_f32_16x16x32_bf16 v[46:49], v[224:227], v[168:171], v[46:49]
	v_mfma_f32_16x16x32_bf16 v[42:45], v[232:235], v[168:171], v[42:45]
	v_mfma_f32_16x16x32_bf16 v[30:33], v[224:227], v[176:179], v[30:33]
	v_mfma_f32_16x16x32_bf16 v[26:29], v[232:235], v[176:179], v[26:29]
	v_mfma_f32_16x16x32_bf16 v[14:17], v[224:227], v[196:199], v[14:17]
	v_mfma_f32_16x16x32_bf16 v[10:13], v[232:235], v[196:199], v[10:13]
	v_mfma_f32_16x16x32_bf16 v[6:9], v[224:227], v[204:207], v[6:9]
	v_mfma_f32_16x16x32_bf16 v[2:5], v[232:235], v[204:207], v[2:5]
	s_add_i32 s56, 0, 0x18000
	s_barrier
	s_add_u32 s22, s22, 0x80000
	s_addc_u32 s23, s23, 0
	s_mov_b32 m0, s45
	v_lshl_add_u64 v[208:209], s[22:23], 0, v[136:137]
	ds_read_b128 v[164:167], v154 offset:32768
	ds_read_b128 v[168:171], v154 offset:33792
	ds_read_b128 v[172:175], v154 offset:34816
	ds_read_b128 v[176:179], v154 offset:35840
	ds_read_b128 v[192:195], v154 offset:36864
	ds_read_b128 v[196:199], v154 offset:37888
	ds_read_b128 v[200:203], v154 offset:38912
	ds_read_b128 v[204:207], v154 offset:39936
	global_load_lds_dwordx4 v[208:209], off
	v_lshl_add_u64 v[208:209], s[22:23], 0, v[132:133]
	s_mov_b32 m0, s46
	s_nop 0
	global_load_lds_dwordx4 v[208:209], off
	s_waitcnt lgkmcnt(8)
	s_barrier
	s_waitcnt lgkmcnt(0)
	s_waitcnt lgkmcnt(0)
	v_mfma_f32_16x16x32_bf16 v[126:129], v[144:147], v[164:167], v[126:129]
	v_mfma_f32_16x16x32_bf16 v[122:125], v[156:159], v[164:167], v[122:125]
	v_mfma_f32_16x16x32_bf16 v[118:121], v[144:147], v[172:175], v[118:121]
	v_mfma_f32_16x16x32_bf16 v[114:117], v[156:159], v[172:175], v[114:117]
	v_mfma_f32_16x16x32_bf16 v[102:105], v[144:147], v[192:195], v[102:105]
	v_mfma_f32_16x16x32_bf16 v[98:101], v[156:159], v[192:195], v[98:101]
	v_mfma_f32_16x16x32_bf16 v[86:89], v[144:147], v[200:203], v[86:89]
	v_mfma_f32_16x16x32_bf16 v[82:85], v[156:159], v[200:203], v[82:85]
	v_mfma_f32_16x16x32_bf16 v[126:129], v[148:151], v[168:171], v[126:129]
	v_mfma_f32_16x16x32_bf16 v[122:125], v[160:163], v[168:171], v[122:125]
	v_mfma_f32_16x16x32_bf16 v[118:121], v[148:151], v[176:179], v[118:121]
	v_mfma_f32_16x16x32_bf16 v[114:117], v[160:163], v[176:179], v[114:117]
	v_mfma_f32_16x16x32_bf16 v[102:105], v[148:151], v[196:199], v[102:105]
	v_mfma_f32_16x16x32_bf16 v[98:101], v[160:163], v[196:199], v[98:101]
	v_mfma_f32_16x16x32_bf16 v[86:89], v[148:151], v[204:207], v[86:89]
	v_mfma_f32_16x16x32_bf16 v[82:85], v[160:163], v[204:207], v[82:85]
	s_barrier
	s_add_i32 s22, 0, 0x1c000
	s_add_i32 s23, s56, s28
	v_add_u32_e32 v155, s22, v139
	v_lshl_add_u64 v[152:153], v[152:153], 0, s[78:79]
	s_mov_b32 m0, s23
	ds_read_b128 v[208:211], v155
	ds_read_b128 v[224:227], v155 offset:1024
	ds_read_b128 v[228:231], v155 offset:2048
	ds_read_b128 v[232:235], v155 offset:3072
	global_load_lds_dwordx4 v[152:153], off
	v_lshl_add_u64 v[152:153], v[212:213], 0, s[78:79]
	s_add_i32 m0, s23, 0x2000
	s_nop 0
	global_load_lds_dwordx4 v[152:153], off
	s_barrier
	s_waitcnt lgkmcnt(0)
	s_waitcnt lgkmcnt(0)
	v_mfma_f32_16x16x32_bf16 v[110:113], v[208:211], v[164:167], v[110:113]
	v_mfma_f32_16x16x32_bf16 v[106:109], v[228:231], v[164:167], v[106:109]
	v_mfma_f32_16x16x32_bf16 v[94:97], v[208:211], v[172:175], v[94:97]
	v_mfma_f32_16x16x32_bf16 v[90:93], v[228:231], v[172:175], v[90:93]
	v_mfma_f32_16x16x32_bf16 v[78:81], v[208:211], v[192:195], v[78:81]
	v_mfma_f32_16x16x32_bf16 v[74:77], v[228:231], v[192:195], v[74:77]
	v_mfma_f32_16x16x32_bf16 v[70:73], v[208:211], v[200:203], v[70:73]
	v_mfma_f32_16x16x32_bf16 v[66:69], v[228:231], v[200:203], v[66:69]
	v_mfma_f32_16x16x32_bf16 v[110:113], v[224:227], v[168:171], v[110:113]
	v_mfma_f32_16x16x32_bf16 v[106:109], v[232:235], v[168:171], v[106:109]
	v_mfma_f32_16x16x32_bf16 v[94:97], v[224:227], v[176:179], v[94:97]
	v_mfma_f32_16x16x32_bf16 v[90:93], v[232:235], v[176:179], v[90:93]
	v_mfma_f32_16x16x32_bf16 v[78:81], v[224:227], v[196:199], v[78:81]
	v_mfma_f32_16x16x32_bf16 v[74:77], v[232:235], v[196:199], v[74:77]
	v_mfma_f32_16x16x32_bf16 v[70:73], v[224:227], v[204:207], v[70:73]
	v_mfma_f32_16x16x32_bf16 v[66:69], v[232:235], v[204:207], v[66:69]
	s_mov_b32 m0, s47
	v_lshl_add_u64 v[152:153], v[236:237], 0, s[78:79]
	s_barrier
	ds_read_b128 v[164:167], v154 offset:49152
	ds_read_b128 v[168:171], v154 offset:50176
	ds_read_b128 v[172:175], v154 offset:51200
	ds_read_b128 v[176:179], v154 offset:52224
	ds_read_b128 v[192:195], v154 offset:53248
	ds_read_b128 v[196:199], v154 offset:54272
	ds_read_b128 v[200:203], v154 offset:55296
	ds_read_b128 v[204:207], v154 offset:56320
	global_load_lds_dwordx4 v[152:153], off
	v_lshl_add_u64 v[152:153], v[238:239], 0, s[78:79]
	s_mov_b32 m0, s48
	s_nop 0
	global_load_lds_dwordx4 v[152:153], off
	s_waitcnt vmcnt(10)
	s_barrier
	s_waitcnt lgkmcnt(0)
	s_waitcnt lgkmcnt(0)
	v_mfma_f32_16x16x32_bf16 v[62:65], v[144:147], v[164:167], v[62:65]
	v_mfma_f32_16x16x32_bf16 v[58:61], v[156:159], v[164:167], v[58:61]
	v_mfma_f32_16x16x32_bf16 v[54:57], v[144:147], v[172:175], v[54:57]
	v_mfma_f32_16x16x32_bf16 v[50:53], v[156:159], v[172:175], v[50:53]
	v_mfma_f32_16x16x32_bf16 v[38:41], v[144:147], v[192:195], v[38:41]
	v_mfma_f32_16x16x32_bf16 v[34:37], v[156:159], v[192:195], v[34:37]
	v_mfma_f32_16x16x32_bf16 v[22:25], v[144:147], v[200:203], v[22:25]
	v_mfma_f32_16x16x32_bf16 v[18:21], v[156:159], v[200:203], v[18:21]
	v_mfma_f32_16x16x32_bf16 v[62:65], v[148:151], v[168:171], v[62:65]
	v_mfma_f32_16x16x32_bf16 v[58:61], v[160:163], v[168:171], v[58:61]
	v_mfma_f32_16x16x32_bf16 v[54:57], v[148:151], v[176:179], v[54:57]
	v_mfma_f32_16x16x32_bf16 v[50:53], v[160:163], v[176:179], v[50:53]
	v_mfma_f32_16x16x32_bf16 v[38:41], v[148:151], v[196:199], v[38:41]
	v_mfma_f32_16x16x32_bf16 v[34:37], v[160:163], v[196:199], v[34:37]
	v_mfma_f32_16x16x32_bf16 v[22:25], v[148:151], v[204:207], v[22:25]
	v_mfma_f32_16x16x32_bf16 v[18:21], v[160:163], v[204:207], v[18:21]
	s_barrier
	s_add_u32 s20, s20, 0x80080
	s_addc_u32 s21, s21, 0
	s_add_i32 s22, s22, s28
	v_lshl_add_u64 v[144:145], s[20:21], 0, v[134:135]
	s_mov_b32 m0, s22
	s_nop 0
	global_load_lds_dwordx4 v[144:145], off
	v_lshl_add_u64 v[144:145], s[20:21], 0, v[130:131]
	s_add_i32 m0, s22, 0x2000
	s_nop 0
	global_load_lds_dwordx4 v[144:145], off
	v_add_u32_e32 v152, 0x10000, v139
	ds_read_b128 v[144:147], v152
	ds_read_b128 v[148:151], v152 offset:1024
	ds_read_b128 v[156:159], v152 offset:2048
	ds_read_b128 v[160:163], v152 offset:3072
	s_waitcnt vmcnt(6)
	s_barrier
	v_mfma_f32_16x16x32_bf16 v[46:49], v[208:211], v[164:167], v[46:49]
	v_mfma_f32_16x16x32_bf16 v[42:45], v[228:231], v[164:167], v[42:45]
	v_mfma_f32_16x16x32_bf16 v[30:33], v[208:211], v[172:175], v[30:33]
	v_mfma_f32_16x16x32_bf16 v[26:29], v[228:231], v[172:175], v[26:29]
	v_mfma_f32_16x16x32_bf16 v[14:17], v[208:211], v[192:195], v[14:17]
	v_mfma_f32_16x16x32_bf16 v[10:13], v[228:231], v[192:195], v[10:13]
	v_mfma_f32_16x16x32_bf16 v[6:9], v[208:211], v[200:203], v[6:9]
	v_mfma_f32_16x16x32_bf16 v[2:5], v[228:231], v[200:203], v[2:5]
	v_mfma_f32_16x16x32_bf16 v[46:49], v[224:227], v[168:171], v[46:49]
	v_mfma_f32_16x16x32_bf16 v[42:45], v[232:235], v[168:171], v[42:45]
	v_mfma_f32_16x16x32_bf16 v[30:33], v[224:227], v[176:179], v[30:33]
	v_mfma_f32_16x16x32_bf16 v[26:29], v[232:235], v[176:179], v[26:29]
	v_mfma_f32_16x16x32_bf16 v[14:17], v[224:227], v[196:199], v[14:17]
	v_mfma_f32_16x16x32_bf16 v[10:13], v[232:235], v[196:199], v[10:13]
	v_mfma_f32_16x16x32_bf16 v[6:9], v[224:227], v[204:207], v[6:9]
	v_mfma_f32_16x16x32_bf16 v[2:5], v[232:235], v[204:207], v[2:5]
	s_add_i32 s55, s55, 2
	s_add_u32 s18, s18, 0x100
	s_addc_u32 s19, s19, 0
	s_add_u32 s53, s53, 0x100
	s_addc_u32 s54, s54, 0
	s_cmp_gt_u32 s55, 29
	s_barrier
	s_cbranch_scc0 .LBB0_526
	s_waitcnt lgkmcnt(0)
	v_lshl_add_u32 v152, s36, 8, v1
	v_or_b32_e32 v150, 16, v152
	v_or_b32_e32 v148, 32, v152
	v_or_b32_e32 v146, 48, v152
	s_mov_b64 s[18:19], -1
	s_cmp_lt_i32 s50, 8
	v_ashrrev_i32_e32 v153, 31, v152
	v_lshlrev_b32_e32 v144, 1, v138
	v_ashrrev_i32_e32 v151, 31, v150
	v_ashrrev_i32_e32 v149, 31, v148
	v_ashrrev_i32_e32 v147, 31, v146
	s_cbranch_scc1 .LBB0_529
	s_lshl_b32 s18, s50, 7
	s_add_i32 s36, s18, 0xfffffc00
	v_lshlrev_b64 v[156:157], 12, v[152:153]
	v_lshl_add_u64 v[156:157], s[72:73], 0, v[156:157]
	s_lshl_b64 s[18:19], s[36:37], 1
	v_lshl_add_u64 v[156:157], v[156:157], 0, s[18:19]
	v_mov_b32_e32 v145, v0
	v_lshl_add_u64 v[160:161], v[156:157], 0, v[144:145]
	v_pk_mul_f32 v[158:159], v[128:129], v[112:113]
	v_pk_mul_f32 v[156:157], v[126:127], v[110:111]
	v_pk_mul_f32 v[162:163], v[124:125], v[108:109]
	v_pk_mul_f32 v[164:165], v[122:123], v[106:107]
	v_cvt_pk_bf16_f32 v156, v156, v157
	v_cvt_pk_bf16_f32 v157, v158, v159
	v_cvt_pk_bf16_f32 v158, v164, v165
	v_cvt_pk_bf16_f32 v159, v162, v163
	global_store_dwordx4 v[160:161], v[156:159], off
	v_pk_mul_f32 v[164:165], v[116:117], v[92:93]
	v_pk_mul_f32 v[166:167], v[114:115], v[90:91]
	v_lshlrev_b64 v[156:157], 12, v[150:151]
	v_lshl_add_u64 v[156:157], s[72:73], 0, v[156:157]
	v_lshl_add_u64 v[156:157], v[156:157], 0, s[18:19]
	v_lshl_add_u64 v[162:163], v[156:157], 0, v[144:145]
	v_pk_mul_f32 v[158:159], v[120:121], v[96:97]
	v_pk_mul_f32 v[156:157], v[118:119], v[94:95]
	s_nop 0
	v_cvt_pk_bf16_f32 v156, v156, v157
	v_cvt_pk_bf16_f32 v157, v158, v159
	v_cvt_pk_bf16_f32 v158, v166, v167
	v_cvt_pk_bf16_f32 v159, v164, v165
	global_store_dwordx4 v[162:163], v[156:159], off
	v_pk_mul_f32 v[164:165], v[100:101], v[76:77]
	v_pk_mul_f32 v[166:167], v[98:99], v[74:75]
	v_lshlrev_b64 v[156:157], 12, v[148:149]
	v_lshl_add_u64 v[156:157], s[72:73], 0, v[156:157]
	v_lshl_add_u64 v[156:157], v[156:157], 0, s[18:19]
	v_lshl_add_u64 v[162:163], v[156:157], 0, v[144:145]
	v_pk_mul_f32 v[158:159], v[104:105], v[80:81]
	v_pk_mul_f32 v[156:157], v[102:103], v[78:79]
	s_nop 0
	v_cvt_pk_bf16_f32 v156, v156, v157
	v_cvt_pk_bf16_f32 v157, v158, v159
	v_cvt_pk_bf16_f32 v158, v166, v167
	v_cvt_pk_bf16_f32 v159, v164, v165
	global_store_dwordx4 v[162:163], v[156:159], off
	v_pk_mul_f32 v[164:165], v[84:85], v[68:69]
	v_pk_mul_f32 v[166:167], v[82:83], v[66:67]
	v_lshlrev_b64 v[156:157], 12, v[146:147]
	v_lshl_add_u64 v[156:157], s[72:73], 0, v[156:157]
	v_lshl_add_u64 v[156:157], v[156:157], 0, s[18:19]
	v_lshl_add_u64 v[162:163], v[156:157], 0, v[144:145]
	v_pk_mul_f32 v[158:159], v[88:89], v[72:73]
	v_pk_mul_f32 v[156:157], v[86:87], v[70:71]
	s_mov_b32 s18, 0x80000
	v_cvt_pk_bf16_f32 v156, v156, v157
	v_cvt_pk_bf16_f32 v157, v158, v159
	v_cvt_pk_bf16_f32 v158, v166, v167
	v_cvt_pk_bf16_f32 v159, v164, v165
	global_store_dwordx4 v[162:163], v[156:159], off
	v_pk_mul_f32 v[162:163], v[60:61], v[44:45]
	v_pk_mul_f32 v[164:165], v[58:59], v[42:43]
	v_pk_mul_f32 v[158:159], v[64:65], v[48:49]
	v_pk_mul_f32 v[156:157], v[62:63], v[46:47]
	s_nop 0
	v_cvt_pk_bf16_f32 v156, v156, v157
	v_cvt_pk_bf16_f32 v157, v158, v159
	v_cvt_pk_bf16_f32 v159, v162, v163
	v_add_co_u32_e32 v162, vcc, s18, v160
	v_cvt_pk_bf16_f32 v158, v164, v165
	s_nop 0
	v_addc_co_u32_e32 v163, vcc, 0, v161, vcc
	global_store_dwordx4 v[162:163], v[156:159], off
	v_pk_mul_f32 v[162:163], v[52:53], v[28:29]
	s_mov_b32 s18, 0x90000
	v_pk_mul_f32 v[158:159], v[56:57], v[32:33]
	v_pk_mul_f32 v[156:157], v[54:55], v[30:31]
	v_pk_mul_f32 v[164:165], v[50:51], v[26:27]
	v_cvt_pk_bf16_f32 v156, v156, v157
	v_cvt_pk_bf16_f32 v157, v158, v159
	v_cvt_pk_bf16_f32 v159, v162, v163
	v_add_co_u32_e32 v162, vcc, s18, v160
	v_cvt_pk_bf16_f32 v158, v164, v165
	s_nop 0
	v_addc_co_u32_e32 v163, vcc, 0, v161, vcc
	global_store_dwordx4 v[162:163], v[156:159], off
	v_pk_mul_f32 v[162:163], v[36:37], v[12:13]
	s_mov_b32 s18, 0xa0000
	v_pk_mul_f32 v[158:159], v[40:41], v[16:17]
	v_pk_mul_f32 v[156:157], v[38:39], v[14:15]
	v_pk_mul_f32 v[164:165], v[34:35], v[10:11]
	v_cvt_pk_bf16_f32 v156, v156, v157
	v_cvt_pk_bf16_f32 v157, v158, v159
	v_cvt_pk_bf16_f32 v159, v162, v163
	v_add_co_u32_e32 v162, vcc, s18, v160
	v_cvt_pk_bf16_f32 v158, v164, v165
	s_nop 0
	v_addc_co_u32_e32 v163, vcc, 0, v161, vcc
	global_store_dwordx4 v[162:163], v[156:159], off
	v_pk_mul_f32 v[162:163], v[20:21], v[4:5]
	v_pk_mul_f32 v[164:165], v[18:19], v[2:3]
	v_pk_mul_f32 v[158:159], v[24:25], v[8:9]
	v_pk_mul_f32 v[156:157], v[22:23], v[6:7]
	v_add_co_u32_e32 v160, vcc, 0xb0000, v160
	v_cvt_pk_bf16_f32 v156, v156, v157
	v_cvt_pk_bf16_f32 v157, v158, v159
	v_cvt_pk_bf16_f32 v158, v164, v165
	v_cvt_pk_bf16_f32 v159, v162, v163
	v_addc_co_u32_e32 v161, vcc, 0, v161, vcc
	s_mov_b64 s[18:19], 0
	global_store_dwordx4 v[160:161], v[156:159], off

.LBB0_649:
	s_add_u32 s18, s38, vcc_lo
	s_addc_u32 s19, s39, vcc_hi
	s_add_u32 s18, s18, 0x100
	s_addc_u32 s19, s19, 0
	s_add_u32 s57, s50, vcc_lo
	s_addc_u32 s58, s51, vcc_hi
	s_add_i32 s59, 0, 0x10000
	s_cmpk_eq_i32 vcc_lo, 0xf00
	s_cselect_b32 s23, s52, s19
	s_cselect_b32 s22, s53, s18
	s_cselect_b32 s19, s54, s58
	s_cselect_b32 s18, s55, s57
	v_lshl_add_u64 v[162:163], v[142:143], 0, vcc
	s_add_i32 m0, s28, 0xc000
	ds_read_b128 v[170:173], v148
	ds_read_b128 v[174:177], v148 offset:1024
	ds_read_b128 v[192:195], v148 offset:2048
	ds_read_b128 v[196:199], v148 offset:3072
	ds_read_b128 v[200:203], v148 offset:4096
	ds_read_b128 v[204:207], v148 offset:5120
	ds_read_b128 v[208:211], v148 offset:6144
	ds_read_b128 v[224:227], v148 offset:7168
	global_load_lds_dwordx4 v[162:163], off
	v_lshl_add_u64 v[162:163], v[144:145], 0, vcc
	s_add_i32 m0, s28, 0xe000
	s_nop 0
	global_load_lds_dwordx4 v[162:163], off
	s_waitcnt lgkmcnt(8)
	s_barrier
	s_waitcnt lgkmcnt(0)
	s_waitcnt lgkmcnt(0)
	v_mfma_f32_16x16x32_bf16 v[90:93], v[150:153], v[170:173], v[90:93]
	v_mfma_f32_16x16x32_bf16 v[94:97], v[158:161], v[170:173], v[94:97]
	v_mfma_f32_16x16x32_bf16 v[102:105], v[150:153], v[192:195], v[102:105]
	v_mfma_f32_16x16x32_bf16 v[106:109], v[158:161], v[192:195], v[106:109]
	v_mfma_f32_16x16x32_bf16 v[114:117], v[150:153], v[200:203], v[114:117]
	v_mfma_f32_16x16x32_bf16 v[118:121], v[158:161], v[200:203], v[118:121]
	v_mfma_f32_16x16x32_bf16 v[122:125], v[150:153], v[208:211], v[122:125]
	v_mfma_f32_16x16x32_bf16 v[126:129], v[158:161], v[208:211], v[126:129]
	v_mfma_f32_16x16x32_bf16 v[90:93], v[154:157], v[174:177], v[90:93]
	v_mfma_f32_16x16x32_bf16 v[94:97], v[166:169], v[174:177], v[94:97]
	v_mfma_f32_16x16x32_bf16 v[102:105], v[154:157], v[196:199], v[102:105]
	v_mfma_f32_16x16x32_bf16 v[106:109], v[166:169], v[196:199], v[106:109]
	v_mfma_f32_16x16x32_bf16 v[114:117], v[154:157], v[204:207], v[114:117]
	v_mfma_f32_16x16x32_bf16 v[118:121], v[166:169], v[204:207], v[118:121]
	v_mfma_f32_16x16x32_bf16 v[122:125], v[154:157], v[224:227], v[122:125]
	v_mfma_f32_16x16x32_bf16 v[126:129], v[166:169], v[224:227], v[126:129]
	s_barrier
	s_add_i32 s57, 0, 0x14000
	s_add_i32 s58, s59, s85
	v_add_u32_e32 v149, s57, v147
	v_lshl_add_u64 v[162:163], s[18:19], 0, v[134:135]
	s_mov_b32 m0, s58
	ds_read_b128 v[228:231], v149
	ds_read_b128 v[232:235], v149 offset:1024
	ds_read_b128 v[236:239], v149 offset:2048
	ds_read_b128 v[240:243], v149 offset:3072
	global_load_lds_dwordx4 v[162:163], off
	v_lshl_add_u64 v[178:179], s[18:19], 0, v[130:131]
	s_add_i32 m0, s58, 0x2000
	s_nop 0
	global_load_lds_dwordx4 v[178:179], off
	s_barrier
	s_waitcnt lgkmcnt(0)
	s_waitcnt lgkmcnt(0)
	v_mfma_f32_16x16x32_bf16 v[10:13], v[228:231], v[170:173], v[10:13]
	v_mfma_f32_16x16x32_bf16 v[14:17], v[236:239], v[170:173], v[14:17]
	v_mfma_f32_16x16x32_bf16 v[26:29], v[228:231], v[192:195], v[26:29]
	v_mfma_f32_16x16x32_bf16 v[38:41], v[236:239], v[192:195], v[38:41]
	v_mfma_f32_16x16x32_bf16 v[58:61], v[228:231], v[200:203], v[58:61]
	v_mfma_f32_16x16x32_bf16 v[62:65], v[236:239], v[200:203], v[62:65]
	v_mfma_f32_16x16x32_bf16 v[74:77], v[228:231], v[208:211], v[74:77]
	v_mfma_f32_16x16x32_bf16 v[78:81], v[236:239], v[208:211], v[78:81]
	v_mfma_f32_16x16x32_bf16 v[10:13], v[232:235], v[174:177], v[10:13]
	v_mfma_f32_16x16x32_bf16 v[14:17], v[240:243], v[174:177], v[14:17]
	v_mfma_f32_16x16x32_bf16 v[26:29], v[232:235], v[196:199], v[26:29]
	v_mfma_f32_16x16x32_bf16 v[38:41], v[240:243], v[196:199], v[38:41]
	v_mfma_f32_16x16x32_bf16 v[58:61], v[232:235], v[204:207], v[58:61]
	v_mfma_f32_16x16x32_bf16 v[62:65], v[240:243], v[204:207], v[62:65]
	v_mfma_f32_16x16x32_bf16 v[74:77], v[232:235], v[224:227], v[74:77]
	v_mfma_f32_16x16x32_bf16 v[78:81], v[240:243], v[224:227], v[78:81]
	s_mov_b32 m0, s28
	v_lshl_add_u64 v[212:213], s[22:23], 0, v[136:137]
	s_barrier
	ds_read_b128 v[170:173], v148 offset:16384
	ds_read_b128 v[174:177], v148 offset:17408
	ds_read_b128 v[192:195], v148 offset:18432
	ds_read_b128 v[196:199], v148 offset:19456
	ds_read_b128 v[200:203], v148 offset:20480
	ds_read_b128 v[204:207], v148 offset:21504
	ds_read_b128 v[208:211], v148 offset:22528
	ds_read_b128 v[224:227], v148 offset:23552
	global_load_lds_dwordx4 v[212:213], off
	v_lshl_add_u64 v[244:245], s[22:23], 0, v[132:133]
	s_mov_b32 m0, s29
	s_nop 0
	global_load_lds_dwordx4 v[244:245], off
	s_waitcnt vmcnt(10)
	s_barrier
	s_waitcnt lgkmcnt(0)
	s_waitcnt lgkmcnt(0)
	v_mfma_f32_16x16x32_bf16 v[110:113], v[150:153], v[170:173], v[110:113]
	v_mfma_f32_16x16x32_bf16 v[98:101], v[158:161], v[170:173], v[98:101]
	v_mfma_f32_16x16x32_bf16 v[82:85], v[150:153], v[192:195], v[82:85]
	v_mfma_f32_16x16x32_bf16 v[66:69], v[158:161], v[192:195], v[66:69]
	v_mfma_f32_16x16x32_bf16 v[50:53], v[150:153], v[200:203], v[50:53]
	v_mfma_f32_16x16x32_bf16 v[42:45], v[158:161], v[200:203], v[42:45]
	v_mfma_f32_16x16x32_bf16 v[30:33], v[150:153], v[208:211], v[30:33]
	v_mfma_f32_16x16x32_bf16 v[18:21], v[158:161], v[208:211], v[18:21]
	v_mfma_f32_16x16x32_bf16 v[110:113], v[154:157], v[174:177], v[110:113]
	v_mfma_f32_16x16x32_bf16 v[98:101], v[166:169], v[174:177], v[98:101]
	v_mfma_f32_16x16x32_bf16 v[82:85], v[154:157], v[196:199], v[82:85]
	v_mfma_f32_16x16x32_bf16 v[66:69], v[166:169], v[196:199], v[66:69]
	v_mfma_f32_16x16x32_bf16 v[50:53], v[154:157], v[204:207], v[50:53]
	v_mfma_f32_16x16x32_bf16 v[42:45], v[166:169], v[204:207], v[42:45]
	v_mfma_f32_16x16x32_bf16 v[30:33], v[154:157], v[224:227], v[30:33]
	v_mfma_f32_16x16x32_bf16 v[18:21], v[166:169], v[224:227], v[18:21]
	s_barrier
	s_add_u32 s58, s18, 0x80000
	s_addc_u32 s59, s19, 0
	s_add_i32 s57, s57, s85
	v_lshl_add_u64 v[150:151], s[58:59], 0, v[134:135]
	s_mov_b32 m0, s57
	s_nop 0
	global_load_lds_dwordx4 v[150:151], off
	v_lshl_add_u64 v[150:151], s[58:59], 0, v[130:131]
	s_add_i32 m0, s57, 0x2000
	s_nop 0
	global_load_lds_dwordx4 v[150:151], off
	v_add_u32_e32 v149, 0x18000, v147
	ds_read_b128 v[150:153], v149
	ds_read_b128 v[154:157], v149 offset:1024
	ds_read_b128 v[158:161], v149 offset:2048
	ds_read_b128 v[166:169], v149 offset:3072
	s_waitcnt vmcnt(6)
	s_barrier
	v_mfma_f32_16x16x32_bf16 v[86:89], v[228:231], v[170:173], v[86:89]
	v_mfma_f32_16x16x32_bf16 v[70:73], v[236:239], v[170:173], v[70:73]
	v_mfma_f32_16x16x32_bf16 v[54:57], v[228:231], v[192:195], v[54:57]
	v_mfma_f32_16x16x32_bf16 v[46:49], v[236:239], v[192:195], v[46:49]
	v_mfma_f32_16x16x32_bf16 v[34:37], v[228:231], v[200:203], v[34:37]
	v_mfma_f32_16x16x32_bf16 v[22:25], v[236:239], v[200:203], v[22:25]
	v_mfma_f32_16x16x32_bf16 v[6:9], v[228:231], v[208:211], v[6:9]
	v_mfma_f32_16x16x32_bf16 v[2:5], v[236:239], v[208:211], v[2:5]
	v_mfma_f32_16x16x32_bf16 v[86:89], v[232:235], v[174:177], v[86:89]
	v_mfma_f32_16x16x32_bf16 v[70:73], v[240:243], v[174:177], v[70:73]
	v_mfma_f32_16x16x32_bf16 v[54:57], v[232:235], v[196:199], v[54:57]
	v_mfma_f32_16x16x32_bf16 v[46:49], v[240:243], v[196:199], v[46:49]
	v_mfma_f32_16x16x32_bf16 v[34:37], v[232:235], v[204:207], v[34:37]
	v_mfma_f32_16x16x32_bf16 v[22:25], v[240:243], v[204:207], v[22:25]
	v_mfma_f32_16x16x32_bf16 v[6:9], v[232:235], v[224:227], v[6:9]
	v_mfma_f32_16x16x32_bf16 v[2:5], v[240:243], v[224:227], v[2:5]
	s_add_i32 s57, 0, 0x18000
	s_barrier
	s_add_u32 s22, s22, 0x80000
	s_addc_u32 s23, s23, 0
	s_mov_b32 m0, s97
	v_lshl_add_u64 v[228:229], s[22:23], 0, v[136:137]
	ds_read_b128 v[170:173], v148 offset:32768
	ds_read_b128 v[174:177], v148 offset:33792
	ds_read_b128 v[192:195], v148 offset:34816
	ds_read_b128 v[196:199], v148 offset:35840
	ds_read_b128 v[200:203], v148 offset:36864
	ds_read_b128 v[204:207], v148 offset:37888
	ds_read_b128 v[208:211], v148 offset:38912
	ds_read_b128 v[224:227], v148 offset:39936
	global_load_lds_dwordx4 v[228:229], off
	v_lshl_add_u64 v[228:229], s[22:23], 0, v[132:133]
	s_mov_b32 m0, s44
	s_nop 0
	global_load_lds_dwordx4 v[228:229], off
	s_waitcnt lgkmcnt(8)
	s_barrier
	s_waitcnt lgkmcnt(0)
	s_waitcnt lgkmcnt(0)
	v_mfma_f32_16x16x32_bf16 v[90:93], v[150:153], v[170:173], v[90:93]
	v_mfma_f32_16x16x32_bf16 v[94:97], v[158:161], v[170:173], v[94:97]
	v_mfma_f32_16x16x32_bf16 v[102:105], v[150:153], v[192:195], v[102:105]
	v_mfma_f32_16x16x32_bf16 v[106:109], v[158:161], v[192:195], v[106:109]
	v_mfma_f32_16x16x32_bf16 v[114:117], v[150:153], v[200:203], v[114:117]
	v_mfma_f32_16x16x32_bf16 v[118:121], v[158:161], v[200:203], v[118:121]
	v_mfma_f32_16x16x32_bf16 v[122:125], v[150:153], v[208:211], v[122:125]
	v_mfma_f32_16x16x32_bf16 v[126:129], v[158:161], v[208:211], v[126:129]
	v_mfma_f32_16x16x32_bf16 v[90:93], v[154:157], v[174:177], v[90:93]
	v_mfma_f32_16x16x32_bf16 v[94:97], v[166:169], v[174:177], v[94:97]
	v_mfma_f32_16x16x32_bf16 v[102:105], v[154:157], v[196:199], v[102:105]
	v_mfma_f32_16x16x32_bf16 v[106:109], v[166:169], v[196:199], v[106:109]
	v_mfma_f32_16x16x32_bf16 v[114:117], v[154:157], v[204:207], v[114:117]
	v_mfma_f32_16x16x32_bf16 v[118:121], v[166:169], v[204:207], v[118:121]
	v_mfma_f32_16x16x32_bf16 v[122:125], v[154:157], v[224:227], v[122:125]
	v_mfma_f32_16x16x32_bf16 v[126:129], v[166:169], v[224:227], v[126:129]
	s_barrier
	s_add_i32 s22, 0, 0x1c000
	s_add_i32 s23, s57, s85
	v_add_u32_e32 v149, s22, v147
	v_lshl_add_u64 v[162:163], v[162:163], 0, s[78:79]
	s_mov_b32 m0, s23
	ds_read_b128 v[228:231], v149
	ds_read_b128 v[232:235], v149 offset:1024
	ds_read_b128 v[236:239], v149 offset:2048
	ds_read_b128 v[240:243], v149 offset:3072
	global_load_lds_dwordx4 v[162:163], off
	v_lshl_add_u64 v[162:163], v[178:179], 0, s[78:79]
	s_add_i32 m0, s23, 0x2000
	s_nop 0
	global_load_lds_dwordx4 v[162:163], off
	s_barrier
	s_waitcnt lgkmcnt(0)
	s_waitcnt lgkmcnt(0)
	v_mfma_f32_16x16x32_bf16 v[10:13], v[228:231], v[170:173], v[10:13]
	v_mfma_f32_16x16x32_bf16 v[14:17], v[236:239], v[170:173], v[14:17]
	v_mfma_f32_16x16x32_bf16 v[26:29], v[228:231], v[192:195], v[26:29]
	v_mfma_f32_16x16x32_bf16 v[38:41], v[236:239], v[192:195], v[38:41]
	v_mfma_f32_16x16x32_bf16 v[58:61], v[228:231], v[200:203], v[58:61]
	v_mfma_f32_16x16x32_bf16 v[62:65], v[236:239], v[200:203], v[62:65]
	v_mfma_f32_16x16x32_bf16 v[74:77], v[228:231], v[208:211], v[74:77]
	v_mfma_f32_16x16x32_bf16 v[78:81], v[236:239], v[208:211], v[78:81]
	v_mfma_f32_16x16x32_bf16 v[10:13], v[232:235], v[174:177], v[10:13]
	v_mfma_f32_16x16x32_bf16 v[14:17], v[240:243], v[174:177], v[14:17]
	v_mfma_f32_16x16x32_bf16 v[26:29], v[232:235], v[196:199], v[26:29]
	v_mfma_f32_16x16x32_bf16 v[38:41], v[240:243], v[196:199], v[38:41]
	v_mfma_f32_16x16x32_bf16 v[58:61], v[232:235], v[204:207], v[58:61]
	v_mfma_f32_16x16x32_bf16 v[62:65], v[240:243], v[204:207], v[62:65]
	v_mfma_f32_16x16x32_bf16 v[74:77], v[232:235], v[224:227], v[74:77]
	v_mfma_f32_16x16x32_bf16 v[78:81], v[240:243], v[224:227], v[78:81]
	s_mov_b32 m0, s46
	v_lshl_add_u64 v[162:163], v[212:213], 0, s[78:79]
	s_barrier
	ds_read_b128 v[170:173], v148 offset:49152
	ds_read_b128 v[174:177], v148 offset:50176
	ds_read_b128 v[192:195], v148 offset:51200
	ds_read_b128 v[196:199], v148 offset:52224
	ds_read_b128 v[200:203], v148 offset:53248
	ds_read_b128 v[204:207], v148 offset:54272
	ds_read_b128 v[208:211], v148 offset:55296
	ds_read_b128 v[224:227], v148 offset:56320
	global_load_lds_dwordx4 v[162:163], off
	v_lshl_add_u64 v[162:163], v[244:245], 0, s[78:79]
	s_mov_b32 m0, s47
	s_nop 0
	global_load_lds_dwordx4 v[162:163], off
	s_waitcnt vmcnt(10)
	s_barrier
	s_waitcnt lgkmcnt(0)
	s_waitcnt lgkmcnt(0)
	v_mfma_f32_16x16x32_bf16 v[110:113], v[150:153], v[170:173], v[110:113]
	v_mfma_f32_16x16x32_bf16 v[98:101], v[158:161], v[170:173], v[98:101]
	v_mfma_f32_16x16x32_bf16 v[82:85], v[150:153], v[192:195], v[82:85]
	v_mfma_f32_16x16x32_bf16 v[66:69], v[158:161], v[192:195], v[66:69]
	v_mfma_f32_16x16x32_bf16 v[50:53], v[150:153], v[200:203], v[50:53]
	v_mfma_f32_16x16x32_bf16 v[42:45], v[158:161], v[200:203], v[42:45]
	v_mfma_f32_16x16x32_bf16 v[30:33], v[150:153], v[208:211], v[30:33]
	v_mfma_f32_16x16x32_bf16 v[18:21], v[158:161], v[208:211], v[18:21]
	v_mfma_f32_16x16x32_bf16 v[110:113], v[154:157], v[174:177], v[110:113]
	v_mfma_f32_16x16x32_bf16 v[98:101], v[166:169], v[174:177], v[98:101]
	v_mfma_f32_16x16x32_bf16 v[82:85], v[154:157], v[196:199], v[82:85]
	v_mfma_f32_16x16x32_bf16 v[66:69], v[166:169], v[196:199], v[66:69]
	v_mfma_f32_16x16x32_bf16 v[50:53], v[154:157], v[204:207], v[50:53]
	v_mfma_f32_16x16x32_bf16 v[42:45], v[166:169], v[204:207], v[42:45]
	v_mfma_f32_16x16x32_bf16 v[30:33], v[154:157], v[224:227], v[30:33]
	v_mfma_f32_16x16x32_bf16 v[18:21], v[166:169], v[224:227], v[18:21]
	s_barrier
	s_add_u32 s18, s18, 0x80080
	s_addc_u32 s19, s19, 0
	s_add_i32 s22, s22, s85
	v_lshl_add_u64 v[150:151], s[18:19], 0, v[134:135]
	s_mov_b32 m0, s22
	s_nop 0
	global_load_lds_dwordx4 v[150:151], off
	v_lshl_add_u64 v[150:151], s[18:19], 0, v[130:131]
	s_add_i32 m0, s22, 0x2000
	s_nop 0
	global_load_lds_dwordx4 v[150:151], off
	v_add_u32_e32 v149, 0x10000, v147
	ds_read_b128 v[150:153], v149
	ds_read_b128 v[154:157], v149 offset:1024
	ds_read_b128 v[158:161], v149 offset:2048
	ds_read_b128 v[166:169], v149 offset:3072
	s_waitcnt vmcnt(6)
	s_barrier
	v_mfma_f32_16x16x32_bf16 v[86:89], v[228:231], v[170:173], v[86:89]
	v_mfma_f32_16x16x32_bf16 v[70:73], v[236:239], v[170:173], v[70:73]
	v_mfma_f32_16x16x32_bf16 v[54:57], v[228:231], v[192:195], v[54:57]
	v_mfma_f32_16x16x32_bf16 v[46:49], v[236:239], v[192:195], v[46:49]
	v_mfma_f32_16x16x32_bf16 v[34:37], v[228:231], v[200:203], v[34:37]
	v_mfma_f32_16x16x32_bf16 v[22:25], v[236:239], v[200:203], v[22:25]
	v_mfma_f32_16x16x32_bf16 v[6:9], v[228:231], v[208:211], v[6:9]
	v_mfma_f32_16x16x32_bf16 v[2:5], v[236:239], v[208:211], v[2:5]
	v_mfma_f32_16x16x32_bf16 v[86:89], v[232:235], v[174:177], v[86:89]
	v_mfma_f32_16x16x32_bf16 v[70:73], v[240:243], v[174:177], v[70:73]
	v_mfma_f32_16x16x32_bf16 v[54:57], v[232:235], v[196:199], v[54:57]
	v_mfma_f32_16x16x32_bf16 v[46:49], v[240:243], v[196:199], v[46:49]
	v_mfma_f32_16x16x32_bf16 v[34:37], v[232:235], v[204:207], v[34:37]
	v_mfma_f32_16x16x32_bf16 v[22:25], v[240:243], v[204:207], v[22:25]
	v_mfma_f32_16x16x32_bf16 v[6:9], v[232:235], v[224:227], v[6:9]
	v_mfma_f32_16x16x32_bf16 v[2:5], v[240:243], v[224:227], v[2:5]
	s_add_i32 s56, s56, 2
	s_add_u32 vcc_lo, vcc_lo, 0x100
	s_addc_u32 vcc_hi, vcc_hi, 0
	s_cmp_gt_u32 s56, 29
	s_barrier
	s_cbranch_scc0 .LBB0_649
	s_waitcnt lgkmcnt(0)
	s_add_u32 s18, s50, 0xffffff00
	s_addc_u32 s19, s51, -1
	s_andn2_b64 vcc, exec, s[42:43]
	s_cbranch_vccnz .LBB0_652
	v_mov_b32_e32 v2, 0
	s_mov_b32 s84, s80
	s_mov_b32 s25, s82
	s_mov_b64 s[38:39], s[20:21]
	s_mov_b32 s48, s49
	v_mov_b32_e32 v3, v2
	v_mov_b32_e32 v4, v2
	v_mov_b32_e32 v5, v2
	v_mov_b32_e32 v6, v2
	v_mov_b32_e32 v7, v2
	v_mov_b32_e32 v8, v2
	v_mov_b32_e32 v9, v2
	v_mov_b32_e32 v22, v2
	v_mov_b32_e32 v23, v2
	v_mov_b32_e32 v24, v2
	v_mov_b32_e32 v25, v2
	v_mov_b32_e32 v34, v2
	v_mov_b32_e32 v35, v2
	v_mov_b32_e32 v36, v2
	v_mov_b32_e32 v37, v2
	v_mov_b32_e32 v46, v2
	v_mov_b32_e32 v47, v2
	v_mov_b32_e32 v48, v2
	v_mov_b32_e32 v49, v2
	v_mov_b32_e32 v54, v2
	v_mov_b32_e32 v55, v2
	v_mov_b32_e32 v56, v2
	v_mov_b32_e32 v57, v2
	v_mov_b32_e32 v70, v2
	v_mov_b32_e32 v71, v2
	v_mov_b32_e32 v72, v2
	v_mov_b32_e32 v73, v2
	v_mov_b32_e32 v86, v2
	v_mov_b32_e32 v87, v2
	v_mov_b32_e32 v88, v2
	v_mov_b32_e32 v89, v2
	v_mov_b32_e32 v18, v2
	v_mov_b32_e32 v19, v2
	v_mov_b32_e32 v20, v2
	v_mov_b32_e32 v21, v2
	v_mov_b32_e32 v30, v2
	v_mov_b32_e32 v31, v2
	v_mov_b32_e32 v32, v2
	v_mov_b32_e32 v33, v2
	v_mov_b32_e32 v42, v2
	v_mov_b32_e32 v43, v2
	v_mov_b32_e32 v44, v2
	v_mov_b32_e32 v45, v2
	v_mov_b32_e32 v50, v2
	v_mov_b32_e32 v51, v2
	v_mov_b32_e32 v52, v2
	v_mov_b32_e32 v53, v2
	v_mov_b32_e32 v66, v2
	v_mov_b32_e32 v67, v2
	v_mov_b32_e32 v68, v2
	v_mov_b32_e32 v69, v2
	v_mov_b32_e32 v82, v2
	v_mov_b32_e32 v83, v2
	v_mov_b32_e32 v84, v2
	v_mov_b32_e32 v85, v2
	v_mov_b32_e32 v98, v2
	v_mov_b32_e32 v99, v2
	v_mov_b32_e32 v100, v2
	v_mov_b32_e32 v101, v2
	v_mov_b32_e32 v110, v2
	v_mov_b32_e32 v111, v2
	v_mov_b32_e32 v112, v2
	v_mov_b32_e32 v113, v2
	v_mov_b32_e32 v78, v2
	v_mov_b32_e32 v79, v2
	v_mov_b32_e32 v80, v2
	v_mov_b32_e32 v81, v2
	v_mov_b32_e32 v74, v2
	v_mov_b32_e32 v75, v2
	v_mov_b32_e32 v76, v2
	v_mov_b32_e32 v77, v2
	v_mov_b32_e32 v62, v2
	v_mov_b32_e32 v63, v2
	v_mov_b32_e32 v64, v2
	v_mov_b32_e32 v65, v2
	v_mov_b32_e32 v58, v2
	v_mov_b32_e32 v59, v2
	v_mov_b32_e32 v60, v2
	v_mov_b32_e32 v61, v2
	v_mov_b32_e32 v38, v2
	v_mov_b32_e32 v39, v2
	v_mov_b32_e32 v40, v2
	v_mov_b32_e32 v41, v2
	v_mov_b32_e32 v26, v2
	v_mov_b32_e32 v27, v2
	v_mov_b32_e32 v28, v2
	v_mov_b32_e32 v29, v2
	v_mov_b32_e32 v14, v2
	v_mov_b32_e32 v15, v2
	v_mov_b32_e32 v16, v2
	v_mov_b32_e32 v17, v2
	v_mov_b32_e32 v10, v2
	v_mov_b32_e32 v11, v2
	v_mov_b32_e32 v12, v2
	v_mov_b32_e32 v13, v2
	v_mov_b32_e32 v126, v2
	v_mov_b32_e32 v127, v2
	v_mov_b32_e32 v128, v2
	v_mov_b32_e32 v129, v2
	v_mov_b32_e32 v122, v2
	v_mov_b32_e32 v123, v2
	v_mov_b32_e32 v124, v2
	v_mov_b32_e32 v125, v2
	v_mov_b32_e32 v118, v2
	v_mov_b32_e32 v119, v2
	v_mov_b32_e32 v120, v2
	v_mov_b32_e32 v121, v2
	v_mov_b32_e32 v114, v2
	v_mov_b32_e32 v115, v2
	v_mov_b32_e32 v116, v2
	v_mov_b32_e32 v117, v2
	v_mov_b32_e32 v106, v2
	v_mov_b32_e32 v107, v2
	v_mov_b32_e32 v108, v2
	v_mov_b32_e32 v109, v2
	v_mov_b32_e32 v102, v2
	v_mov_b32_e32 v103, v2
	v_mov_b32_e32 v104, v2
	v_mov_b32_e32 v105, v2
	v_mov_b32_e32 v94, v2
	v_mov_b32_e32 v95, v2
	v_mov_b32_e32 v96, v2
	v_mov_b32_e32 v97, v2
	v_mov_b32_e32 v90, v2
	v_mov_b32_e32 v91, v2
	v_mov_b32_e32 v92, v2
	v_mov_b32_e32 v93, v2
	s_andn2_b64 vcc, exec, s[0:1]
	s_cbranch_vccnz .LBB0_653
	s_branch .LBB0_654

.LBB0_749:
	s_add_u32 s20, s18, 0xfff80080
	s_addc_u32 s21, s19, -1
	s_add_i32 s58, 0, 0x10000
	s_cmp_eq_u32 s57, 28
	s_cselect_b32 s23, s39, s21
	s_cselect_b32 s22, s53, s20
	s_cselect_b32 s21, s31, s56
	s_cselect_b32 s20, s54, s55
	v_lshl_add_u64 v[212:213], s[18:19], 0, v[154:155]
	s_add_i32 m0, s44, 0xc000
	ds_read_b128 v[176:179], v158
	ds_read_b128 v[192:195], v158 offset:1024
	ds_read_b128 v[196:199], v158 offset:2048
	ds_read_b128 v[200:203], v158 offset:3072
	ds_read_b128 v[204:207], v158 offset:4096
	ds_read_b128 v[208:211], v158 offset:5120
	ds_read_b128 v[224:227], v158 offset:6144
	ds_read_b128 v[228:231], v158 offset:7168
	global_load_lds_dwordx4 v[212:213], off
	v_lshl_add_u64 v[212:213], s[18:19], 0, v[156:157]
	s_add_i32 m0, s44, 0xe000
	s_nop 0
	global_load_lds_dwordx4 v[212:213], off
	s_waitcnt lgkmcnt(8)
	s_barrier
	s_waitcnt lgkmcnt(0)
	s_waitcnt lgkmcnt(0)
	v_mfma_f32_16x16x32_bf16 v[126:129], v[160:163], v[176:179], v[126:129]
	v_mfma_f32_16x16x32_bf16 v[122:125], v[168:171], v[176:179], v[122:125]
	v_mfma_f32_16x16x32_bf16 v[110:113], v[160:163], v[196:199], v[110:113]
	v_mfma_f32_16x16x32_bf16 v[106:109], v[168:171], v[196:199], v[106:109]
	v_mfma_f32_16x16x32_bf16 v[94:97], v[160:163], v[204:207], v[94:97]
	v_mfma_f32_16x16x32_bf16 v[90:93], v[168:171], v[204:207], v[90:93]
	v_mfma_f32_16x16x32_bf16 v[78:81], v[160:163], v[224:227], v[78:81]
	v_mfma_f32_16x16x32_bf16 v[74:77], v[168:171], v[224:227], v[74:77]
	v_mfma_f32_16x16x32_bf16 v[126:129], v[164:167], v[192:195], v[126:129]
	v_mfma_f32_16x16x32_bf16 v[122:125], v[172:175], v[192:195], v[122:125]
	v_mfma_f32_16x16x32_bf16 v[110:113], v[164:167], v[200:203], v[110:113]
	v_mfma_f32_16x16x32_bf16 v[106:109], v[172:175], v[200:203], v[106:109]
	v_mfma_f32_16x16x32_bf16 v[94:97], v[164:167], v[208:211], v[94:97]
	v_mfma_f32_16x16x32_bf16 v[90:93], v[172:175], v[208:211], v[90:93]
	v_mfma_f32_16x16x32_bf16 v[78:81], v[164:167], v[228:231], v[78:81]
	v_mfma_f32_16x16x32_bf16 v[74:77], v[172:175], v[228:231], v[74:77]
	s_barrier
	s_add_i32 s82, 0, 0x14000
	s_add_i32 s58, s58, s29
	v_add_u32_e32 v159, s82, v1
	v_lshl_add_u64 v[212:213], s[20:21], 0, v[134:135]
	s_mov_b32 m0, s58
	ds_read_b128 v[232:235], v159
	ds_read_b128 v[236:239], v159 offset:1024
	ds_read_b128 v[240:243], v159 offset:2048
	ds_read_b128 v[244:247], v159 offset:3072
	global_load_lds_dwordx4 v[212:213], off
	v_lshl_add_u64 v[248:249], s[20:21], 0, v[130:131]
	s_add_i32 m0, s58, 0x2000
	s_nop 0
	global_load_lds_dwordx4 v[248:249], off
	s_barrier
	s_waitcnt lgkmcnt(0)
	s_waitcnt lgkmcnt(0)
	v_mfma_f32_16x16x32_bf16 v[118:121], v[232:235], v[176:179], v[118:121]
	v_mfma_f32_16x16x32_bf16 v[114:117], v[240:243], v[176:179], v[114:117]
	v_mfma_f32_16x16x32_bf16 v[102:105], v[232:235], v[196:199], v[102:105]
	v_mfma_f32_16x16x32_bf16 v[98:101], v[240:243], v[196:199], v[98:101]
	v_mfma_f32_16x16x32_bf16 v[86:89], v[232:235], v[204:207], v[86:89]
	v_mfma_f32_16x16x32_bf16 v[82:85], v[240:243], v[204:207], v[82:85]
	v_mfma_f32_16x16x32_bf16 v[70:73], v[232:235], v[224:227], v[70:73]
	v_mfma_f32_16x16x32_bf16 v[66:69], v[240:243], v[224:227], v[66:69]
	v_mfma_f32_16x16x32_bf16 v[118:121], v[236:239], v[192:195], v[118:121]
	v_mfma_f32_16x16x32_bf16 v[114:117], v[244:247], v[192:195], v[114:117]
	v_mfma_f32_16x16x32_bf16 v[102:105], v[236:239], v[200:203], v[102:105]
	v_mfma_f32_16x16x32_bf16 v[98:101], v[244:247], v[200:203], v[98:101]
	v_mfma_f32_16x16x32_bf16 v[86:89], v[236:239], v[208:211], v[86:89]
	v_mfma_f32_16x16x32_bf16 v[82:85], v[244:247], v[208:211], v[82:85]
	v_mfma_f32_16x16x32_bf16 v[70:73], v[236:239], v[228:231], v[70:73]
	v_mfma_f32_16x16x32_bf16 v[66:69], v[244:247], v[228:231], v[66:69]
	s_mov_b32 m0, s44
	v_lshl_add_u64 v[250:251], s[22:23], 0, v[136:137]
	s_barrier
	ds_read_b128 v[176:179], v158 offset:16384
	ds_read_b128 v[192:195], v158 offset:17408
	ds_read_b128 v[196:199], v158 offset:18432
	ds_read_b128 v[200:203], v158 offset:19456
	ds_read_b128 v[204:207], v158 offset:20480
	ds_read_b128 v[208:211], v158 offset:21504
	ds_read_b128 v[224:227], v158 offset:22528
	ds_read_b128 v[228:231], v158 offset:23552
	global_load_lds_dwordx4 v[250:251], off
	v_lshl_add_u64 v[222:223], s[22:23], 0, v[132:133]
	s_mov_b32 m0, s45
	s_nop 0
	global_load_lds_dwordx4 v[222:223], off
	s_waitcnt vmcnt(10)
	s_barrier
	s_waitcnt lgkmcnt(0)
	s_waitcnt lgkmcnt(0)
	v_mfma_f32_16x16x32_bf16 v[62:65], v[160:163], v[176:179], v[62:65]
	v_mfma_f32_16x16x32_bf16 v[58:61], v[168:171], v[176:179], v[58:61]
	v_mfma_f32_16x16x32_bf16 v[46:49], v[160:163], v[196:199], v[46:49]
	v_mfma_f32_16x16x32_bf16 v[42:45], v[168:171], v[196:199], v[42:45]
	v_mfma_f32_16x16x32_bf16 v[30:33], v[160:163], v[204:207], v[30:33]
	v_mfma_f32_16x16x32_bf16 v[26:29], v[168:171], v[204:207], v[26:29]
	v_mfma_f32_16x16x32_bf16 v[14:17], v[160:163], v[224:227], v[14:17]
	v_mfma_f32_16x16x32_bf16 v[10:13], v[168:171], v[224:227], v[10:13]
	v_mfma_f32_16x16x32_bf16 v[62:65], v[164:167], v[192:195], v[62:65]
	v_mfma_f32_16x16x32_bf16 v[58:61], v[172:175], v[192:195], v[58:61]
	v_mfma_f32_16x16x32_bf16 v[46:49], v[164:167], v[200:203], v[46:49]
	v_mfma_f32_16x16x32_bf16 v[42:45], v[172:175], v[200:203], v[42:45]
	v_mfma_f32_16x16x32_bf16 v[30:33], v[164:167], v[208:211], v[30:33]
	v_mfma_f32_16x16x32_bf16 v[26:29], v[172:175], v[208:211], v[26:29]
	v_mfma_f32_16x16x32_bf16 v[14:17], v[164:167], v[228:231], v[14:17]
	v_mfma_f32_16x16x32_bf16 v[10:13], v[172:175], v[228:231], v[10:13]
	s_barrier
	s_add_u32 s58, s20, 0x80000
	s_addc_u32 s59, s21, 0
	s_add_i32 s82, s82, s29
	v_lshl_add_u64 v[160:161], s[58:59], 0, v[134:135]
	s_mov_b32 m0, s82
	s_nop 0
	global_load_lds_dwordx4 v[160:161], off
	v_lshl_add_u64 v[160:161], s[58:59], 0, v[130:131]
	s_add_i32 m0, s82, 0x2000
	s_nop 0
	global_load_lds_dwordx4 v[160:161], off
	v_add_u32_e32 v159, 0x18000, v1
	ds_read_b128 v[160:163], v159
	ds_read_b128 v[164:167], v159 offset:1024
	ds_read_b128 v[168:171], v159 offset:2048
	ds_read_b128 v[172:175], v159 offset:3072
	s_waitcnt vmcnt(6)
	s_barrier
	v_mfma_f32_16x16x32_bf16 v[54:57], v[232:235], v[176:179], v[54:57]
	v_mfma_f32_16x16x32_bf16 v[50:53], v[240:243], v[176:179], v[50:53]
	v_mfma_f32_16x16x32_bf16 v[38:41], v[232:235], v[196:199], v[38:41]
	v_mfma_f32_16x16x32_bf16 v[34:37], v[240:243], v[196:199], v[34:37]
	v_mfma_f32_16x16x32_bf16 v[22:25], v[232:235], v[204:207], v[22:25]
	v_mfma_f32_16x16x32_bf16 v[18:21], v[240:243], v[204:207], v[18:21]
	v_mfma_f32_16x16x32_bf16 v[6:9], v[232:235], v[224:227], v[6:9]
	v_mfma_f32_16x16x32_bf16 v[2:5], v[240:243], v[224:227], v[2:5]
	v_mfma_f32_16x16x32_bf16 v[54:57], v[236:239], v[192:195], v[54:57]
	v_mfma_f32_16x16x32_bf16 v[50:53], v[244:247], v[192:195], v[50:53]
	v_mfma_f32_16x16x32_bf16 v[38:41], v[236:239], v[200:203], v[38:41]
	v_mfma_f32_16x16x32_bf16 v[34:37], v[244:247], v[200:203], v[34:37]
	v_mfma_f32_16x16x32_bf16 v[22:25], v[236:239], v[208:211], v[22:25]
	v_mfma_f32_16x16x32_bf16 v[18:21], v[244:247], v[208:211], v[18:21]
	v_mfma_f32_16x16x32_bf16 v[6:9], v[236:239], v[228:231], v[6:9]
	v_mfma_f32_16x16x32_bf16 v[2:5], v[244:247], v[228:231], v[2:5]
	s_add_i32 s58, 0, 0x18000
	s_barrier
	s_add_u32 s22, s22, 0x80000
	s_addc_u32 s23, s23, 0
	s_mov_b32 m0, s46
	v_lshl_add_u64 v[232:233], s[22:23], 0, v[136:137]
	ds_read_b128 v[176:179], v158 offset:32768
	ds_read_b128 v[192:195], v158 offset:33792
	ds_read_b128 v[196:199], v158 offset:34816
	ds_read_b128 v[200:203], v158 offset:35840
	ds_read_b128 v[204:207], v158 offset:36864
	ds_read_b128 v[208:211], v158 offset:37888
	ds_read_b128 v[224:227], v158 offset:38912
	ds_read_b128 v[228:231], v158 offset:39936
	global_load_lds_dwordx4 v[232:233], off
	v_lshl_add_u64 v[232:233], s[22:23], 0, v[132:133]
	s_mov_b32 m0, s47
	s_nop 0
	global_load_lds_dwordx4 v[232:233], off
	s_waitcnt lgkmcnt(8)
	s_barrier
	s_waitcnt lgkmcnt(0)
	s_waitcnt lgkmcnt(0)
	v_mfma_f32_16x16x32_bf16 v[126:129], v[160:163], v[176:179], v[126:129]
	v_mfma_f32_16x16x32_bf16 v[122:125], v[168:171], v[176:179], v[122:125]
	v_mfma_f32_16x16x32_bf16 v[110:113], v[160:163], v[196:199], v[110:113]
	v_mfma_f32_16x16x32_bf16 v[106:109], v[168:171], v[196:199], v[106:109]
	v_mfma_f32_16x16x32_bf16 v[94:97], v[160:163], v[204:207], v[94:97]
	v_mfma_f32_16x16x32_bf16 v[90:93], v[168:171], v[204:207], v[90:93]
	v_mfma_f32_16x16x32_bf16 v[78:81], v[160:163], v[224:227], v[78:81]
	v_mfma_f32_16x16x32_bf16 v[74:77], v[168:171], v[224:227], v[74:77]
	v_mfma_f32_16x16x32_bf16 v[126:129], v[164:167], v[192:195], v[126:129]
	v_mfma_f32_16x16x32_bf16 v[122:125], v[172:175], v[192:195], v[122:125]
	v_mfma_f32_16x16x32_bf16 v[110:113], v[164:167], v[200:203], v[110:113]
	v_mfma_f32_16x16x32_bf16 v[106:109], v[172:175], v[200:203], v[106:109]
	v_mfma_f32_16x16x32_bf16 v[94:97], v[164:167], v[208:211], v[94:97]
	v_mfma_f32_16x16x32_bf16 v[90:93], v[172:175], v[208:211], v[90:93]
	v_mfma_f32_16x16x32_bf16 v[78:81], v[164:167], v[228:231], v[78:81]
	v_mfma_f32_16x16x32_bf16 v[74:77], v[172:175], v[228:231], v[74:77]
	s_barrier
	s_add_i32 s22, 0, 0x1c000
	s_add_i32 s23, s58, s29
	v_add_u32_e32 v159, s22, v1
	v_lshl_add_u64 v[212:213], v[212:213], 0, s[78:79]
	s_mov_b32 m0, s23
	ds_read_b128 v[232:235], v159
	ds_read_b128 v[236:239], v159 offset:1024
	ds_read_b128 v[240:243], v159 offset:2048
	ds_read_b128 v[244:247], v159 offset:3072
	global_load_lds_dwordx4 v[212:213], off
	v_lshl_add_u64 v[212:213], v[248:249], 0, s[78:79]
	s_add_i32 m0, s23, 0x2000
	s_nop 0
	global_load_lds_dwordx4 v[212:213], off
	s_barrier
	s_waitcnt lgkmcnt(0)
	s_waitcnt lgkmcnt(0)
	v_mfma_f32_16x16x32_bf16 v[118:121], v[232:235], v[176:179], v[118:121]
	v_mfma_f32_16x16x32_bf16 v[114:117], v[240:243], v[176:179], v[114:117]
	v_mfma_f32_16x16x32_bf16 v[102:105], v[232:235], v[196:199], v[102:105]
	v_mfma_f32_16x16x32_bf16 v[98:101], v[240:243], v[196:199], v[98:101]
	v_mfma_f32_16x16x32_bf16 v[86:89], v[232:235], v[204:207], v[86:89]
	v_mfma_f32_16x16x32_bf16 v[82:85], v[240:243], v[204:207], v[82:85]
	v_mfma_f32_16x16x32_bf16 v[70:73], v[232:235], v[224:227], v[70:73]
	v_mfma_f32_16x16x32_bf16 v[66:69], v[240:243], v[224:227], v[66:69]
	v_mfma_f32_16x16x32_bf16 v[118:121], v[236:239], v[192:195], v[118:121]
	v_mfma_f32_16x16x32_bf16 v[114:117], v[244:247], v[192:195], v[114:117]
	v_mfma_f32_16x16x32_bf16 v[102:105], v[236:239], v[200:203], v[102:105]
	v_mfma_f32_16x16x32_bf16 v[98:101], v[244:247], v[200:203], v[98:101]
	v_mfma_f32_16x16x32_bf16 v[86:89], v[236:239], v[208:211], v[86:89]
	v_mfma_f32_16x16x32_bf16 v[82:85], v[244:247], v[208:211], v[82:85]
	v_mfma_f32_16x16x32_bf16 v[70:73], v[236:239], v[228:231], v[70:73]
	v_mfma_f32_16x16x32_bf16 v[66:69], v[244:247], v[228:231], v[66:69]
	s_mov_b32 m0, s48
	v_lshl_add_u64 v[212:213], v[250:251], 0, s[78:79]
	s_barrier
	ds_read_b128 v[176:179], v158 offset:49152
	ds_read_b128 v[192:195], v158 offset:50176
	ds_read_b128 v[196:199], v158 offset:51200
	ds_read_b128 v[200:203], v158 offset:52224
	ds_read_b128 v[204:207], v158 offset:53248
	ds_read_b128 v[208:211], v158 offset:54272
	ds_read_b128 v[224:227], v158 offset:55296
	ds_read_b128 v[228:231], v158 offset:56320
	global_load_lds_dwordx4 v[212:213], off
	v_lshl_add_u64 v[212:213], v[222:223], 0, s[78:79]
	s_mov_b32 m0, s49
	s_nop 0
	global_load_lds_dwordx4 v[212:213], off
	s_waitcnt vmcnt(10)
	s_barrier
	s_waitcnt lgkmcnt(0)
	s_waitcnt lgkmcnt(0)
	v_mfma_f32_16x16x32_bf16 v[62:65], v[160:163], v[176:179], v[62:65]
	v_mfma_f32_16x16x32_bf16 v[58:61], v[168:171], v[176:179], v[58:61]
	v_mfma_f32_16x16x32_bf16 v[46:49], v[160:163], v[196:199], v[46:49]
	v_mfma_f32_16x16x32_bf16 v[42:45], v[168:171], v[196:199], v[42:45]
	v_mfma_f32_16x16x32_bf16 v[30:33], v[160:163], v[204:207], v[30:33]
	v_mfma_f32_16x16x32_bf16 v[26:29], v[168:171], v[204:207], v[26:29]
	v_mfma_f32_16x16x32_bf16 v[14:17], v[160:163], v[224:227], v[14:17]
	v_mfma_f32_16x16x32_bf16 v[10:13], v[168:171], v[224:227], v[10:13]
	v_mfma_f32_16x16x32_bf16 v[62:65], v[164:167], v[192:195], v[62:65]
	v_mfma_f32_16x16x32_bf16 v[58:61], v[172:175], v[192:195], v[58:61]
	v_mfma_f32_16x16x32_bf16 v[46:49], v[164:167], v[200:203], v[46:49]
	v_mfma_f32_16x16x32_bf16 v[42:45], v[172:175], v[200:203], v[42:45]
	v_mfma_f32_16x16x32_bf16 v[30:33], v[164:167], v[208:211], v[30:33]
	v_mfma_f32_16x16x32_bf16 v[26:29], v[172:175], v[208:211], v[26:29]
	v_mfma_f32_16x16x32_bf16 v[14:17], v[164:167], v[228:231], v[14:17]
	v_mfma_f32_16x16x32_bf16 v[10:13], v[172:175], v[228:231], v[10:13]
	s_barrier
	s_add_u32 s20, s20, 0x80080
	s_addc_u32 s21, s21, 0
	s_add_i32 s22, s22, s29
	v_lshl_add_u64 v[160:161], s[20:21], 0, v[134:135]
	s_mov_b32 m0, s22
	s_nop 0
	global_load_lds_dwordx4 v[160:161], off
	v_lshl_add_u64 v[160:161], s[20:21], 0, v[130:131]
	s_add_i32 m0, s22, 0x2000
	s_nop 0
	global_load_lds_dwordx4 v[160:161], off
	v_add_u32_e32 v159, 0x10000, v1
	ds_read_b128 v[160:163], v159
	ds_read_b128 v[164:167], v159 offset:1024
	ds_read_b128 v[168:171], v159 offset:2048
	ds_read_b128 v[172:175], v159 offset:3072
	s_waitcnt vmcnt(6)
	s_barrier
	v_mfma_f32_16x16x32_bf16 v[54:57], v[232:235], v[176:179], v[54:57]
	v_mfma_f32_16x16x32_bf16 v[50:53], v[240:243], v[176:179], v[50:53]
	v_mfma_f32_16x16x32_bf16 v[38:41], v[232:235], v[196:199], v[38:41]
	v_mfma_f32_16x16x32_bf16 v[34:37], v[240:243], v[196:199], v[34:37]
	v_mfma_f32_16x16x32_bf16 v[22:25], v[232:235], v[204:207], v[22:25]
	v_mfma_f32_16x16x32_bf16 v[18:21], v[240:243], v[204:207], v[18:21]
	v_mfma_f32_16x16x32_bf16 v[6:9], v[232:235], v[224:227], v[6:9]
	v_mfma_f32_16x16x32_bf16 v[2:5], v[240:243], v[224:227], v[2:5]
	v_mfma_f32_16x16x32_bf16 v[54:57], v[236:239], v[192:195], v[54:57]
	v_mfma_f32_16x16x32_bf16 v[50:53], v[244:247], v[192:195], v[50:53]
	v_mfma_f32_16x16x32_bf16 v[38:41], v[236:239], v[200:203], v[38:41]
	v_mfma_f32_16x16x32_bf16 v[34:37], v[244:247], v[200:203], v[34:37]
	v_mfma_f32_16x16x32_bf16 v[22:25], v[236:239], v[208:211], v[22:25]
	v_mfma_f32_16x16x32_bf16 v[18:21], v[244:247], v[208:211], v[18:21]
	v_mfma_f32_16x16x32_bf16 v[6:9], v[236:239], v[228:231], v[6:9]
	v_mfma_f32_16x16x32_bf16 v[2:5], v[244:247], v[228:231], v[2:5]
	s_add_i32 s57, s57, 2
	s_add_u32 s18, s18, 0x100
	s_addc_u32 s19, s19, 0
	s_add_u32 s55, s55, 0x100
	s_addc_u32 s56, s56, 0
	s_cmp_gt_u32 s57, 29
	s_barrier
	s_cbranch_scc0 .LBB0_749
	s_waitcnt lgkmcnt(0)
	s_lshl_b32 s18, s52, 5
	s_add_i32 s18, s18, s51
	v_max_f32_e32 v122, 0, v122
	v_max_f32_e32 v123, 0, v123
	s_ashr_i32 s19, s18, 31
	v_pk_mul_f32 v[162:163], v[122:123], v[122:123]
	v_max_f32_e32 v123, v124, v124
	s_lshl_b64 s[18:19], s[18:19], 17
	v_max_f32_e32 v122, v128, v128
	v_max_f32_e32 v124, 0, v123
	v_max_f32_e32 v123, v129, v129
	s_add_u32 s18, s68, s18
	v_max_f32_e32 v126, 0, v126
	v_max_f32_e32 v127, 0, v127
	v_max_f32_e32 v122, 0, v122
	v_max_f32_e32 v123, 0, v123
	v_max_f32_e32 v125, 0, v125
	s_addc_u32 s19, s69, s19
	v_pk_mul_f32 v[126:127], v[126:127], v[126:127]
	v_pk_mul_f32 v[128:129], v[122:123], v[122:123]
	v_pk_mul_f32 v[164:165], v[124:125], v[124:125]
	v_lshl_add_u64 v[160:161], v[138:139], 1, s[18:19]
	v_cvt_pk_bf16_f32 v122, v126, v127
	v_cvt_pk_bf16_f32 v123, v128, v129
	v_cvt_pk_bf16_f32 v124, v162, v163
	v_cvt_pk_bf16_f32 v125, v164, v165
	v_max_f32_e32 v114, 0, v114
	v_max_f32_e32 v115, 0, v115
	global_store_dwordx4 v[160:161], v[122:125], off
	v_max_f32_e32 v118, v118, v118
	v_max_f32_e32 v119, v119, v119
	v_pk_mul_f32 v[122:123], v[114:115], v[114:115]
	v_max_f32_e32 v115, v116, v116
	v_max_f32_e32 v114, v120, v120
	v_max_f32_e32 v116, 0, v115
	v_max_f32_e32 v115, v121, v121
	v_max_f32_e32 v118, 0, v118
	v_max_f32_e32 v119, 0, v119
	v_max_f32_e32 v114, 0, v114
	v_max_f32_e32 v115, 0, v115
	v_max_f32_e32 v117, 0, v117
	v_pk_mul_f32 v[118:119], v[118:119], v[118:119]
	v_pk_mul_f32 v[120:121], v[114:115], v[114:115]
	v_pk_mul_f32 v[124:125], v[116:117], v[116:117]
	v_cvt_pk_bf16_f32 v114, v118, v119
	v_cvt_pk_bf16_f32 v115, v120, v121
	v_cvt_pk_bf16_f32 v116, v122, v123
	v_cvt_pk_bf16_f32 v117, v124, v125
	v_max_f32_e32 v106, 0, v106
	v_max_f32_e32 v107, 0, v107
	global_store_dwordx4 v[160:161], v[114:117], off offset:256
	v_max_f32_e32 v110, v110, v110
	v_max_f32_e32 v111, v111, v111
	v_pk_mul_f32 v[116:117], v[106:107], v[106:107]
	v_max_f32_e32 v107, v108, v108
	v_max_f32_e32 v106, v112, v112
	v_max_f32_e32 v108, 0, v107
	v_max_f32_e32 v107, v113, v113
	v_max_f32_e32 v110, 0, v110
	v_max_f32_e32 v111, 0, v111
	v_max_f32_e32 v106, 0, v106
	v_max_f32_e32 v107, 0, v107
	v_max_f32_e32 v109, 0, v109
	v_pk_mul_f32 v[110:111], v[110:111], v[110:111]
	v_pk_mul_f32 v[112:113], v[106:107], v[106:107]
	v_pk_mul_f32 v[118:119], v[108:109], v[108:109]
	v_lshl_add_u64 v[114:115], v[140:141], 1, s[18:19]
	v_cvt_pk_bf16_f32 v106, v110, v111
	v_cvt_pk_bf16_f32 v107, v112, v113
	v_cvt_pk_bf16_f32 v108, v116, v117
	v_cvt_pk_bf16_f32 v109, v118, v119
	v_max_f32_e32 v98, 0, v98
	v_max_f32_e32 v99, 0, v99
	global_store_dwordx4 v[114:115], v[106:109], off
	v_max_f32_e32 v102, v102, v102
	v_max_f32_e32 v103, v103, v103
	v_pk_mul_f32 v[106:107], v[98:99], v[98:99]
	v_max_f32_e32 v99, v100, v100
	v_max_f32_e32 v98, v104, v104
	v_max_f32_e32 v100, 0, v99
	v_max_f32_e32 v99, v105, v105
	v_max_f32_e32 v102, 0, v102
	v_max_f32_e32 v103, 0, v103
	v_max_f32_e32 v98, 0, v98
	v_max_f32_e32 v99, 0, v99
	v_max_f32_e32 v101, 0, v101
	v_pk_mul_f32 v[102:103], v[102:103], v[102:103]
	v_pk_mul_f32 v[104:105], v[98:99], v[98:99]
	v_pk_mul_f32 v[108:109], v[100:101], v[100:101]
	v_cvt_pk_bf16_f32 v98, v102, v103
	v_cvt_pk_bf16_f32 v99, v104, v105
	v_cvt_pk_bf16_f32 v100, v106, v107
	v_cvt_pk_bf16_f32 v101, v108, v109
	v_max_f32_e32 v90, 0, v90
	v_max_f32_e32 v91, 0, v91
	global_store_dwordx4 v[114:115], v[98:101], off offset:256
	v_max_f32_e32 v94, v94, v94
	v_max_f32_e32 v95, v95, v95
	v_pk_mul_f32 v[100:101], v[90:91], v[90:91]
	v_max_f32_e32 v91, v92, v92
	v_max_f32_e32 v90, v96, v96
	v_max_f32_e32 v92, 0, v91
	v_max_f32_e32 v91, v97, v97
	v_max_f32_e32 v94, 0, v94
	v_max_f32_e32 v95, 0, v95
	v_max_f32_e32 v90, 0, v90
	v_max_f32_e32 v91, 0, v91
	v_max_f32_e32 v93, 0, v93
	v_pk_mul_f32 v[94:95], v[94:95], v[94:95]
	v_pk_mul_f32 v[96:97], v[90:91], v[90:91]
	v_pk_mul_f32 v[102:103], v[92:93], v[92:93]
	v_lshl_add_u64 v[98:99], v[142:143], 1, s[18:19]
	v_cvt_pk_bf16_f32 v90, v94, v95
	v_cvt_pk_bf16_f32 v91, v96, v97
	v_cvt_pk_bf16_f32 v92, v100, v101
	v_cvt_pk_bf16_f32 v93, v102, v103
	v_max_f32_e32 v82, 0, v82
	v_max_f32_e32 v83, 0, v83
	global_store_dwordx4 v[98:99], v[90:93], off
	v_max_f32_e32 v86, v86, v86
	v_max_f32_e32 v87, v87, v87
	v_pk_mul_f32 v[90:91], v[82:83], v[82:83]
	v_max_f32_e32 v83, v84, v84
	v_max_f32_e32 v82, v88, v88
	v_max_f32_e32 v84, 0, v83
	v_max_f32_e32 v83, v89, v89
	v_max_f32_e32 v86, 0, v86
	v_max_f32_e32 v87, 0, v87
	v_max_f32_e32 v82, 0, v82
	v_max_f32_e32 v83, 0, v83
	v_max_f32_e32 v85, 0, v85
	v_pk_mul_f32 v[86:87], v[86:87], v[86:87]
	v_pk_mul_f32 v[88:89], v[82:83], v[82:83]
	v_pk_mul_f32 v[92:93], v[84:85], v[84:85]
	v_cvt_pk_bf16_f32 v82, v86, v87
	v_cvt_pk_bf16_f32 v83, v88, v89
	v_cvt_pk_bf16_f32 v84, v90, v91
	v_cvt_pk_bf16_f32 v85, v92, v93
	v_max_f32_e32 v74, 0, v74
	v_max_f32_e32 v75, 0, v75
	global_store_dwordx4 v[98:99], v[82:85], off offset:256
	v_max_f32_e32 v78, v78, v78
	v_max_f32_e32 v79, v79, v79
	v_pk_mul_f32 v[84:85], v[74:75], v[74:75]
	v_max_f32_e32 v75, v76, v76
	v_max_f32_e32 v74, v80, v80
	v_max_f32_e32 v76, 0, v75
	v_max_f32_e32 v75, v81, v81
	v_max_f32_e32 v78, 0, v78
	v_max_f32_e32 v79, 0, v79
	v_max_f32_e32 v74, 0, v74
	v_max_f32_e32 v75, 0, v75
	v_max_f32_e32 v77, 0, v77
	v_pk_mul_f32 v[78:79], v[78:79], v[78:79]
	v_pk_mul_f32 v[80:81], v[74:75], v[74:75]
	v_pk_mul_f32 v[86:87], v[76:77], v[76:77]
	v_lshl_add_u64 v[82:83], v[144:145], 1, s[18:19]
	v_cvt_pk_bf16_f32 v74, v78, v79
	v_cvt_pk_bf16_f32 v75, v80, v81
	v_cvt_pk_bf16_f32 v76, v84, v85
	v_cvt_pk_bf16_f32 v77, v86, v87
	v_max_f32_e32 v66, 0, v66
	v_max_f32_e32 v67, 0, v67
	global_store_dwordx4 v[82:83], v[74:77], off
	v_max_f32_e32 v70, v70, v70
	v_max_f32_e32 v71, v71, v71
	v_pk_mul_f32 v[74:75], v[66:67], v[66:67]
	v_max_f32_e32 v67, v68, v68
	v_max_f32_e32 v66, v72, v72
	v_max_f32_e32 v68, 0, v67
	v_max_f32_e32 v67, v73, v73
	v_max_f32_e32 v70, 0, v70
	v_max_f32_e32 v71, 0, v71
	v_max_f32_e32 v66, 0, v66
	v_max_f32_e32 v67, 0, v67
	v_max_f32_e32 v69, 0, v69
	v_pk_mul_f32 v[70:71], v[70:71], v[70:71]
	v_pk_mul_f32 v[72:73], v[66:67], v[66:67]
	v_pk_mul_f32 v[76:77], v[68:69], v[68:69]
	v_cvt_pk_bf16_f32 v66, v70, v71
	v_cvt_pk_bf16_f32 v67, v72, v73
	v_cvt_pk_bf16_f32 v68, v74, v75
	v_cvt_pk_bf16_f32 v69, v76, v77
	v_max_f32_e32 v58, 0, v58
	v_max_f32_e32 v59, 0, v59
	global_store_dwordx4 v[82:83], v[66:69], off offset:256
	v_max_f32_e32 v62, v62, v62
	v_max_f32_e32 v63, v63, v63
	v_pk_mul_f32 v[68:69], v[58:59], v[58:59]
	v_max_f32_e32 v59, v60, v60
	v_max_f32_e32 v58, v64, v64
	v_max_f32_e32 v60, 0, v59
	v_max_f32_e32 v59, v65, v65
	v_max_f32_e32 v62, 0, v62
	v_max_f32_e32 v63, 0, v63
	v_max_f32_e32 v58, 0, v58
	v_max_f32_e32 v59, 0, v59
	v_max_f32_e32 v61, 0, v61
	v_pk_mul_f32 v[62:63], v[62:63], v[62:63]
	v_pk_mul_f32 v[64:65], v[58:59], v[58:59]
	v_pk_mul_f32 v[70:71], v[60:61], v[60:61]
	v_lshl_add_u64 v[66:67], v[146:147], 1, s[18:19]
	v_cvt_pk_bf16_f32 v58, v62, v63
	v_cvt_pk_bf16_f32 v59, v64, v65
	v_cvt_pk_bf16_f32 v60, v68, v69
	v_cvt_pk_bf16_f32 v61, v70, v71
	v_max_f32_e32 v50, 0, v50
	v_max_f32_e32 v51, 0, v51
	global_store_dwordx4 v[66:67], v[58:61], off
	v_max_f32_e32 v54, v54, v54
	v_max_f32_e32 v55, v55, v55
	v_pk_mul_f32 v[58:59], v[50:51], v[50:51]
	v_max_f32_e32 v51, v52, v52
	v_max_f32_e32 v50, v56, v56
	v_max_f32_e32 v52, 0, v51
	v_max_f32_e32 v51, v57, v57
	v_max_f32_e32 v54, 0, v54
	v_max_f32_e32 v55, 0, v55
	v_max_f32_e32 v50, 0, v50
	v_max_f32_e32 v51, 0, v51
	v_max_f32_e32 v53, 0, v53
	v_pk_mul_f32 v[54:55], v[54:55], v[54:55]
	v_pk_mul_f32 v[56:57], v[50:51], v[50:51]
	v_pk_mul_f32 v[60:61], v[52:53], v[52:53]
	v_cvt_pk_bf16_f32 v50, v54, v55
	v_cvt_pk_bf16_f32 v51, v56, v57
	v_cvt_pk_bf16_f32 v52, v58, v59
	v_cvt_pk_bf16_f32 v53, v60, v61
	v_max_f32_e32 v42, 0, v42
	v_max_f32_e32 v43, 0, v43
	global_store_dwordx4 v[66:67], v[50:53], off offset:256
	v_max_f32_e32 v46, v46, v46
	v_max_f32_e32 v47, v47, v47
	v_pk_mul_f32 v[52:53], v[42:43], v[42:43]
	v_max_f32_e32 v43, v44, v44
	v_max_f32_e32 v42, v48, v48
	v_max_f32_e32 v44, 0, v43
	v_max_f32_e32 v43, v49, v49
	v_max_f32_e32 v46, 0, v46
	v_max_f32_e32 v47, 0, v47
	v_max_f32_e32 v42, 0, v42
	v_max_f32_e32 v43, 0, v43
	v_max_f32_e32 v45, 0, v45
	v_pk_mul_f32 v[46:47], v[46:47], v[46:47]
	v_pk_mul_f32 v[48:49], v[42:43], v[42:43]
	v_pk_mul_f32 v[54:55], v[44:45], v[44:45]
	v_lshl_add_u64 v[50:51], v[148:149], 1, s[18:19]
	v_cvt_pk_bf16_f32 v42, v46, v47
	v_cvt_pk_bf16_f32 v43, v48, v49
	v_cvt_pk_bf16_f32 v44, v52, v53
	v_cvt_pk_bf16_f32 v45, v54, v55
	v_max_f32_e32 v34, 0, v34
	v_max_f32_e32 v35, 0, v35
	global_store_dwordx4 v[50:51], v[42:45], off
	v_max_f32_e32 v38, v38, v38
	v_max_f32_e32 v39, v39, v39
	v_pk_mul_f32 v[42:43], v[34:35], v[34:35]
	v_max_f32_e32 v35, v36, v36
	v_max_f32_e32 v34, v40, v40
	v_max_f32_e32 v36, 0, v35
	v_max_f32_e32 v35, v41, v41
	v_max_f32_e32 v38, 0, v38
	v_max_f32_e32 v39, 0, v39
	v_max_f32_e32 v34, 0, v34
	v_max_f32_e32 v35, 0, v35
	v_max_f32_e32 v37, 0, v37
	v_pk_mul_f32 v[38:39], v[38:39], v[38:39]
	v_pk_mul_f32 v[40:41], v[34:35], v[34:35]
	v_pk_mul_f32 v[44:45], v[36:37], v[36:37]
	v_cvt_pk_bf16_f32 v34, v38, v39
	v_cvt_pk_bf16_f32 v35, v40, v41
	v_cvt_pk_bf16_f32 v36, v42, v43
	v_cvt_pk_bf16_f32 v37, v44, v45
	v_max_f32_e32 v26, 0, v26
	v_max_f32_e32 v27, 0, v27
	global_store_dwordx4 v[50:51], v[34:37], off offset:256
	v_max_f32_e32 v30, v30, v30
	v_max_f32_e32 v31, v31, v31
	v_pk_mul_f32 v[36:37], v[26:27], v[26:27]
	v_max_f32_e32 v27, v28, v28
	v_max_f32_e32 v26, v32, v32
	v_max_f32_e32 v28, 0, v27
	v_max_f32_e32 v27, v33, v33
	v_max_f32_e32 v30, 0, v30
	v_max_f32_e32 v31, 0, v31
	v_max_f32_e32 v26, 0, v26
	v_max_f32_e32 v27, 0, v27
	v_max_f32_e32 v29, 0, v29
	v_pk_mul_f32 v[30:31], v[30:31], v[30:31]
	v_pk_mul_f32 v[32:33], v[26:27], v[26:27]
	v_pk_mul_f32 v[38:39], v[28:29], v[28:29]
	v_lshl_add_u64 v[34:35], v[150:151], 1, s[18:19]
	v_cvt_pk_bf16_f32 v26, v30, v31
	v_cvt_pk_bf16_f32 v27, v32, v33
	v_cvt_pk_bf16_f32 v28, v36, v37
	v_cvt_pk_bf16_f32 v29, v38, v39
	v_max_f32_e32 v18, 0, v18
	v_max_f32_e32 v19, 0, v19
	global_store_dwordx4 v[34:35], v[26:29], off
	v_max_f32_e32 v22, v22, v22
	v_max_f32_e32 v23, v23, v23
	v_pk_mul_f32 v[26:27], v[18:19], v[18:19]
	v_max_f32_e32 v19, v20, v20
	v_max_f32_e32 v18, v24, v24
	v_max_f32_e32 v20, 0, v19
	v_max_f32_e32 v19, v25, v25
	v_max_f32_e32 v22, 0, v22
	v_max_f32_e32 v23, 0, v23
	v_max_f32_e32 v18, 0, v18
	v_max_f32_e32 v19, 0, v19
	v_max_f32_e32 v21, 0, v21
	v_pk_mul_f32 v[22:23], v[22:23], v[22:23]
	v_pk_mul_f32 v[24:25], v[18:19], v[18:19]
	v_pk_mul_f32 v[28:29], v[20:21], v[20:21]
	v_cvt_pk_bf16_f32 v18, v22, v23
	v_cvt_pk_bf16_f32 v19, v24, v25
	v_cvt_pk_bf16_f32 v20, v26, v27
	v_cvt_pk_bf16_f32 v21, v28, v29
	v_max_f32_e32 v10, 0, v10
	v_max_f32_e32 v11, 0, v11
	global_store_dwordx4 v[34:35], v[18:21], off offset:256
	v_max_f32_e32 v14, v14, v14
	v_max_f32_e32 v15, v15, v15
	v_pk_mul_f32 v[20:21], v[10:11], v[10:11]
	v_max_f32_e32 v11, v12, v12
	v_max_f32_e32 v10, v16, v16
	v_max_f32_e32 v12, 0, v11
	v_max_f32_e32 v11, v17, v17
	v_max_f32_e32 v14, 0, v14
	v_max_f32_e32 v15, 0, v15
	v_max_f32_e32 v10, 0, v10
	v_max_f32_e32 v11, 0, v11
	v_max_f32_e32 v13, 0, v13
	v_pk_mul_f32 v[14:15], v[14:15], v[14:15]
	v_pk_mul_f32 v[16:17], v[10:11], v[10:11]
	v_pk_mul_f32 v[22:23], v[12:13], v[12:13]
	v_lshl_add_u64 v[18:19], v[152:153], 1, s[18:19]
	v_cvt_pk_bf16_f32 v10, v14, v15
	v_cvt_pk_bf16_f32 v11, v16, v17
	v_cvt_pk_bf16_f32 v12, v20, v21
	v_cvt_pk_bf16_f32 v13, v22, v23
	v_max_f32_e32 v2, 0, v2
	v_max_f32_e32 v3, 0, v3
	global_store_dwordx4 v[18:19], v[10:13], off
	v_max_f32_e32 v6, v6, v6
	v_max_f32_e32 v7, v7, v7
	v_pk_mul_f32 v[10:11], v[2:3], v[2:3]
	v_max_f32_e32 v3, v4, v4
	v_max_f32_e32 v2, v8, v8
	v_max_f32_e32 v4, 0, v3
	v_max_f32_e32 v3, v9, v9
	v_max_f32_e32 v6, 0, v6
	v_max_f32_e32 v7, 0, v7
	v_max_f32_e32 v2, 0, v2
	v_max_f32_e32 v3, 0, v3
	v_max_f32_e32 v5, 0, v5
	v_pk_mul_f32 v[6:7], v[6:7], v[6:7]
	v_pk_mul_f32 v[8:9], v[2:3], v[2:3]
	v_pk_mul_f32 v[12:13], v[4:5], v[4:5]
	v_cvt_pk_bf16_f32 v2, v6, v7
	v_cvt_pk_bf16_f32 v3, v8, v9
	v_cvt_pk_bf16_f32 v4, v10, v11
	v_cvt_pk_bf16_f32 v5, v12, v13
	s_and_b64 vcc, exec, s[0:1]
	s_mov_b32 s51, s30
	s_mov_b32 s52, s38
	s_mov_b64 s[20:21], s[80:81]
	s_mov_b64 s[18:19], s[42:43]
	global_store_dwordx4 v[18:19], v[2:5], off offset:256
	s_cbranch_vccz .LBB0_742
	s_waitcnt vmcnt(0)
	v_readlane_b32 s38, v255, 28
	s_cmpk_gt_u32 s26, 0xff
	v_readlane_b32 s39, v255, 29
	v_readlane_b32 s42, v255, 32
	s_cbranch_scc1 .LBB0_753
	s_barrier

.LBB0_814:
	s_add_i32 s22, s55, 0xffff0000
	s_and_b32 s22, s22, 0x3e0000
	s_and_b32 s23, s90, 0x100
	s_or_b32 s56, s23, s22
	s_and_b32 s22, s55, 0x7e0000
	s_add_u32 vcc_lo, s90, 0x100
	s_addc_u32 vcc_hi, s91, 0
	s_and_b32 s23, vcc_lo, 0x100
	s_or_b32 s22, s22, s23
	s_add_u32 s22, s84, s22
	s_addc_u32 s23, s85, 0
	s_add_u32 s57, s30, s90
	s_addc_u32 s58, s31, s91
	s_add_u32 s57, s57, 0x100
	s_addc_u32 s58, s58, 0
	s_add_i32 s59, 0, 0x10000
	s_cmpk_eq_i32 s54, 0x7c
	s_cselect_b32 s91, s43, s58
	s_cselect_b32 s90, s53, s57
	s_cselect_b32 s23, s51, s23
	s_cselect_b32 s22, s52, s22
	s_add_u32 s56, s84, s56
	s_addc_u32 s57, s85, 0
	s_add_u32 s56, s56, 0x10080
	s_addc_u32 s57, s57, 0
	v_lshl_add_u64 v[204:205], s[56:57], 0, v[136:137]
	s_add_i32 m0, s28, 0xc000
	ds_read_b128 v[158:161], v140
	ds_read_b128 v[162:165], v140 offset:1024
	ds_read_b128 v[168:171], v140 offset:2048
	ds_read_b128 v[172:175], v140 offset:3072
	ds_read_b128 v[176:179], v140 offset:4096
	ds_read_b128 v[192:195], v140 offset:5120
	ds_read_b128 v[196:199], v140 offset:6144
	ds_read_b128 v[200:203], v140 offset:7168
	global_load_lds_dwordx4 v[204:205], off
	v_lshl_add_u64 v[204:205], s[56:57], 0, v[132:133]
	s_add_i32 m0, s28, 0xe000
	s_nop 0
	global_load_lds_dwordx4 v[204:205], off
	s_waitcnt lgkmcnt(8)
	s_barrier
	s_waitcnt lgkmcnt(0)
	s_waitcnt lgkmcnt(0)
	v_mfma_f32_16x16x32_bf16 v[86:89], v[142:145], v[158:161], v[86:89]
	v_mfma_f32_16x16x32_bf16 v[94:97], v[150:153], v[158:161], v[94:97]
	v_mfma_f32_16x16x32_bf16 v[98:101], v[142:145], v[168:171], v[98:101]
	v_mfma_f32_16x16x32_bf16 v[102:105], v[150:153], v[168:171], v[102:105]
	v_mfma_f32_16x16x32_bf16 v[114:117], v[142:145], v[176:179], v[114:117]
	v_mfma_f32_16x16x32_bf16 v[122:125], v[150:153], v[176:179], v[122:125]
	v_mfma_f32_16x16x32_bf16 v[126:129], v[142:145], v[196:199], v[126:129]
	v_mfma_f32_16x16x32_bf16 v[118:121], v[150:153], v[196:199], v[118:121]
	v_mfma_f32_16x16x32_bf16 v[86:89], v[146:149], v[162:165], v[86:89]
	v_mfma_f32_16x16x32_bf16 v[94:97], v[154:157], v[162:165], v[94:97]
	v_mfma_f32_16x16x32_bf16 v[98:101], v[146:149], v[172:175], v[98:101]
	v_mfma_f32_16x16x32_bf16 v[102:105], v[154:157], v[172:175], v[102:105]
	v_mfma_f32_16x16x32_bf16 v[114:117], v[146:149], v[192:195], v[114:117]
	v_mfma_f32_16x16x32_bf16 v[122:125], v[154:157], v[192:195], v[122:125]
	v_mfma_f32_16x16x32_bf16 v[126:129], v[146:149], v[200:203], v[126:129]
	v_mfma_f32_16x16x32_bf16 v[118:121], v[154:157], v[200:203], v[118:121]
	s_barrier
	s_add_i32 s58, 0, 0x14000
	s_add_i32 s56, s59, s81
	v_add_u32_e32 v141, s58, v139
	v_lshl_add_u64 v[212:213], s[90:91], 0, v[134:135]
	s_mov_b32 m0, s56
	ds_read_b128 v[204:207], v141
	ds_read_b128 v[208:211], v141 offset:1024
	ds_read_b128 v[224:227], v141 offset:2048
	ds_read_b128 v[228:231], v141 offset:3072
	global_load_lds_dwordx4 v[212:213], off
	v_lshl_add_u64 v[222:223], s[90:91], 0, v[130:131]
	s_add_i32 m0, s56, 0x2000
	s_nop 0
	global_load_lds_dwordx4 v[222:223], off
	s_barrier
	s_waitcnt lgkmcnt(0)
	s_waitcnt lgkmcnt(0)
	v_mfma_f32_16x16x32_bf16 v[2:5], v[204:207], v[158:161], v[2:5]
	v_mfma_f32_16x16x32_bf16 v[6:9], v[224:227], v[158:161], v[6:9]
	v_mfma_f32_16x16x32_bf16 v[10:13], v[204:207], v[168:171], v[10:13]
	v_mfma_f32_16x16x32_bf16 v[14:17], v[224:227], v[168:171], v[14:17]
	v_mfma_f32_16x16x32_bf16 v[22:25], v[204:207], v[176:179], v[22:25]
	v_mfma_f32_16x16x32_bf16 v[18:21], v[224:227], v[176:179], v[18:21]
	v_mfma_f32_16x16x32_bf16 v[30:33], v[204:207], v[196:199], v[30:33]
	v_mfma_f32_16x16x32_bf16 v[26:29], v[224:227], v[196:199], v[26:29]
	v_mfma_f32_16x16x32_bf16 v[2:5], v[208:211], v[162:165], v[2:5]
	v_mfma_f32_16x16x32_bf16 v[6:9], v[228:231], v[162:165], v[6:9]
	v_mfma_f32_16x16x32_bf16 v[10:13], v[208:211], v[172:175], v[10:13]
	v_mfma_f32_16x16x32_bf16 v[14:17], v[228:231], v[172:175], v[14:17]
	v_mfma_f32_16x16x32_bf16 v[22:25], v[208:211], v[192:195], v[22:25]
	v_mfma_f32_16x16x32_bf16 v[18:21], v[228:231], v[192:195], v[18:21]
	v_mfma_f32_16x16x32_bf16 v[30:33], v[208:211], v[200:203], v[30:33]
	v_mfma_f32_16x16x32_bf16 v[26:29], v[228:231], v[200:203], v[26:29]
	s_mov_b32 m0, s28
	v_lshl_add_u64 v[232:233], s[22:23], 0, v[136:137]
	s_barrier
	ds_read_b128 v[158:161], v140 offset:16384
	ds_read_b128 v[162:165], v140 offset:17408
	ds_read_b128 v[168:171], v140 offset:18432
	ds_read_b128 v[172:175], v140 offset:19456
	ds_read_b128 v[176:179], v140 offset:20480
	ds_read_b128 v[192:195], v140 offset:21504
	ds_read_b128 v[196:199], v140 offset:22528
	ds_read_b128 v[200:203], v140 offset:23552
	global_load_lds_dwordx4 v[232:233], off
	v_lshl_add_u64 v[234:235], s[22:23], 0, v[132:133]
	s_mov_b32 m0, s29
	s_nop 0
	global_load_lds_dwordx4 v[234:235], off
	s_waitcnt vmcnt(10)
	s_barrier
	s_waitcnt lgkmcnt(0)
	s_waitcnt lgkmcnt(0)
	v_mfma_f32_16x16x32_bf16 v[110:113], v[142:145], v[158:161], v[110:113]
	v_mfma_f32_16x16x32_bf16 v[106:109], v[150:153], v[158:161], v[106:109]
	v_mfma_f32_16x16x32_bf16 v[90:93], v[142:145], v[168:171], v[90:93]
	v_mfma_f32_16x16x32_bf16 v[82:85], v[150:153], v[168:171], v[82:85]
	v_mfma_f32_16x16x32_bf16 v[78:81], v[142:145], v[176:179], v[78:81]
	v_mfma_f32_16x16x32_bf16 v[74:77], v[150:153], v[176:179], v[74:77]
	v_mfma_f32_16x16x32_bf16 v[70:73], v[142:145], v[196:199], v[70:73]
	v_mfma_f32_16x16x32_bf16 v[66:69], v[150:153], v[196:199], v[66:69]
	v_mfma_f32_16x16x32_bf16 v[110:113], v[146:149], v[162:165], v[110:113]
	v_mfma_f32_16x16x32_bf16 v[106:109], v[154:157], v[162:165], v[106:109]
	v_mfma_f32_16x16x32_bf16 v[90:93], v[146:149], v[172:175], v[90:93]
	v_mfma_f32_16x16x32_bf16 v[82:85], v[154:157], v[172:175], v[82:85]
	v_mfma_f32_16x16x32_bf16 v[78:81], v[146:149], v[192:195], v[78:81]
	v_mfma_f32_16x16x32_bf16 v[74:77], v[154:157], v[192:195], v[74:77]
	v_mfma_f32_16x16x32_bf16 v[70:73], v[146:149], v[200:203], v[70:73]
	v_mfma_f32_16x16x32_bf16 v[66:69], v[154:157], v[200:203], v[66:69]
	s_barrier
	s_add_u32 s56, s90, 0x200000
	s_addc_u32 s57, s91, 0
	s_add_i32 s58, s58, s81
	v_lshl_add_u64 v[142:143], s[56:57], 0, v[134:135]
	s_mov_b32 m0, s58
	s_nop 0
	global_load_lds_dwordx4 v[142:143], off
	v_lshl_add_u64 v[142:143], s[56:57], 0, v[130:131]
	s_add_i32 m0, s58, 0x2000
	s_nop 0
	global_load_lds_dwordx4 v[142:143], off
	v_add_u32_e32 v141, 0x18000, v139
	ds_read_b128 v[142:145], v141
	ds_read_b128 v[146:149], v141 offset:1024
	ds_read_b128 v[150:153], v141 offset:2048
	ds_read_b128 v[154:157], v141 offset:3072
	s_waitcnt vmcnt(6)
	s_barrier
	v_mfma_f32_16x16x32_bf16 v[38:41], v[204:207], v[158:161], v[38:41]
	v_mfma_f32_16x16x32_bf16 v[34:37], v[224:227], v[158:161], v[34:37]
	v_mfma_f32_16x16x32_bf16 v[46:49], v[204:207], v[168:171], v[46:49]
	v_mfma_f32_16x16x32_bf16 v[42:45], v[224:227], v[168:171], v[42:45]
	v_mfma_f32_16x16x32_bf16 v[54:57], v[204:207], v[176:179], v[54:57]
	v_mfma_f32_16x16x32_bf16 v[50:53], v[224:227], v[176:179], v[50:53]
	v_mfma_f32_16x16x32_bf16 v[62:65], v[204:207], v[196:199], v[62:65]
	v_mfma_f32_16x16x32_bf16 v[58:61], v[224:227], v[196:199], v[58:61]
	v_mfma_f32_16x16x32_bf16 v[38:41], v[208:211], v[162:165], v[38:41]
	v_mfma_f32_16x16x32_bf16 v[34:37], v[228:231], v[162:165], v[34:37]
	v_mfma_f32_16x16x32_bf16 v[46:49], v[208:211], v[172:175], v[46:49]
	v_mfma_f32_16x16x32_bf16 v[42:45], v[228:231], v[172:175], v[42:45]
	v_mfma_f32_16x16x32_bf16 v[54:57], v[208:211], v[192:195], v[54:57]
	v_mfma_f32_16x16x32_bf16 v[50:53], v[228:231], v[192:195], v[50:53]
	v_mfma_f32_16x16x32_bf16 v[62:65], v[208:211], v[200:203], v[62:65]
	v_mfma_f32_16x16x32_bf16 v[58:61], v[228:231], v[200:203], v[58:61]
	s_add_i32 s56, 0, 0x18000
	s_barrier
	s_add_u32 s22, s22, 0x10000
	s_addc_u32 s23, s23, 0
	s_mov_b32 m0, s44
	v_lshl_add_u64 v[204:205], s[22:23], 0, v[136:137]
	ds_read_b128 v[158:161], v140 offset:32768
	ds_read_b128 v[162:165], v140 offset:33792
	ds_read_b128 v[168:171], v140 offset:34816
	ds_read_b128 v[172:175], v140 offset:35840
	ds_read_b128 v[176:179], v140 offset:36864
	ds_read_b128 v[192:195], v140 offset:37888
	ds_read_b128 v[196:199], v140 offset:38912
	ds_read_b128 v[200:203], v140 offset:39936
	global_load_lds_dwordx4 v[204:205], off
	v_lshl_add_u64 v[204:205], s[22:23], 0, v[132:133]
	s_mov_b32 m0, s45
	s_nop 0
	global_load_lds_dwordx4 v[204:205], off
	s_waitcnt lgkmcnt(8)
	s_barrier
	s_waitcnt lgkmcnt(0)
	s_waitcnt lgkmcnt(0)
	v_mfma_f32_16x16x32_bf16 v[86:89], v[142:145], v[158:161], v[86:89]
	v_mfma_f32_16x16x32_bf16 v[94:97], v[150:153], v[158:161], v[94:97]
	v_mfma_f32_16x16x32_bf16 v[98:101], v[142:145], v[168:171], v[98:101]
	v_mfma_f32_16x16x32_bf16 v[102:105], v[150:153], v[168:171], v[102:105]
	v_mfma_f32_16x16x32_bf16 v[114:117], v[142:145], v[176:179], v[114:117]
	v_mfma_f32_16x16x32_bf16 v[122:125], v[150:153], v[176:179], v[122:125]
	v_mfma_f32_16x16x32_bf16 v[126:129], v[142:145], v[196:199], v[126:129]
	v_mfma_f32_16x16x32_bf16 v[118:121], v[150:153], v[196:199], v[118:121]
	v_mfma_f32_16x16x32_bf16 v[86:89], v[146:149], v[162:165], v[86:89]
	v_mfma_f32_16x16x32_bf16 v[94:97], v[154:157], v[162:165], v[94:97]
	v_mfma_f32_16x16x32_bf16 v[98:101], v[146:149], v[172:175], v[98:101]
	v_mfma_f32_16x16x32_bf16 v[102:105], v[154:157], v[172:175], v[102:105]
	v_mfma_f32_16x16x32_bf16 v[114:117], v[146:149], v[192:195], v[114:117]
	v_mfma_f32_16x16x32_bf16 v[122:125], v[154:157], v[192:195], v[122:125]
	v_mfma_f32_16x16x32_bf16 v[126:129], v[146:149], v[200:203], v[126:129]
	v_mfma_f32_16x16x32_bf16 v[118:121], v[154:157], v[200:203], v[118:121]
	s_barrier
	s_add_i32 s57, 0, 0x1c000
	s_add_i32 s22, s56, s81
	v_add_u32_e32 v141, s57, v139
	v_lshl_add_u64 v[212:213], v[212:213], 0, s[78:79]
	s_mov_b32 m0, s22
	ds_read_b128 v[204:207], v141
	ds_read_b128 v[208:211], v141 offset:1024
	ds_read_b128 v[224:227], v141 offset:2048
	ds_read_b128 v[228:231], v141 offset:3072
	global_load_lds_dwordx4 v[212:213], off
	v_lshl_add_u64 v[212:213], v[222:223], 0, s[78:79]
	s_add_i32 m0, s22, 0x2000
	s_nop 0
	global_load_lds_dwordx4 v[212:213], off
	s_barrier
	s_waitcnt lgkmcnt(0)
	s_waitcnt lgkmcnt(0)
	v_mfma_f32_16x16x32_bf16 v[2:5], v[204:207], v[158:161], v[2:5]
	v_mfma_f32_16x16x32_bf16 v[6:9], v[224:227], v[158:161], v[6:9]
	v_mfma_f32_16x16x32_bf16 v[10:13], v[204:207], v[168:171], v[10:13]
	v_mfma_f32_16x16x32_bf16 v[14:17], v[224:227], v[168:171], v[14:17]
	v_mfma_f32_16x16x32_bf16 v[22:25], v[204:207], v[176:179], v[22:25]
	v_mfma_f32_16x16x32_bf16 v[18:21], v[224:227], v[176:179], v[18:21]
	v_mfma_f32_16x16x32_bf16 v[30:33], v[204:207], v[196:199], v[30:33]
	v_mfma_f32_16x16x32_bf16 v[26:29], v[224:227], v[196:199], v[26:29]
	v_mfma_f32_16x16x32_bf16 v[2:5], v[208:211], v[162:165], v[2:5]
	v_mfma_f32_16x16x32_bf16 v[6:9], v[228:231], v[162:165], v[6:9]
	v_mfma_f32_16x16x32_bf16 v[10:13], v[208:211], v[172:175], v[10:13]
	v_mfma_f32_16x16x32_bf16 v[14:17], v[228:231], v[172:175], v[14:17]
	v_mfma_f32_16x16x32_bf16 v[22:25], v[208:211], v[192:195], v[22:25]
	v_mfma_f32_16x16x32_bf16 v[18:21], v[228:231], v[192:195], v[18:21]
	v_mfma_f32_16x16x32_bf16 v[30:33], v[208:211], v[200:203], v[30:33]
	v_mfma_f32_16x16x32_bf16 v[26:29], v[228:231], v[200:203], v[26:29]
	s_mov_b32 m0, s47
	v_lshl_add_u64 v[212:213], v[232:233], 0, s[78:79]
	s_barrier
	ds_read_b128 v[158:161], v140 offset:49152
	ds_read_b128 v[162:165], v140 offset:50176
	ds_read_b128 v[168:171], v140 offset:51200
	ds_read_b128 v[172:175], v140 offset:52224
	ds_read_b128 v[176:179], v140 offset:53248
	ds_read_b128 v[192:195], v140 offset:54272
	ds_read_b128 v[196:199], v140 offset:55296
	ds_read_b128 v[200:203], v140 offset:56320
	global_load_lds_dwordx4 v[212:213], off
	v_lshl_add_u64 v[212:213], v[234:235], 0, s[78:79]
	s_mov_b32 m0, s48
	s_nop 0
	global_load_lds_dwordx4 v[212:213], off
	s_waitcnt vmcnt(10)
	s_barrier
	s_waitcnt lgkmcnt(0)
	s_waitcnt lgkmcnt(0)
	v_mfma_f32_16x16x32_bf16 v[110:113], v[142:145], v[158:161], v[110:113]
	v_mfma_f32_16x16x32_bf16 v[106:109], v[150:153], v[158:161], v[106:109]
	v_mfma_f32_16x16x32_bf16 v[90:93], v[142:145], v[168:171], v[90:93]
	v_mfma_f32_16x16x32_bf16 v[82:85], v[150:153], v[168:171], v[82:85]
	v_mfma_f32_16x16x32_bf16 v[78:81], v[142:145], v[176:179], v[78:81]
	v_mfma_f32_16x16x32_bf16 v[74:77], v[150:153], v[176:179], v[74:77]
	v_mfma_f32_16x16x32_bf16 v[70:73], v[142:145], v[196:199], v[70:73]
	v_mfma_f32_16x16x32_bf16 v[66:69], v[150:153], v[196:199], v[66:69]
	v_mfma_f32_16x16x32_bf16 v[110:113], v[146:149], v[162:165], v[110:113]
	v_mfma_f32_16x16x32_bf16 v[106:109], v[154:157], v[162:165], v[106:109]
	v_mfma_f32_16x16x32_bf16 v[90:93], v[146:149], v[172:175], v[90:93]
	v_mfma_f32_16x16x32_bf16 v[82:85], v[154:157], v[172:175], v[82:85]
	v_mfma_f32_16x16x32_bf16 v[78:81], v[146:149], v[192:195], v[78:81]
	v_mfma_f32_16x16x32_bf16 v[74:77], v[154:157], v[192:195], v[74:77]
	v_mfma_f32_16x16x32_bf16 v[70:73], v[146:149], v[200:203], v[70:73]
	v_mfma_f32_16x16x32_bf16 v[66:69], v[154:157], v[200:203], v[66:69]
	s_barrier
	s_add_u32 s22, s90, 0x200080
	s_addc_u32 s23, s91, 0
	s_add_i32 s56, s57, s81
	v_lshl_add_u64 v[142:143], s[22:23], 0, v[134:135]
	s_mov_b32 m0, s56
	s_nop 0
	global_load_lds_dwordx4 v[142:143], off
	v_lshl_add_u64 v[142:143], s[22:23], 0, v[130:131]
	s_add_i32 m0, s56, 0x2000
	s_nop 0
	global_load_lds_dwordx4 v[142:143], off
	v_add_u32_e32 v141, 0x10000, v139
	ds_read_b128 v[142:145], v141
	ds_read_b128 v[146:149], v141 offset:1024
	ds_read_b128 v[150:153], v141 offset:2048
	ds_read_b128 v[154:157], v141 offset:3072
	s_waitcnt vmcnt(6)
	s_barrier
	v_mfma_f32_16x16x32_bf16 v[38:41], v[204:207], v[158:161], v[38:41]
	v_mfma_f32_16x16x32_bf16 v[34:37], v[224:227], v[158:161], v[34:37]
	v_mfma_f32_16x16x32_bf16 v[46:49], v[204:207], v[168:171], v[46:49]
	v_mfma_f32_16x16x32_bf16 v[42:45], v[224:227], v[168:171], v[42:45]
	v_mfma_f32_16x16x32_bf16 v[54:57], v[204:207], v[176:179], v[54:57]
	v_mfma_f32_16x16x32_bf16 v[50:53], v[224:227], v[176:179], v[50:53]
	v_mfma_f32_16x16x32_bf16 v[62:65], v[204:207], v[196:199], v[62:65]
	v_mfma_f32_16x16x32_bf16 v[58:61], v[224:227], v[196:199], v[58:61]
	v_mfma_f32_16x16x32_bf16 v[38:41], v[208:211], v[162:165], v[38:41]
	v_mfma_f32_16x16x32_bf16 v[34:37], v[228:231], v[162:165], v[34:37]
	v_mfma_f32_16x16x32_bf16 v[46:49], v[208:211], v[172:175], v[46:49]
	v_mfma_f32_16x16x32_bf16 v[42:45], v[228:231], v[172:175], v[42:45]
	v_mfma_f32_16x16x32_bf16 v[54:57], v[208:211], v[192:195], v[54:57]
	v_mfma_f32_16x16x32_bf16 v[50:53], v[228:231], v[192:195], v[50:53]
	v_mfma_f32_16x16x32_bf16 v[62:65], v[208:211], v[200:203], v[62:65]
	v_mfma_f32_16x16x32_bf16 v[58:61], v[228:231], v[200:203], v[58:61]
	s_add_i32 s54, s54, 2
	s_add_i32 s55, s55, 0x10000
	s_cmpk_gt_u32 s54, 0x7d
	s_mov_b64 s[90:91], vcc
	s_barrier
	s_cbranch_scc0 .LBB0_814
	s_waitcnt lgkmcnt(0)
	s_andn2_b64 vcc, exec, s[38:39]
	s_cbranch_vccnz .LBB0_806
	v_mov_b32_e32 v58, 0
	s_mov_b32 s80, s42
	s_mov_b32 s25, s82
	s_mov_b64 s[30:31], s[20:21]
	s_mov_b64 s[84:85], s[18:19]
	s_mov_b32 s49, s50
	v_mov_b32_e32 v59, v58
	v_mov_b32_e32 v60, v58
	v_mov_b32_e32 v61, v58
	v_mov_b32_e32 v62, v58
	v_mov_b32_e32 v63, v58
	v_mov_b32_e32 v64, v58
	v_mov_b32_e32 v65, v58
	v_mov_b32_e32 v50, v58
	v_mov_b32_e32 v51, v58
	v_mov_b32_e32 v52, v58
	v_mov_b32_e32 v53, v58
	v_mov_b32_e32 v54, v58
	v_mov_b32_e32 v55, v58
	v_mov_b32_e32 v56, v58
	v_mov_b32_e32 v57, v58
	v_mov_b32_e32 v42, v58
	v_mov_b32_e32 v43, v58
	v_mov_b32_e32 v44, v58
	v_mov_b32_e32 v45, v58
	v_mov_b32_e32 v46, v58
	v_mov_b32_e32 v47, v58
	v_mov_b32_e32 v48, v58
	v_mov_b32_e32 v49, v58
	v_mov_b32_e32 v34, v58
	v_mov_b32_e32 v35, v58
	v_mov_b32_e32 v36, v58
	v_mov_b32_e32 v37, v58
	v_mov_b32_e32 v38, v58
	v_mov_b32_e32 v39, v58
	v_mov_b32_e32 v40, v58
	v_mov_b32_e32 v41, v58
	v_mov_b32_e32 v66, v58
	v_mov_b32_e32 v67, v58
	v_mov_b32_e32 v68, v58
	v_mov_b32_e32 v69, v58
	v_mov_b32_e32 v70, v58
	v_mov_b32_e32 v71, v58
	v_mov_b32_e32 v72, v58
	v_mov_b32_e32 v73, v58
	v_mov_b32_e32 v74, v58
	v_mov_b32_e32 v75, v58
	v_mov_b32_e32 v76, v58
	v_mov_b32_e32 v77, v58
	v_mov_b32_e32 v78, v58
	v_mov_b32_e32 v79, v58
	v_mov_b32_e32 v80, v58
	v_mov_b32_e32 v81, v58
	v_mov_b32_e32 v82, v58
	v_mov_b32_e32 v83, v58
	v_mov_b32_e32 v84, v58
	v_mov_b32_e32 v85, v58
	v_mov_b32_e32 v90, v58
	v_mov_b32_e32 v91, v58
	v_mov_b32_e32 v92, v58
	v_mov_b32_e32 v93, v58
	v_mov_b32_e32 v106, v58
	v_mov_b32_e32 v107, v58
	v_mov_b32_e32 v108, v58
	v_mov_b32_e32 v109, v58
	v_mov_b32_e32 v110, v58
	v_mov_b32_e32 v111, v58
	v_mov_b32_e32 v112, v58
	v_mov_b32_e32 v113, v58
	v_mov_b32_e32 v26, v58
	v_mov_b32_e32 v27, v58
	v_mov_b32_e32 v28, v58
	v_mov_b32_e32 v29, v58
	v_mov_b32_e32 v30, v58
	v_mov_b32_e32 v31, v58
	v_mov_b32_e32 v32, v58
	v_mov_b32_e32 v33, v58
	v_mov_b32_e32 v18, v58
	v_mov_b32_e32 v19, v58
	v_mov_b32_e32 v20, v58
	v_mov_b32_e32 v21, v58
	v_mov_b32_e32 v22, v58
	v_mov_b32_e32 v23, v58
	v_mov_b32_e32 v24, v58
	v_mov_b32_e32 v25, v58
	v_mov_b32_e32 v14, v58
	v_mov_b32_e32 v15, v58
	v_mov_b32_e32 v16, v58
	v_mov_b32_e32 v17, v58
	v_mov_b32_e32 v10, v58
	v_mov_b32_e32 v11, v58
	v_mov_b32_e32 v12, v58
	v_mov_b32_e32 v13, v58
	v_mov_b32_e32 v6, v58
	v_mov_b32_e32 v7, v58
	v_mov_b32_e32 v8, v58
	v_mov_b32_e32 v9, v58
	v_mov_b32_e32 v2, v58
	v_mov_b32_e32 v3, v58
	v_mov_b32_e32 v4, v58
	v_mov_b32_e32 v5, v58
	v_mov_b32_e32 v118, v58
	v_mov_b32_e32 v119, v58
	v_mov_b32_e32 v120, v58
	v_mov_b32_e32 v121, v58
	v_mov_b32_e32 v126, v58
	v_mov_b32_e32 v127, v58
	v_mov_b32_e32 v128, v58
	v_mov_b32_e32 v129, v58
	v_mov_b32_e32 v122, v58
	v_mov_b32_e32 v123, v58
	v_mov_b32_e32 v124, v58
	v_mov_b32_e32 v125, v58
	v_mov_b32_e32 v114, v58
	v_mov_b32_e32 v115, v58
	v_mov_b32_e32 v116, v58
	v_mov_b32_e32 v117, v58
	v_mov_b32_e32 v102, v58
	v_mov_b32_e32 v103, v58
	v_mov_b32_e32 v104, v58
	v_mov_b32_e32 v105, v58
	v_mov_b32_e32 v98, v58
	v_mov_b32_e32 v99, v58
	v_mov_b32_e32 v100, v58
	v_mov_b32_e32 v101, v58
	v_mov_b32_e32 v94, v58
	v_mov_b32_e32 v95, v58
	v_mov_b32_e32 v96, v58
	v_mov_b32_e32 v97, v58
	v_mov_b32_e32 v86, v58
	v_mov_b32_e32 v87, v58
	v_mov_b32_e32 v88, v58
	v_mov_b32_e32 v89, v58
	s_branch .LBB0_806
